# GEMM K-loops: in the 12-read load sections the 8 B-fragment reads are issued first, A reads after, with the full LDS wait before the barrier
# speedup vs baseline: 1.0123x; 1.0019x over previous
.LBB0_175:
	ds_read_b128 v[40:43], v234
	ds_read_b128 v[44:47], v234 offset:1024
	ds_read_b128 v[48:51], v234 offset:2048
	ds_read_b128 v[52:55], v234 offset:3072
	ds_read_b128 v[186:189], v234 offset:4096
	ds_read_b128 v[190:193], v234 offset:5120
	ds_read_b128 v[194:197], v234 offset:6144
	ds_read_b128 v[198:201], v234 offset:7168
	ds_read_b128 v[16:19], v233
	ds_read_b128 v[20:23], v233 offset:1024
	ds_read_b128 v[24:27], v233 offset:2048
	ds_read_b128 v[28:31], v233 offset:3072
	s_add_u32 s6, s4, 0xfffc0080
	s_addc_u32 s7, s5, -1
	s_cmp_eq_u32 s34, 12
	s_cselect_b32 s9, s10, s7
	s_cselect_b32 s8, s11, s6
	s_cselect_b32 s7, s25, s31
	s_cselect_b32 s6, s29, s30
	v_lshl_add_u64 v[202:203], s[4:5], 0, v[182:183]
	s_add_i32 m0, s92, 0xc000
	global_load_lds_dwordx4 v[202:203], off
	v_lshl_add_u64 v[202:203], s[4:5], 0, v[184:185]
	s_add_i32 m0, s92, 0xe000
	s_nop 0
	global_load_lds_dwordx4 v[202:203], off
	s_waitcnt lgkmcnt(0)
	s_barrier
	s_waitcnt lgkmcnt(0)
	v_mfma_f32_16x16x32_bf16 v[156:159], v[16:19], v[40:43], v[156:159]
	v_mfma_f32_16x16x32_bf16 v[152:155], v[24:27], v[40:43], v[152:155]
	v_mfma_f32_16x16x32_bf16 v[140:143], v[16:19], v[48:51], v[140:143]
	v_mfma_f32_16x16x32_bf16 v[136:139], v[24:27], v[48:51], v[136:139]
	v_mfma_f32_16x16x32_bf16 v[124:127], v[16:19], v[186:189], v[124:127]
	v_mfma_f32_16x16x32_bf16 v[120:123], v[24:27], v[186:189], v[120:123]
	v_mfma_f32_16x16x32_bf16 v[108:111], v[16:19], v[194:197], v[108:111]
	v_mfma_f32_16x16x32_bf16 v[104:107], v[24:27], v[194:197], v[104:107]
	v_mfma_f32_16x16x32_bf16 v[156:159], v[20:23], v[44:47], v[156:159]
	v_mfma_f32_16x16x32_bf16 v[152:155], v[28:31], v[44:47], v[152:155]
	v_mfma_f32_16x16x32_bf16 v[140:143], v[20:23], v[52:55], v[140:143]
	v_mfma_f32_16x16x32_bf16 v[136:139], v[28:31], v[52:55], v[136:139]
	v_mfma_f32_16x16x32_bf16 v[124:127], v[20:23], v[190:193], v[124:127]
	v_mfma_f32_16x16x32_bf16 v[120:123], v[28:31], v[190:193], v[120:123]
	v_mfma_f32_16x16x32_bf16 v[108:111], v[20:23], v[198:201], v[108:111]
	v_mfma_f32_16x16x32_bf16 v[104:107], v[28:31], v[198:201], v[104:107]
	s_barrier
	s_add_i32 s35, s1, s33
	v_lshl_add_u64 v[218:219], s[6:7], 0, v[166:167]
	s_mov_b32 m0, s35
	ds_read_b128 v[202:205], v235
	ds_read_b128 v[206:209], v235 offset:1024
	ds_read_b128 v[210:213], v235 offset:2048
	ds_read_b128 v[214:217], v235 offset:3072
	global_load_lds_dwordx4 v[218:219], off
	v_lshl_add_u64 v[246:247], s[6:7], 0, v[162:163]
	s_add_i32 m0, s35, 0x2000
	s_nop 0
	global_load_lds_dwordx4 v[246:247], off
	s_barrier
	s_waitcnt lgkmcnt(0)
	v_mfma_f32_16x16x32_bf16 v[148:151], v[202:205], v[40:43], v[148:151]
	v_mfma_f32_16x16x32_bf16 v[40:43], v[210:213], v[40:43], v[144:147]
	v_mfma_f32_16x16x32_bf16 v[148:151], v[206:209], v[44:47], v[148:151]
	v_mfma_f32_16x16x32_bf16 v[40:43], v[214:217], v[44:47], v[40:43]
	v_mfma_f32_16x16x32_bf16 v[44:47], v[202:205], v[48:51], v[132:135]
	v_mfma_f32_16x16x32_bf16 v[48:51], v[210:213], v[48:51], v[128:131]
	v_mfma_f32_16x16x32_bf16 v[112:115], v[210:213], v[186:189], v[112:115]
	v_mfma_f32_16x16x32_bf16 v[100:103], v[202:205], v[194:197], v[100:103]
	v_mfma_f32_16x16x32_bf16 v[96:99], v[210:213], v[194:197], v[96:99]
	v_mfma_f32_16x16x32_bf16 v[44:47], v[206:209], v[52:55], v[44:47]
	v_mfma_f32_16x16x32_bf16 v[48:51], v[214:217], v[52:55], v[48:51]
	v_mfma_f32_16x16x32_bf16 v[52:55], v[202:205], v[186:189], v[116:119]
	v_mfma_f32_16x16x32_bf16 v[112:115], v[214:217], v[190:193], v[112:115]
	v_mfma_f32_16x16x32_bf16 v[100:103], v[206:209], v[198:201], v[100:103]
	v_mfma_f32_16x16x32_bf16 v[96:99], v[214:217], v[198:201], v[96:99]
	v_mfma_f32_16x16x32_bf16 v[52:55], v[206:209], v[190:193], v[52:55]
	s_mov_b32 m0, s92
	v_lshl_add_u64 v[248:249], s[8:9], 0, v[168:169]
	s_barrier
	ds_read_b128 v[116:119], v234 offset:16384
	ds_read_b128 v[128:131], v234 offset:17408
	ds_read_b128 v[132:135], v234 offset:18432
	ds_read_b128 v[144:147], v234 offset:19456
	ds_read_b128 v[186:189], v234 offset:20480
	ds_read_b128 v[190:193], v234 offset:21504
	ds_read_b128 v[194:197], v234 offset:22528
	ds_read_b128 v[198:201], v234 offset:23552
	global_load_lds_dwordx4 v[248:249], off
	v_lshl_add_u64 v[250:251], s[8:9], 0, v[164:165]
	s_mov_b32 m0, s93
	s_nop 0
	global_load_lds_dwordx4 v[250:251], off
	s_barrier
	s_waitcnt lgkmcnt(0)
	v_mfma_f32_16x16x32_bf16 v[92:95], v[16:19], v[116:119], v[92:95]
	v_mfma_f32_16x16x32_bf16 v[88:91], v[24:27], v[116:119], v[88:91]
	v_mfma_f32_16x16x32_bf16 v[76:79], v[16:19], v[132:135], v[76:79]
	v_mfma_f32_16x16x32_bf16 v[72:75], v[24:27], v[132:135], v[72:75]
	v_mfma_f32_16x16x32_bf16 v[60:63], v[16:19], v[186:189], v[60:63]
	v_mfma_f32_16x16x32_bf16 v[56:59], v[24:27], v[186:189], v[56:59]
	v_mfma_f32_16x16x32_bf16 v[12:15], v[16:19], v[194:197], v[12:15]
	v_mfma_f32_16x16x32_bf16 v[8:11], v[24:27], v[194:197], v[8:11]
	v_mfma_f32_16x16x32_bf16 v[92:95], v[20:23], v[128:131], v[92:95]
	v_mfma_f32_16x16x32_bf16 v[88:91], v[28:31], v[128:131], v[88:91]
	v_mfma_f32_16x16x32_bf16 v[76:79], v[20:23], v[144:147], v[76:79]
	v_mfma_f32_16x16x32_bf16 v[72:75], v[28:31], v[144:147], v[72:75]
	v_mfma_f32_16x16x32_bf16 v[60:63], v[20:23], v[190:193], v[60:63]
	v_mfma_f32_16x16x32_bf16 v[56:59], v[28:31], v[190:193], v[56:59]
	v_mfma_f32_16x16x32_bf16 v[12:15], v[20:23], v[198:201], v[12:15]
	v_mfma_f32_16x16x32_bf16 v[8:11], v[28:31], v[198:201], v[8:11]
	s_barrier
	s_add_u32 s56, s6, 0x40000
	s_addc_u32 s57, s7, 0
	s_add_i32 s35, s18, s33
	v_lshl_add_u64 v[16:17], s[56:57], 0, v[166:167]
	s_mov_b32 m0, s35
	s_nop 0
	global_load_lds_dwordx4 v[16:17], off
	v_lshl_add_u64 v[16:17], s[56:57], 0, v[162:163]
	s_add_i32 m0, s35, 0x2000
	s_nop 0
	global_load_lds_dwordx4 v[16:17], off
	s_waitcnt vmcnt(6)
	s_barrier
	v_mfma_f32_16x16x32_bf16 v[36:39], v[202:205], v[186:189], v[36:39]
	v_mfma_f32_16x16x32_bf16 v[32:35], v[210:213], v[186:189], v[32:35]
	v_mfma_f32_16x16x32_bf16 v[4:7], v[202:205], v[194:197], v[4:7]
	v_mfma_f32_16x16x32_bf16 v[0:3], v[210:213], v[194:197], v[0:3]
	v_mfma_f32_16x16x32_bf16 v[16:19], v[202:205], v[116:119], v[84:87]
	v_mfma_f32_16x16x32_bf16 v[20:23], v[210:213], v[116:119], v[80:83]
	v_mfma_f32_16x16x32_bf16 v[24:27], v[202:205], v[132:135], v[68:71]
	v_mfma_f32_16x16x32_bf16 v[28:31], v[210:213], v[132:135], v[64:67]
	v_mfma_f32_16x16x32_bf16 v[36:39], v[206:209], v[190:193], v[36:39]
	v_mfma_f32_16x16x32_bf16 v[32:35], v[214:217], v[190:193], v[32:35]
	v_mfma_f32_16x16x32_bf16 v[4:7], v[206:209], v[198:201], v[4:7]
	v_mfma_f32_16x16x32_bf16 v[0:3], v[214:217], v[198:201], v[0:3]
	v_mfma_f32_16x16x32_bf16 v[16:19], v[206:209], v[128:131], v[16:19]
	v_mfma_f32_16x16x32_bf16 v[20:23], v[214:217], v[128:131], v[20:23]
	v_mfma_f32_16x16x32_bf16 v[24:27], v[206:209], v[144:147], v[24:27]
	v_mfma_f32_16x16x32_bf16 v[28:31], v[214:217], v[144:147], v[28:31]
	s_add_i32 s35, 0, 0x18000
	v_add_u32_e32 v84, s35, v232
	s_barrier
	ds_read_b128 v[116:119], v234 offset:32768
	ds_read_b128 v[128:131], v234 offset:33792
	ds_read_b128 v[186:189], v234 offset:34816
	ds_read_b128 v[190:193], v234 offset:35840
	ds_read_b128 v[194:197], v234 offset:36864
	ds_read_b128 v[198:201], v234 offset:37888
	ds_read_b128 v[202:205], v234 offset:38912
	ds_read_b128 v[206:209], v234 offset:39936
	ds_read_b128 v[64:67], v84
	ds_read_b128 v[68:71], v84 offset:1024
	ds_read_b128 v[80:83], v84 offset:2048
	ds_read_b128 v[84:87], v84 offset:3072
	s_add_u32 s8, s8, 0x40000
	s_addc_u32 s9, s9, 0
	s_mov_b32 m0, s96
	v_lshl_add_u64 v[132:133], s[8:9], 0, v[168:169]
	global_load_lds_dwordx4 v[132:133], off
	v_lshl_add_u64 v[132:133], s[8:9], 0, v[164:165]
	s_mov_b32 m0, s97
	s_nop 0
	global_load_lds_dwordx4 v[132:133], off
	s_waitcnt lgkmcnt(0)
	s_barrier
	s_waitcnt lgkmcnt(0)
	v_mfma_f32_16x16x32_bf16 v[132:135], v[64:67], v[116:119], v[156:159]
	v_mfma_f32_16x16x32_bf16 v[156:159], v[68:71], v[128:131], v[132:135]
	v_mfma_f32_16x16x32_bf16 v[132:135], v[80:83], v[116:119], v[152:155]
	v_mfma_f32_16x16x32_bf16 v[152:155], v[84:87], v[128:131], v[132:135]
	v_mfma_f32_16x16x32_bf16 v[132:135], v[64:67], v[186:189], v[140:143]
	v_mfma_f32_16x16x32_bf16 v[140:143], v[68:71], v[190:193], v[132:135]
	v_mfma_f32_16x16x32_bf16 v[132:135], v[80:83], v[186:189], v[136:139]
	v_mfma_f32_16x16x32_bf16 v[124:127], v[64:67], v[194:197], v[124:127]
	v_mfma_f32_16x16x32_bf16 v[120:123], v[80:83], v[194:197], v[120:123]
	v_mfma_f32_16x16x32_bf16 v[108:111], v[64:67], v[202:205], v[108:111]
	v_mfma_f32_16x16x32_bf16 v[104:107], v[80:83], v[202:205], v[104:107]
	v_mfma_f32_16x16x32_bf16 v[136:139], v[84:87], v[190:193], v[132:135]
	v_mfma_f32_16x16x32_bf16 v[124:127], v[68:71], v[198:201], v[124:127]
	v_mfma_f32_16x16x32_bf16 v[120:123], v[84:87], v[198:201], v[120:123]
	v_mfma_f32_16x16x32_bf16 v[108:111], v[68:71], v[206:209], v[108:111]
	v_mfma_f32_16x16x32_bf16 v[104:107], v[84:87], v[206:209], v[104:107]
	s_barrier
	s_add_i32 s8, 0, 0x1c000
	v_add_u32_e32 v132, s8, v232
	s_add_i32 s9, s35, s33
	ds_read_b128 v[210:213], v132
	ds_read_b128 v[214:217], v132 offset:1024
	ds_read_b128 v[238:241], v132 offset:2048
	ds_read_b128 v[242:245], v132 offset:3072
	v_lshl_add_u64 v[132:133], v[218:219], 0, s[14:15]
	s_mov_b32 m0, s9
	s_nop 0
	global_load_lds_dwordx4 v[132:133], off
	v_lshl_add_u64 v[132:133], v[246:247], 0, s[14:15]
	s_add_i32 m0, s9, 0x2000
	s_nop 0
	global_load_lds_dwordx4 v[132:133], off
	s_barrier
	s_waitcnt lgkmcnt(0)
	v_mfma_f32_16x16x32_bf16 v[40:43], v[238:241], v[116:119], v[40:43]
	v_mfma_f32_16x16x32_bf16 v[132:135], v[210:213], v[116:119], v[148:151]
	v_mfma_f32_16x16x32_bf16 v[144:147], v[242:245], v[128:131], v[40:43]
	v_mfma_f32_16x16x32_bf16 v[40:43], v[210:213], v[186:189], v[44:47]
	v_mfma_f32_16x16x32_bf16 v[148:151], v[214:217], v[128:131], v[132:135]
	v_mfma_f32_16x16x32_bf16 v[132:135], v[214:217], v[190:193], v[40:43]
	v_mfma_f32_16x16x32_bf16 v[40:43], v[238:241], v[186:189], v[48:51]
	v_mfma_f32_16x16x32_bf16 v[128:131], v[242:245], v[190:193], v[40:43]
	v_mfma_f32_16x16x32_bf16 v[40:43], v[210:213], v[194:197], v[52:55]
	v_mfma_f32_16x16x32_bf16 v[116:119], v[214:217], v[198:201], v[40:43]
	v_mfma_f32_16x16x32_bf16 v[40:43], v[238:241], v[194:197], v[112:115]
	v_mfma_f32_16x16x32_bf16 v[112:115], v[242:245], v[198:201], v[40:43]
	v_mfma_f32_16x16x32_bf16 v[40:43], v[210:213], v[202:205], v[100:103]
	v_mfma_f32_16x16x32_bf16 v[100:103], v[214:217], v[206:209], v[40:43]
	v_mfma_f32_16x16x32_bf16 v[40:43], v[238:241], v[202:205], v[96:99]
	v_mfma_f32_16x16x32_bf16 v[96:99], v[242:245], v[206:209], v[40:43]
	s_mov_b32 m0, s53
	v_lshl_add_u64 v[202:203], v[248:249], 0, s[14:15]
	s_barrier
	s_nop 2
	ds_read_b128 v[40:43], v234 offset:49152
	ds_read_b128 v[44:47], v234 offset:50176
	ds_read_b128 v[48:51], v234 offset:51200
	ds_read_b128 v[52:55], v234 offset:52224
	ds_read_b128 v[186:189], v234 offset:53248
	ds_read_b128 v[190:193], v234 offset:54272
	ds_read_b128 v[194:197], v234 offset:55296
	ds_read_b128 v[198:201], v234 offset:56320
	global_load_lds_dwordx4 v[202:203], off
	v_lshl_add_u64 v[202:203], v[250:251], 0, s[14:15]
	s_mov_b32 m0, s23
	s_nop 0
	global_load_lds_dwordx4 v[202:203], off
	s_barrier
	s_waitcnt lgkmcnt(0)
	v_mfma_f32_16x16x32_bf16 v[92:95], v[64:67], v[40:43], v[92:95]
	v_mfma_f32_16x16x32_bf16 v[88:91], v[80:83], v[40:43], v[88:91]
	v_mfma_f32_16x16x32_bf16 v[76:79], v[64:67], v[48:51], v[76:79]
	v_mfma_f32_16x16x32_bf16 v[72:75], v[80:83], v[48:51], v[72:75]
	v_mfma_f32_16x16x32_bf16 v[60:63], v[64:67], v[186:189], v[60:63]
	v_mfma_f32_16x16x32_bf16 v[56:59], v[80:83], v[186:189], v[56:59]
	v_mfma_f32_16x16x32_bf16 v[12:15], v[64:67], v[194:197], v[12:15]
	v_mfma_f32_16x16x32_bf16 v[8:11], v[80:83], v[194:197], v[8:11]
	v_mfma_f32_16x16x32_bf16 v[92:95], v[68:71], v[44:47], v[92:95]
	v_mfma_f32_16x16x32_bf16 v[88:91], v[84:87], v[44:47], v[88:91]
	v_mfma_f32_16x16x32_bf16 v[76:79], v[68:71], v[52:55], v[76:79]
	v_mfma_f32_16x16x32_bf16 v[72:75], v[84:87], v[52:55], v[72:75]
	v_mfma_f32_16x16x32_bf16 v[60:63], v[68:71], v[190:193], v[60:63]
	v_mfma_f32_16x16x32_bf16 v[56:59], v[84:87], v[190:193], v[56:59]
	v_mfma_f32_16x16x32_bf16 v[12:15], v[68:71], v[198:201], v[12:15]
	v_mfma_f32_16x16x32_bf16 v[8:11], v[84:87], v[198:201], v[8:11]
	s_barrier
	s_add_u32 s6, s6, 0x40080
	s_addc_u32 s7, s7, 0
	s_add_i32 s8, s8, s33
	v_lshl_add_u64 v[64:65], s[6:7], 0, v[166:167]
	s_mov_b32 m0, s8
	s_nop 0
	global_load_lds_dwordx4 v[64:65], off
	v_lshl_add_u64 v[64:65], s[6:7], 0, v[162:163]
	s_add_i32 m0, s8, 0x2000
	s_nop 0
	global_load_lds_dwordx4 v[64:65], off
	s_waitcnt vmcnt(6)
	s_barrier
	v_mfma_f32_16x16x32_bf16 v[16:19], v[210:213], v[40:43], v[16:19]
	v_mfma_f32_16x16x32_bf16 v[84:87], v[214:217], v[44:47], v[16:19]
	v_mfma_f32_16x16x32_bf16 v[16:19], v[238:241], v[40:43], v[20:23]
	v_mfma_f32_16x16x32_bf16 v[80:83], v[242:245], v[44:47], v[16:19]
	v_mfma_f32_16x16x32_bf16 v[16:19], v[210:213], v[48:51], v[24:27]
	v_mfma_f32_16x16x32_bf16 v[68:71], v[214:217], v[52:55], v[16:19]
	v_mfma_f32_16x16x32_bf16 v[16:19], v[238:241], v[48:51], v[28:31]
	v_mfma_f32_16x16x32_bf16 v[64:67], v[242:245], v[52:55], v[16:19]
	v_mfma_f32_16x16x32_bf16 v[16:19], v[210:213], v[186:189], v[36:39]
	v_mfma_f32_16x16x32_bf16 v[36:39], v[214:217], v[190:193], v[16:19]
	v_mfma_f32_16x16x32_bf16 v[16:19], v[238:241], v[186:189], v[32:35]
	v_mfma_f32_16x16x32_bf16 v[4:7], v[210:213], v[194:197], v[4:7]
	v_mfma_f32_16x16x32_bf16 v[0:3], v[238:241], v[194:197], v[0:3]
	v_mfma_f32_16x16x32_bf16 v[32:35], v[242:245], v[190:193], v[16:19]
	v_mfma_f32_16x16x32_bf16 v[4:7], v[214:217], v[198:201], v[4:7]
	v_mfma_f32_16x16x32_bf16 v[0:3], v[242:245], v[198:201], v[0:3]
	s_add_i32 s34, s34, 2
	s_add_u32 s4, s4, 0x100
	s_addc_u32 s5, s5, 0
	s_add_u32 s30, s30, 0x100
	s_addc_u32 s31, s31, 0
	s_cmp_gt_u32 s34, 13
	s_barrier
	s_cbranch_scc0 .LBB0_175
	s_cmp_gt_i32 s28, 1
	s_cselect_b64 s[6:7], -1, 0
	s_cmp_lt_i32 s28, 2
	s_cselect_b64 s[4:5], -1, 0
	s_add_i32 s8, s28, -3
	s_cmp_lt_u32 s8, 2
	s_cselect_b64 s[8:9], -1, 0
	s_lshl_b32 s29, s12, 8
	s_add_i32 s29, s29, s52
	v_or_b32_e32 v196, s29, v179
	s_nop 0
	v_ashrrev_i32_e32 v197, 31, v196
	v_readlane_b32 s72, v253, 63
	v_readlane_b32 s73, v252, 0
	s_or_b64 s[4:5], s[4:5], s[8:9]
	s_and_b32 s8, s29, 0xfc0
	v_lshl_add_u64 v[16:17], v[196:197], 2, s[72:73]
	global_load_dword v204, v[16:17], off
	global_load_dword v200, v[16:17], off offset:64
	global_load_dword v198, v[16:17], off offset:128
	global_load_dword v194, v[16:17], off offset:192
	global_load_dword v192, v[16:17], off offset:512
	global_load_dword v190, v[16:17], off offset:576
	global_load_dword v188, v[16:17], off offset:640
	global_load_dword v186, v[16:17], off offset:704
	v_or_b32_e32 v16, s8, v179
	v_readlane_b32 s8, v252, 45
	v_readlane_b32 s9, v252, 46
	s_and_b64 s[62:63], s[8:9], s[4:5]
	v_cndmask_b32_e64 v17, 0, 1, s[62:63]
	v_readlane_b32 s68, v253, 59
	v_readlane_b32 s69, v253, 60
	v_readlane_b32 s76, v252, 3
	v_readlane_b32 s77, v252, 4
	v_readlane_b32 s78, v252, 5
	v_readlane_b32 s79, v252, 6
	v_cmp_ne_u32_e64 s[4:5], 1, v17
	s_andn2_b64 vcc, exec, s[62:63]
	v_lshlrev_b32_e32 v187, 6, v16
	s_nop 6
	s_cbranch_vccnz .LBB0_178
	global_load_dwordx4 v[40:43], v187, s[76:77] offset:48
	global_load_dwordx4 v[44:47], v187, s[76:77] offset:32
	global_load_dwordx4 v[48:51], v187, s[76:77] offset:16
	global_load_dwordx4 v[52:55], v187, s[76:77]
	global_load_dwordx4 v[16:19], v187, s[76:77] offset:1072
	global_load_dwordx4 v[20:23], v187, s[76:77] offset:1056
	global_load_dwordx4 v[24:27], v187, s[76:77] offset:1040
	global_load_dwordx4 v[28:31], v187, s[76:77] offset:1024

.LBB0_612:
	ds_read_b128 v[188:191], v162
	ds_read_b128 v[192:195], v162 offset:1024
	ds_read_b128 v[196:199], v162 offset:2048
	ds_read_b128 v[200:203], v162 offset:3072
	ds_read_b128 v[204:207], v162 offset:4096
	ds_read_b128 v[208:211], v162 offset:5120
	ds_read_b128 v[212:215], v162 offset:6144
	ds_read_b128 v[216:219], v162 offset:7168
	ds_read_b128 v[164:167], v159
	ds_read_b128 v[168:171], v159 offset:1024
	ds_read_b128 v[180:183], v159 offset:2048
	ds_read_b128 v[184:187], v159 offset:3072
	s_add_u32 s24, s22, 0xfffc0080
	s_addc_u32 s25, s23, -1
	s_cmp_eq_u32 s45, 4
	s_cselect_b32 s35, s9, s25
	s_cselect_b32 s34, s41, s24
	s_cselect_b32 s25, s7, s44
	s_cselect_b32 s24, s42, s43
	v_lshl_add_u64 v[172:173], s[22:23], 0, v[154:155]
	s_add_i32 m0, s3, 0xc000
	global_load_lds_dwordx4 v[172:173], off
	v_lshl_add_u64 v[172:173], s[22:23], 0, v[156:157]
	s_add_i32 m0, s3, 0xe000
	s_nop 0
	global_load_lds_dwordx4 v[172:173], off
	s_waitcnt lgkmcnt(0)
	s_barrier
	s_waitcnt lgkmcnt(0)
	v_mfma_f32_16x16x32_bf16 v[124:127], v[164:167], v[188:191], v[124:127]
	v_mfma_f32_16x16x32_bf16 v[120:123], v[180:183], v[188:191], v[120:123]
	v_mfma_f32_16x16x32_bf16 v[116:119], v[164:167], v[196:199], v[116:119]
	v_mfma_f32_16x16x32_bf16 v[112:115], v[180:183], v[196:199], v[112:115]
	v_mfma_f32_16x16x32_bf16 v[108:111], v[164:167], v[204:207], v[108:111]
	v_mfma_f32_16x16x32_bf16 v[100:103], v[180:183], v[204:207], v[100:103]
	v_mfma_f32_16x16x32_bf16 v[92:95], v[164:167], v[212:215], v[92:95]
	v_mfma_f32_16x16x32_bf16 v[84:87], v[180:183], v[212:215], v[84:87]
	v_mfma_f32_16x16x32_bf16 v[124:127], v[168:171], v[192:195], v[124:127]
	v_mfma_f32_16x16x32_bf16 v[120:123], v[184:187], v[192:195], v[120:123]
	v_mfma_f32_16x16x32_bf16 v[116:119], v[168:171], v[200:203], v[116:119]
	v_mfma_f32_16x16x32_bf16 v[112:115], v[184:187], v[200:203], v[112:115]
	v_mfma_f32_16x16x32_bf16 v[108:111], v[168:171], v[208:211], v[108:111]
	v_mfma_f32_16x16x32_bf16 v[100:103], v[184:187], v[208:211], v[100:103]
	v_mfma_f32_16x16x32_bf16 v[92:95], v[168:171], v[216:219], v[92:95]
	v_mfma_f32_16x16x32_bf16 v[84:87], v[184:187], v[216:219], v[84:87]
	s_barrier
	s_add_i32 s52, s31, s19
	v_lshl_add_u64 v[172:173], s[24:25], 0, v[130:131]
	s_mov_b32 m0, s52
	ds_read_b128 v[232:235], v163
	ds_read_b128 v[236:239], v163 offset:1024
	ds_read_b128 v[240:243], v163 offset:2048
	ds_read_b128 v[244:247], v163 offset:3072
	global_load_lds_dwordx4 v[172:173], off
	v_lshl_add_u64 v[176:177], s[24:25], 0, v[134:135]
	s_add_i32 m0, s52, 0x2000
	s_nop 0
	global_load_lds_dwordx4 v[176:177], off
	s_barrier
	s_waitcnt lgkmcnt(0)
	v_mfma_f32_16x16x32_bf16 v[104:107], v[232:235], v[188:191], v[104:107]
	v_mfma_f32_16x16x32_bf16 v[96:99], v[240:243], v[188:191], v[96:99]
	v_mfma_f32_16x16x32_bf16 v[88:91], v[232:235], v[196:199], v[88:91]
	v_mfma_f32_16x16x32_bf16 v[80:83], v[240:243], v[196:199], v[80:83]
	v_mfma_f32_16x16x32_bf16 v[76:79], v[232:235], v[204:207], v[76:79]
	v_mfma_f32_16x16x32_bf16 v[72:75], v[240:243], v[204:207], v[72:75]
	v_mfma_f32_16x16x32_bf16 v[68:71], v[232:235], v[212:215], v[68:71]
	v_mfma_f32_16x16x32_bf16 v[64:67], v[240:243], v[212:215], v[64:67]
	v_mfma_f32_16x16x32_bf16 v[104:107], v[236:239], v[192:195], v[104:107]
	v_mfma_f32_16x16x32_bf16 v[96:99], v[244:247], v[192:195], v[96:99]
	v_mfma_f32_16x16x32_bf16 v[88:91], v[236:239], v[200:203], v[88:91]
	v_mfma_f32_16x16x32_bf16 v[80:83], v[244:247], v[200:203], v[80:83]
	v_mfma_f32_16x16x32_bf16 v[76:79], v[236:239], v[208:211], v[76:79]
	v_mfma_f32_16x16x32_bf16 v[72:75], v[244:247], v[208:211], v[72:75]
	v_mfma_f32_16x16x32_bf16 v[68:71], v[236:239], v[216:219], v[68:71]
	v_mfma_f32_16x16x32_bf16 v[64:67], v[244:247], v[216:219], v[64:67]
	s_mov_b32 m0, s3
	v_lshl_add_u64 v[248:249], s[34:35], 0, v[128:129]
	s_barrier
	ds_read_b128 v[188:191], v162 offset:16384
	ds_read_b128 v[192:195], v162 offset:17408
	ds_read_b128 v[196:199], v162 offset:18432
	ds_read_b128 v[200:203], v162 offset:19456
	ds_read_b128 v[204:207], v162 offset:20480
	ds_read_b128 v[208:211], v162 offset:21504
	ds_read_b128 v[212:215], v162 offset:22528
	ds_read_b128 v[216:219], v162 offset:23552
	global_load_lds_dwordx4 v[248:249], off
	v_lshl_add_u64 v[250:251], s[34:35], 0, v[132:133]
	s_mov_b32 m0, s20
	s_nop 0
	global_load_lds_dwordx4 v[250:251], off
	s_barrier
	s_waitcnt lgkmcnt(0)
	v_mfma_f32_16x16x32_bf16 v[60:63], v[164:167], v[188:191], v[60:63]
	v_mfma_f32_16x16x32_bf16 v[56:59], v[180:183], v[188:191], v[56:59]
	v_mfma_f32_16x16x32_bf16 v[52:55], v[164:167], v[196:199], v[52:55]
	v_mfma_f32_16x16x32_bf16 v[48:51], v[180:183], v[196:199], v[48:51]
	v_mfma_f32_16x16x32_bf16 v[44:47], v[164:167], v[204:207], v[44:47]
	v_mfma_f32_16x16x32_bf16 v[40:43], v[180:183], v[204:207], v[40:43]
	v_mfma_f32_16x16x32_bf16 v[28:31], v[164:167], v[212:215], v[28:31]
	v_mfma_f32_16x16x32_bf16 v[24:27], v[180:183], v[212:215], v[24:27]
	v_mfma_f32_16x16x32_bf16 v[60:63], v[168:171], v[192:195], v[60:63]
	v_mfma_f32_16x16x32_bf16 v[56:59], v[184:187], v[192:195], v[56:59]
	v_mfma_f32_16x16x32_bf16 v[52:55], v[168:171], v[200:203], v[52:55]
	v_mfma_f32_16x16x32_bf16 v[48:51], v[184:187], v[200:203], v[48:51]
	v_mfma_f32_16x16x32_bf16 v[44:47], v[168:171], v[208:211], v[44:47]
	v_mfma_f32_16x16x32_bf16 v[40:43], v[184:187], v[208:211], v[40:43]
	v_mfma_f32_16x16x32_bf16 v[28:31], v[168:171], v[216:219], v[28:31]
	v_mfma_f32_16x16x32_bf16 v[24:27], v[184:187], v[216:219], v[24:27]
	s_barrier
	s_add_u32 s52, s24, 0x80000
	s_addc_u32 s53, s25, 0
	s_add_i32 s54, s33, s19
	v_lshl_add_u64 v[164:165], s[52:53], 0, v[130:131]
	s_mov_b32 m0, s54
	s_nop 0
	global_load_lds_dwordx4 v[164:165], off
	v_lshl_add_u64 v[164:165], s[52:53], 0, v[134:135]
	s_add_i32 m0, s54, 0x2000
	s_nop 0
	global_load_lds_dwordx4 v[164:165], off
	s_waitcnt vmcnt(6)
	s_barrier
	v_mfma_f32_16x16x32_bf16 v[36:39], v[232:235], v[188:191], v[36:39]
	v_mfma_f32_16x16x32_bf16 v[32:35], v[240:243], v[188:191], v[32:35]
	v_mfma_f32_16x16x32_bf16 v[20:23], v[232:235], v[196:199], v[20:23]
	v_mfma_f32_16x16x32_bf16 v[16:19], v[240:243], v[196:199], v[16:19]
	v_mfma_f32_16x16x32_bf16 v[12:15], v[232:235], v[204:207], v[12:15]
	v_mfma_f32_16x16x32_bf16 v[8:11], v[240:243], v[204:207], v[8:11]
	v_mfma_f32_16x16x32_bf16 v[4:7], v[232:235], v[212:215], v[4:7]
	v_mfma_f32_16x16x32_bf16 v[0:3], v[240:243], v[212:215], v[0:3]
	v_mfma_f32_16x16x32_bf16 v[36:39], v[236:239], v[192:195], v[36:39]
	v_mfma_f32_16x16x32_bf16 v[32:35], v[244:247], v[192:195], v[32:35]
	v_mfma_f32_16x16x32_bf16 v[20:23], v[236:239], v[200:203], v[20:23]
	v_mfma_f32_16x16x32_bf16 v[16:19], v[244:247], v[200:203], v[16:19]
	v_mfma_f32_16x16x32_bf16 v[12:15], v[236:239], v[208:211], v[12:15]
	v_mfma_f32_16x16x32_bf16 v[8:11], v[244:247], v[208:211], v[8:11]
	v_mfma_f32_16x16x32_bf16 v[4:7], v[236:239], v[216:219], v[4:7]
	v_mfma_f32_16x16x32_bf16 v[0:3], v[244:247], v[216:219], v[0:3]
	s_add_i32 s52, 0, 0x18000
	v_add_u32_e32 v174, s52, v158
	s_barrier
	ds_read_b128 v[188:191], v162 offset:32768
	ds_read_b128 v[192:195], v162 offset:33792
	ds_read_b128 v[196:199], v162 offset:34816
	ds_read_b128 v[200:203], v162 offset:35840
	ds_read_b128 v[204:207], v162 offset:36864
	ds_read_b128 v[208:211], v162 offset:37888
	ds_read_b128 v[212:215], v162 offset:38912
	ds_read_b128 v[216:219], v162 offset:39936
	ds_read_b128 v[164:167], v174
	ds_read_b128 v[168:171], v174 offset:1024
	ds_read_b128 v[180:183], v174 offset:2048
	ds_read_b128 v[184:187], v174 offset:3072
	s_add_u32 s34, s34, 0x40000
	s_addc_u32 s35, s35, 0
	s_mov_b32 m0, s21
	v_lshl_add_u64 v[232:233], s[34:35], 0, v[128:129]
	global_load_lds_dwordx4 v[232:233], off
	v_lshl_add_u64 v[232:233], s[34:35], 0, v[132:133]
	s_mov_b32 m0, s27
	s_nop 0
	global_load_lds_dwordx4 v[232:233], off
	s_waitcnt lgkmcnt(0)
	s_barrier
	s_waitcnt lgkmcnt(0)
	v_mfma_f32_16x16x32_bf16 v[124:127], v[164:167], v[188:191], v[124:127]
	v_mfma_f32_16x16x32_bf16 v[120:123], v[180:183], v[188:191], v[120:123]
	v_mfma_f32_16x16x32_bf16 v[116:119], v[164:167], v[196:199], v[116:119]
	v_mfma_f32_16x16x32_bf16 v[112:115], v[180:183], v[196:199], v[112:115]
	v_mfma_f32_16x16x32_bf16 v[108:111], v[164:167], v[204:207], v[108:111]
	v_mfma_f32_16x16x32_bf16 v[100:103], v[180:183], v[204:207], v[100:103]
	v_mfma_f32_16x16x32_bf16 v[92:95], v[164:167], v[212:215], v[92:95]
	v_mfma_f32_16x16x32_bf16 v[84:87], v[180:183], v[212:215], v[84:87]
	v_mfma_f32_16x16x32_bf16 v[124:127], v[168:171], v[192:195], v[124:127]
	v_mfma_f32_16x16x32_bf16 v[120:123], v[184:187], v[192:195], v[120:123]
	v_mfma_f32_16x16x32_bf16 v[116:119], v[168:171], v[200:203], v[116:119]
	v_mfma_f32_16x16x32_bf16 v[112:115], v[184:187], v[200:203], v[112:115]
	v_mfma_f32_16x16x32_bf16 v[108:111], v[168:171], v[208:211], v[108:111]
	v_mfma_f32_16x16x32_bf16 v[100:103], v[184:187], v[208:211], v[100:103]
	v_mfma_f32_16x16x32_bf16 v[92:95], v[168:171], v[216:219], v[92:95]
	v_mfma_f32_16x16x32_bf16 v[84:87], v[184:187], v[216:219], v[84:87]
	s_barrier
	s_add_i32 s34, 0, 0x1c000
	s_add_i32 s35, s52, s19
	v_add_u32_e32 v174, s34, v158
	v_lshl_add_u64 v[172:173], v[172:173], 0, s[4:5]
	s_mov_b32 m0, s35
	ds_read_b128 v[232:235], v174
	ds_read_b128 v[236:239], v174 offset:1024
	ds_read_b128 v[240:243], v174 offset:2048
	ds_read_b128 v[244:247], v174 offset:3072
	global_load_lds_dwordx4 v[172:173], off
	v_lshl_add_u64 v[172:173], v[176:177], 0, s[4:5]
	s_add_i32 m0, s35, 0x2000
	s_nop 0
	global_load_lds_dwordx4 v[172:173], off
	s_barrier
	s_waitcnt lgkmcnt(0)
	v_mfma_f32_16x16x32_bf16 v[104:107], v[232:235], v[188:191], v[104:107]
	v_mfma_f32_16x16x32_bf16 v[96:99], v[240:243], v[188:191], v[96:99]
	v_mfma_f32_16x16x32_bf16 v[88:91], v[232:235], v[196:199], v[88:91]
	v_mfma_f32_16x16x32_bf16 v[80:83], v[240:243], v[196:199], v[80:83]
	v_mfma_f32_16x16x32_bf16 v[76:79], v[232:235], v[204:207], v[76:79]
	v_mfma_f32_16x16x32_bf16 v[72:75], v[240:243], v[204:207], v[72:75]
	v_mfma_f32_16x16x32_bf16 v[68:71], v[232:235], v[212:215], v[68:71]
	v_mfma_f32_16x16x32_bf16 v[64:67], v[240:243], v[212:215], v[64:67]
	v_mfma_f32_16x16x32_bf16 v[104:107], v[236:239], v[192:195], v[104:107]
	v_mfma_f32_16x16x32_bf16 v[96:99], v[244:247], v[192:195], v[96:99]
	v_mfma_f32_16x16x32_bf16 v[88:91], v[236:239], v[200:203], v[88:91]
	v_mfma_f32_16x16x32_bf16 v[80:83], v[244:247], v[200:203], v[80:83]
	v_mfma_f32_16x16x32_bf16 v[76:79], v[236:239], v[208:211], v[76:79]
	v_mfma_f32_16x16x32_bf16 v[72:75], v[244:247], v[208:211], v[72:75]
	v_mfma_f32_16x16x32_bf16 v[68:71], v[236:239], v[216:219], v[68:71]
	v_mfma_f32_16x16x32_bf16 v[64:67], v[244:247], v[216:219], v[64:67]
	s_mov_b32 m0, s29
	v_lshl_add_u64 v[172:173], v[248:249], 0, s[4:5]
	s_barrier
	ds_read_b128 v[188:191], v162 offset:49152
	ds_read_b128 v[192:195], v162 offset:50176
	ds_read_b128 v[196:199], v162 offset:51200
	ds_read_b128 v[200:203], v162 offset:52224
	ds_read_b128 v[204:207], v162 offset:53248
	ds_read_b128 v[208:211], v162 offset:54272
	ds_read_b128 v[212:215], v162 offset:55296
	ds_read_b128 v[216:219], v162 offset:56320
	global_load_lds_dwordx4 v[172:173], off
	v_lshl_add_u64 v[172:173], v[250:251], 0, s[4:5]
	s_mov_b32 m0, s30
	s_nop 0
	global_load_lds_dwordx4 v[172:173], off
	s_barrier
	s_waitcnt lgkmcnt(0)
	v_mfma_f32_16x16x32_bf16 v[60:63], v[164:167], v[188:191], v[60:63]
	v_mfma_f32_16x16x32_bf16 v[56:59], v[180:183], v[188:191], v[56:59]
	v_mfma_f32_16x16x32_bf16 v[52:55], v[164:167], v[196:199], v[52:55]
	v_mfma_f32_16x16x32_bf16 v[48:51], v[180:183], v[196:199], v[48:51]
	v_mfma_f32_16x16x32_bf16 v[44:47], v[164:167], v[204:207], v[44:47]
	v_mfma_f32_16x16x32_bf16 v[40:43], v[180:183], v[204:207], v[40:43]
	v_mfma_f32_16x16x32_bf16 v[28:31], v[164:167], v[212:215], v[28:31]
	v_mfma_f32_16x16x32_bf16 v[24:27], v[180:183], v[212:215], v[24:27]
	v_mfma_f32_16x16x32_bf16 v[60:63], v[168:171], v[192:195], v[60:63]
	v_mfma_f32_16x16x32_bf16 v[56:59], v[184:187], v[192:195], v[56:59]
	v_mfma_f32_16x16x32_bf16 v[52:55], v[168:171], v[200:203], v[52:55]
	v_mfma_f32_16x16x32_bf16 v[48:51], v[184:187], v[200:203], v[48:51]
	v_mfma_f32_16x16x32_bf16 v[44:47], v[168:171], v[208:211], v[44:47]
	v_mfma_f32_16x16x32_bf16 v[40:43], v[184:187], v[208:211], v[40:43]
	v_mfma_f32_16x16x32_bf16 v[28:31], v[168:171], v[216:219], v[28:31]
	v_mfma_f32_16x16x32_bf16 v[24:27], v[184:187], v[216:219], v[24:27]
	s_barrier
	s_add_u32 s24, s24, 0x80080
	s_addc_u32 s25, s25, 0
	s_add_i32 s34, s34, s19
	v_lshl_add_u64 v[164:165], s[24:25], 0, v[130:131]
	s_mov_b32 m0, s34
	s_nop 0
	global_load_lds_dwordx4 v[164:165], off
	v_lshl_add_u64 v[164:165], s[24:25], 0, v[134:135]
	s_add_i32 m0, s34, 0x2000
	s_nop 0
	global_load_lds_dwordx4 v[164:165], off
	s_waitcnt vmcnt(6)
	s_barrier
	v_mfma_f32_16x16x32_bf16 v[36:39], v[232:235], v[188:191], v[36:39]
	v_mfma_f32_16x16x32_bf16 v[32:35], v[240:243], v[188:191], v[32:35]
	v_mfma_f32_16x16x32_bf16 v[20:23], v[232:235], v[196:199], v[20:23]
	v_mfma_f32_16x16x32_bf16 v[16:19], v[240:243], v[196:199], v[16:19]
	v_mfma_f32_16x16x32_bf16 v[12:15], v[232:235], v[204:207], v[12:15]
	v_mfma_f32_16x16x32_bf16 v[8:11], v[240:243], v[204:207], v[8:11]
	v_mfma_f32_16x16x32_bf16 v[4:7], v[232:235], v[212:215], v[4:7]
	v_mfma_f32_16x16x32_bf16 v[0:3], v[240:243], v[212:215], v[0:3]
	v_mfma_f32_16x16x32_bf16 v[36:39], v[236:239], v[192:195], v[36:39]
	v_mfma_f32_16x16x32_bf16 v[32:35], v[244:247], v[192:195], v[32:35]
	v_mfma_f32_16x16x32_bf16 v[20:23], v[236:239], v[200:203], v[20:23]
	v_mfma_f32_16x16x32_bf16 v[16:19], v[244:247], v[200:203], v[16:19]
	v_mfma_f32_16x16x32_bf16 v[12:15], v[236:239], v[208:211], v[12:15]
	v_mfma_f32_16x16x32_bf16 v[8:11], v[244:247], v[208:211], v[8:11]
	v_mfma_f32_16x16x32_bf16 v[4:7], v[236:239], v[216:219], v[4:7]
	v_mfma_f32_16x16x32_bf16 v[0:3], v[244:247], v[216:219], v[0:3]
	s_add_i32 s45, s45, 2
	s_add_u32 s22, s22, 0x100
	s_addc_u32 s23, s23, 0
	s_add_u32 s43, s43, 0x100
	s_addc_u32 s44, s44, 0
	s_cmp_gt_u32 s45, 5
	s_barrier
	s_cbranch_scc0 .LBB0_612
	s_lshl_b32 s7, s26, 2
	s_and_b32 s7, s7, 0x7fffffe0
	s_add_i32 s22, s7, s2
	s_ashr_i32 s23, s22, 31
	s_lshl_b64 s[22:23], s[22:23], 18
	s_add_u32 s22, s82, s22
	s_addc_u32 s23, s83, s23
	v_lshl_add_u64 v[164:165], s[22:23], 0, v[138:139]
	v_lshl_add_u64 v[164:165], v[164:165], 0, v[136:137]
	global_store_dwordx4 v[164:165], v[124:127], off
	global_store_dwordx4 v[164:165], v[120:123], off offset:16
	global_store_dwordx4 v[164:165], v[104:107], off offset:512
	global_store_dwordx4 v[164:165], v[96:99], off offset:528
	s_and_b64 vcc, exec, s[10:11]
	s_mov_b32 s26, s40
	v_lshl_add_u64 v[96:97], s[22:23], 0, v[140:141]
	v_lshl_add_u64 v[96:97], v[96:97], 0, v[136:137]
	global_store_dwordx4 v[96:97], v[116:119], off
	global_store_dwordx4 v[96:97], v[112:115], off offset:16
	global_store_dwordx4 v[96:97], v[88:91], off offset:512
	global_store_dwordx4 v[96:97], v[80:83], off offset:528
	s_mov_b32 s2, s8
	s_mov_b64 s[24:25], s[16:17]
	v_lshl_add_u64 v[80:81], s[22:23], 0, v[142:143]
	v_lshl_add_u64 v[80:81], v[80:81], 0, v[136:137]
	global_store_dwordx4 v[80:81], v[108:111], off
	global_store_dwordx4 v[80:81], v[100:103], off offset:16
	global_store_dwordx4 v[80:81], v[76:79], off offset:512
	global_store_dwordx4 v[80:81], v[72:75], off offset:528
	s_nop 1
	v_lshl_add_u64 v[72:73], s[22:23], 0, v[144:145]
	v_lshl_add_u64 v[72:73], v[72:73], 0, v[136:137]
	global_store_dwordx4 v[72:73], v[92:95], off
	global_store_dwordx4 v[72:73], v[84:87], off offset:16
	global_store_dwordx4 v[72:73], v[68:71], off offset:512
	global_store_dwordx4 v[72:73], v[64:67], off offset:528
	s_nop 1
	v_lshl_add_u64 v[64:65], s[22:23], 0, v[146:147]
	v_lshl_add_u64 v[64:65], v[64:65], 0, v[136:137]
	global_store_dwordx4 v[64:65], v[60:63], off
	global_store_dwordx4 v[64:65], v[56:59], off offset:16
	global_store_dwordx4 v[64:65], v[36:39], off offset:512
	global_store_dwordx4 v[64:65], v[32:35], off offset:528
	s_nop 1
	v_lshl_add_u64 v[32:33], s[22:23], 0, v[148:149]
	v_lshl_add_u64 v[32:33], v[32:33], 0, v[136:137]
	global_store_dwordx4 v[32:33], v[52:55], off
	global_store_dwordx4 v[32:33], v[48:51], off offset:16
	global_store_dwordx4 v[32:33], v[20:23], off offset:512
	global_store_dwordx4 v[32:33], v[16:19], off offset:528
	s_nop 1
	v_lshl_add_u64 v[16:17], s[22:23], 0, v[150:151]
	v_lshl_add_u64 v[16:17], v[16:17], 0, v[136:137]
	global_store_dwordx4 v[16:17], v[44:47], off
	global_store_dwordx4 v[16:17], v[40:43], off offset:16
	global_store_dwordx4 v[16:17], v[12:15], off offset:512
	global_store_dwordx4 v[16:17], v[8:11], off offset:528
	s_nop 1
	v_lshl_add_u64 v[8:9], s[22:23], 0, v[152:153]
	v_lshl_add_u64 v[8:9], v[8:9], 0, v[136:137]
	s_mov_b64 s[22:23], s[14:15]
	global_store_dwordx4 v[8:9], v[28:31], off
	global_store_dwordx4 v[8:9], v[24:27], off offset:16
	global_store_dwordx4 v[8:9], v[4:7], off offset:512
	global_store_dwordx4 v[8:9], v[0:3], off offset:528
	s_cbranch_vccz .LBB0_606
	s_waitcnt vmcnt(0)
	s_cmpk_gt_u32 s18, 0xff
	s_cbranch_scc1 .LBB0_616
	s_barrier

.LBB0_1268:
	ds_read_b128 v[164:167], v150
	ds_read_b128 v[168:171], v150 offset:1024
	ds_read_b128 v[172:175], v150 offset:2048
	ds_read_b128 v[180:183], v150 offset:3072
	ds_read_b128 v[184:187], v150 offset:4096
	ds_read_b128 v[188:191], v150 offset:5120
	ds_read_b128 v[192:195], v150 offset:6144
	ds_read_b128 v[196:199], v150 offset:7168
	ds_read_b128 v[140:143], v149
	ds_read_b128 v[152:155], v149 offset:1024
	ds_read_b128 v[156:159], v149 offset:2048
	ds_read_b128 v[160:163], v149 offset:3072
	s_add_u32 s22, s10, 0xfffe0080
	s_addc_u32 s23, s11, -1
	s_cmp_eq_u32 s44, 4
	s_cselect_b32 s25, s13, s23
	s_cselect_b32 s24, s40, s22
	s_cselect_b32 s23, s15, s43
	s_cselect_b32 s22, s41, s42
	v_lshl_add_u64 v[144:145], s[10:11], 0, v[136:137]
	s_add_i32 m0, s1, 0xc000
	global_load_lds_dwordx4 v[144:145], off
	v_lshl_add_u64 v[144:145], s[10:11], 0, v[138:139]
	s_add_i32 m0, s1, 0xe000
	s_nop 0
	global_load_lds_dwordx4 v[144:145], off
	s_waitcnt lgkmcnt(0)
	s_barrier
	s_waitcnt lgkmcnt(0)
	v_mfma_f32_16x16x32_bf16 v[124:127], v[140:143], v[164:167], v[124:127]
	v_mfma_f32_16x16x32_bf16 v[120:123], v[156:159], v[164:167], v[120:123]
	v_mfma_f32_16x16x32_bf16 v[112:115], v[140:143], v[172:175], v[112:115]
	v_mfma_f32_16x16x32_bf16 v[104:107], v[156:159], v[172:175], v[104:107]
	v_mfma_f32_16x16x32_bf16 v[96:99], v[140:143], v[184:187], v[96:99]
	v_mfma_f32_16x16x32_bf16 v[88:91], v[156:159], v[184:187], v[88:91]
	v_mfma_f32_16x16x32_bf16 v[80:83], v[140:143], v[192:195], v[80:83]
	v_mfma_f32_16x16x32_bf16 v[72:75], v[156:159], v[192:195], v[72:75]
	v_mfma_f32_16x16x32_bf16 v[124:127], v[152:155], v[168:171], v[124:127]
	v_mfma_f32_16x16x32_bf16 v[120:123], v[160:163], v[168:171], v[120:123]
	v_mfma_f32_16x16x32_bf16 v[112:115], v[152:155], v[180:183], v[112:115]
	v_mfma_f32_16x16x32_bf16 v[104:107], v[160:163], v[180:183], v[104:107]
	v_mfma_f32_16x16x32_bf16 v[96:99], v[152:155], v[188:191], v[96:99]
	v_mfma_f32_16x16x32_bf16 v[88:91], v[160:163], v[188:191], v[88:91]
	v_mfma_f32_16x16x32_bf16 v[80:83], v[152:155], v[196:199], v[80:83]
	v_mfma_f32_16x16x32_bf16 v[72:75], v[160:163], v[196:199], v[72:75]
	s_barrier
	s_add_i32 s45, s35, s27
	v_lshl_add_u64 v[144:145], s[22:23], 0, v[132:133]
	s_mov_b32 m0, s45
	ds_read_b128 v[200:203], v151
	ds_read_b128 v[204:207], v151 offset:1024
	ds_read_b128 v[208:211], v151 offset:2048
	ds_read_b128 v[212:215], v151 offset:3072
	global_load_lds_dwordx4 v[144:145], off
	v_lshl_add_u64 v[176:177], s[22:23], 0, v[128:129]
	s_add_i32 m0, s45, 0x2000
	s_nop 0
	global_load_lds_dwordx4 v[176:177], off
	s_barrier
	s_waitcnt lgkmcnt(0)
	v_mfma_f32_16x16x32_bf16 v[116:119], v[200:203], v[164:167], v[116:119]
	v_mfma_f32_16x16x32_bf16 v[108:111], v[208:211], v[164:167], v[108:111]
	v_mfma_f32_16x16x32_bf16 v[100:103], v[200:203], v[172:175], v[100:103]
	v_mfma_f32_16x16x32_bf16 v[92:95], v[208:211], v[172:175], v[92:95]
	v_mfma_f32_16x16x32_bf16 v[84:87], v[200:203], v[184:187], v[84:87]
	v_mfma_f32_16x16x32_bf16 v[76:79], v[208:211], v[184:187], v[76:79]
	v_mfma_f32_16x16x32_bf16 v[68:71], v[200:203], v[192:195], v[68:71]
	v_mfma_f32_16x16x32_bf16 v[64:67], v[208:211], v[192:195], v[64:67]
	v_mfma_f32_16x16x32_bf16 v[116:119], v[204:207], v[168:171], v[116:119]
	v_mfma_f32_16x16x32_bf16 v[108:111], v[212:215], v[168:171], v[108:111]
	v_mfma_f32_16x16x32_bf16 v[100:103], v[204:207], v[180:183], v[100:103]
	v_mfma_f32_16x16x32_bf16 v[92:95], v[212:215], v[180:183], v[92:95]
	v_mfma_f32_16x16x32_bf16 v[84:87], v[204:207], v[188:191], v[84:87]
	v_mfma_f32_16x16x32_bf16 v[76:79], v[212:215], v[188:191], v[76:79]
	v_mfma_f32_16x16x32_bf16 v[68:71], v[204:207], v[196:199], v[68:71]
	v_mfma_f32_16x16x32_bf16 v[64:67], v[212:215], v[196:199], v[64:67]
	s_mov_b32 m0, s1
	v_lshl_add_u64 v[216:217], s[24:25], 0, v[134:135]
	s_barrier
	ds_read_b128 v[164:167], v150 offset:16384
	ds_read_b128 v[168:171], v150 offset:17408
	ds_read_b128 v[172:175], v150 offset:18432
	ds_read_b128 v[180:183], v150 offset:19456
	ds_read_b128 v[184:187], v150 offset:20480
	ds_read_b128 v[188:191], v150 offset:21504
	ds_read_b128 v[192:195], v150 offset:22528
	ds_read_b128 v[196:199], v150 offset:23552
	global_load_lds_dwordx4 v[216:217], off
	v_lshl_add_u64 v[218:219], s[24:25], 0, v[130:131]
	s_mov_b32 m0, s7
	s_nop 0
	global_load_lds_dwordx4 v[218:219], off
	s_barrier
	s_waitcnt lgkmcnt(0)
	v_mfma_f32_16x16x32_bf16 v[60:63], v[140:143], v[164:167], v[60:63]
	v_mfma_f32_16x16x32_bf16 v[56:59], v[156:159], v[164:167], v[56:59]
	v_mfma_f32_16x16x32_bf16 v[48:51], v[140:143], v[172:175], v[48:51]
	v_mfma_f32_16x16x32_bf16 v[40:43], v[156:159], v[172:175], v[40:43]
	v_mfma_f32_16x16x32_bf16 v[32:35], v[140:143], v[184:187], v[32:35]
	v_mfma_f32_16x16x32_bf16 v[24:27], v[156:159], v[184:187], v[24:27]
	v_mfma_f32_16x16x32_bf16 v[16:19], v[140:143], v[192:195], v[16:19]
	v_mfma_f32_16x16x32_bf16 v[8:11], v[156:159], v[192:195], v[8:11]
	v_mfma_f32_16x16x32_bf16 v[60:63], v[152:155], v[168:171], v[60:63]
	v_mfma_f32_16x16x32_bf16 v[56:59], v[160:163], v[168:171], v[56:59]
	v_mfma_f32_16x16x32_bf16 v[48:51], v[152:155], v[180:183], v[48:51]
	v_mfma_f32_16x16x32_bf16 v[40:43], v[160:163], v[180:183], v[40:43]
	v_mfma_f32_16x16x32_bf16 v[32:35], v[152:155], v[188:191], v[32:35]
	v_mfma_f32_16x16x32_bf16 v[24:27], v[160:163], v[188:191], v[24:27]
	v_mfma_f32_16x16x32_bf16 v[16:19], v[152:155], v[196:199], v[16:19]
	v_mfma_f32_16x16x32_bf16 v[8:11], v[160:163], v[196:199], v[8:11]
	s_barrier
	s_add_u32 s46, s22, 0x20000
	s_addc_u32 s47, s23, 0
	s_add_i32 s45, s36, s27
	v_lshl_add_u64 v[140:141], s[46:47], 0, v[132:133]
	s_mov_b32 m0, s45
	s_nop 0
	global_load_lds_dwordx4 v[140:141], off
	v_lshl_add_u64 v[140:141], s[46:47], 0, v[128:129]
	s_add_i32 m0, s45, 0x2000
	s_nop 0
	global_load_lds_dwordx4 v[140:141], off
	s_waitcnt vmcnt(6)
	s_barrier
	v_mfma_f32_16x16x32_bf16 v[52:55], v[200:203], v[164:167], v[52:55]
	v_mfma_f32_16x16x32_bf16 v[44:47], v[208:211], v[164:167], v[44:47]
	v_mfma_f32_16x16x32_bf16 v[36:39], v[200:203], v[172:175], v[36:39]
	v_mfma_f32_16x16x32_bf16 v[28:31], v[208:211], v[172:175], v[28:31]
	v_mfma_f32_16x16x32_bf16 v[20:23], v[200:203], v[184:187], v[20:23]
	v_mfma_f32_16x16x32_bf16 v[12:15], v[208:211], v[184:187], v[12:15]
	v_mfma_f32_16x16x32_bf16 v[4:7], v[200:203], v[192:195], v[4:7]
	v_mfma_f32_16x16x32_bf16 v[0:3], v[208:211], v[192:195], v[0:3]
	v_mfma_f32_16x16x32_bf16 v[52:55], v[204:207], v[168:171], v[52:55]
	v_mfma_f32_16x16x32_bf16 v[44:47], v[212:215], v[168:171], v[44:47]
	v_mfma_f32_16x16x32_bf16 v[36:39], v[204:207], v[180:183], v[36:39]
	v_mfma_f32_16x16x32_bf16 v[28:31], v[212:215], v[180:183], v[28:31]
	v_mfma_f32_16x16x32_bf16 v[20:23], v[204:207], v[188:191], v[20:23]
	v_mfma_f32_16x16x32_bf16 v[12:15], v[212:215], v[188:191], v[12:15]
	v_mfma_f32_16x16x32_bf16 v[4:7], v[204:207], v[196:199], v[4:7]
	v_mfma_f32_16x16x32_bf16 v[0:3], v[212:215], v[196:199], v[0:3]
	s_add_i32 s45, 0, 0x18000
	v_add_u32_e32 v160, s45, v147
	s_barrier
	ds_read_b128 v[164:167], v150 offset:32768
	ds_read_b128 v[168:171], v150 offset:33792
	ds_read_b128 v[172:175], v150 offset:34816
	ds_read_b128 v[180:183], v150 offset:35840
	ds_read_b128 v[184:187], v150 offset:36864
	ds_read_b128 v[188:191], v150 offset:37888
	ds_read_b128 v[192:195], v150 offset:38912
	ds_read_b128 v[196:199], v150 offset:39936
	ds_read_b128 v[140:143], v160
	ds_read_b128 v[152:155], v160 offset:1024
	ds_read_b128 v[156:159], v160 offset:2048
	ds_read_b128 v[160:163], v160 offset:3072
	s_add_u32 s24, s24, 0x20000
	s_addc_u32 s25, s25, 0
	s_mov_b32 m0, s28
	v_lshl_add_u64 v[200:201], s[24:25], 0, v[134:135]
	global_load_lds_dwordx4 v[200:201], off
	v_lshl_add_u64 v[200:201], s[24:25], 0, v[130:131]
	s_mov_b32 m0, s29
	s_nop 0
	global_load_lds_dwordx4 v[200:201], off
	s_waitcnt lgkmcnt(0)
	s_barrier
	s_waitcnt lgkmcnt(0)
	v_mfma_f32_16x16x32_bf16 v[124:127], v[140:143], v[164:167], v[124:127]
	v_mfma_f32_16x16x32_bf16 v[120:123], v[156:159], v[164:167], v[120:123]
	v_mfma_f32_16x16x32_bf16 v[112:115], v[140:143], v[172:175], v[112:115]
	v_mfma_f32_16x16x32_bf16 v[104:107], v[156:159], v[172:175], v[104:107]
	v_mfma_f32_16x16x32_bf16 v[96:99], v[140:143], v[184:187], v[96:99]
	v_mfma_f32_16x16x32_bf16 v[88:91], v[156:159], v[184:187], v[88:91]
	v_mfma_f32_16x16x32_bf16 v[80:83], v[140:143], v[192:195], v[80:83]
	v_mfma_f32_16x16x32_bf16 v[72:75], v[156:159], v[192:195], v[72:75]
	v_mfma_f32_16x16x32_bf16 v[124:127], v[152:155], v[168:171], v[124:127]
	v_mfma_f32_16x16x32_bf16 v[120:123], v[160:163], v[168:171], v[120:123]
	v_mfma_f32_16x16x32_bf16 v[112:115], v[152:155], v[180:183], v[112:115]
	v_mfma_f32_16x16x32_bf16 v[104:107], v[160:163], v[180:183], v[104:107]
	v_mfma_f32_16x16x32_bf16 v[96:99], v[152:155], v[188:191], v[96:99]
	v_mfma_f32_16x16x32_bf16 v[88:91], v[160:163], v[188:191], v[88:91]
	v_mfma_f32_16x16x32_bf16 v[80:83], v[152:155], v[196:199], v[80:83]
	v_mfma_f32_16x16x32_bf16 v[72:75], v[160:163], v[196:199], v[72:75]
	s_barrier
	s_add_i32 s24, 0, 0x1c000
	s_add_i32 s25, s45, s27
	v_add_u32_e32 v179, s24, v147
	v_lshl_add_u64 v[144:145], v[144:145], 0, s[2:3]
	s_mov_b32 m0, s25
	ds_read_b128 v[200:203], v179
	ds_read_b128 v[204:207], v179 offset:1024
	ds_read_b128 v[208:211], v179 offset:2048
	ds_read_b128 v[212:215], v179 offset:3072
	global_load_lds_dwordx4 v[144:145], off
	v_lshl_add_u64 v[144:145], v[176:177], 0, s[2:3]
	s_add_i32 m0, s25, 0x2000
	s_nop 0
	global_load_lds_dwordx4 v[144:145], off
	s_barrier
	s_waitcnt lgkmcnt(0)
	v_mfma_f32_16x16x32_bf16 v[116:119], v[200:203], v[164:167], v[116:119]
	v_mfma_f32_16x16x32_bf16 v[108:111], v[208:211], v[164:167], v[108:111]
	v_mfma_f32_16x16x32_bf16 v[100:103], v[200:203], v[172:175], v[100:103]
	v_mfma_f32_16x16x32_bf16 v[92:95], v[208:211], v[172:175], v[92:95]
	v_mfma_f32_16x16x32_bf16 v[84:87], v[200:203], v[184:187], v[84:87]
	v_mfma_f32_16x16x32_bf16 v[76:79], v[208:211], v[184:187], v[76:79]
	v_mfma_f32_16x16x32_bf16 v[68:71], v[200:203], v[192:195], v[68:71]
	v_mfma_f32_16x16x32_bf16 v[64:67], v[208:211], v[192:195], v[64:67]
	v_mfma_f32_16x16x32_bf16 v[116:119], v[204:207], v[168:171], v[116:119]
	v_mfma_f32_16x16x32_bf16 v[108:111], v[212:215], v[168:171], v[108:111]
	v_mfma_f32_16x16x32_bf16 v[100:103], v[204:207], v[180:183], v[100:103]
	v_mfma_f32_16x16x32_bf16 v[92:95], v[212:215], v[180:183], v[92:95]
	v_mfma_f32_16x16x32_bf16 v[84:87], v[204:207], v[188:191], v[84:87]
	v_mfma_f32_16x16x32_bf16 v[76:79], v[212:215], v[188:191], v[76:79]
	v_mfma_f32_16x16x32_bf16 v[68:71], v[204:207], v[196:199], v[68:71]
	v_mfma_f32_16x16x32_bf16 v[64:67], v[212:215], v[196:199], v[64:67]
	s_mov_b32 m0, s31
	v_lshl_add_u64 v[144:145], v[216:217], 0, s[2:3]
	s_barrier
	ds_read_b128 v[164:167], v150 offset:49152
	ds_read_b128 v[168:171], v150 offset:50176
	ds_read_b128 v[172:175], v150 offset:51200
	ds_read_b128 v[180:183], v150 offset:52224
	ds_read_b128 v[184:187], v150 offset:53248
	ds_read_b128 v[188:191], v150 offset:54272
	ds_read_b128 v[192:195], v150 offset:55296
	ds_read_b128 v[196:199], v150 offset:56320
	global_load_lds_dwordx4 v[144:145], off
	v_lshl_add_u64 v[144:145], v[218:219], 0, s[2:3]
	s_mov_b32 m0, s33
	s_nop 0
	global_load_lds_dwordx4 v[144:145], off
	s_barrier
	s_waitcnt lgkmcnt(0)
	v_mfma_f32_16x16x32_bf16 v[60:63], v[140:143], v[164:167], v[60:63]
	v_mfma_f32_16x16x32_bf16 v[56:59], v[156:159], v[164:167], v[56:59]
	v_mfma_f32_16x16x32_bf16 v[48:51], v[140:143], v[172:175], v[48:51]
	v_mfma_f32_16x16x32_bf16 v[40:43], v[156:159], v[172:175], v[40:43]
	v_mfma_f32_16x16x32_bf16 v[32:35], v[140:143], v[184:187], v[32:35]
	v_mfma_f32_16x16x32_bf16 v[24:27], v[156:159], v[184:187], v[24:27]
	v_mfma_f32_16x16x32_bf16 v[16:19], v[140:143], v[192:195], v[16:19]
	v_mfma_f32_16x16x32_bf16 v[8:11], v[156:159], v[192:195], v[8:11]
	v_mfma_f32_16x16x32_bf16 v[60:63], v[152:155], v[168:171], v[60:63]
	v_mfma_f32_16x16x32_bf16 v[56:59], v[160:163], v[168:171], v[56:59]
	v_mfma_f32_16x16x32_bf16 v[48:51], v[152:155], v[180:183], v[48:51]
	v_mfma_f32_16x16x32_bf16 v[40:43], v[160:163], v[180:183], v[40:43]
	v_mfma_f32_16x16x32_bf16 v[32:35], v[152:155], v[188:191], v[32:35]
	v_mfma_f32_16x16x32_bf16 v[24:27], v[160:163], v[188:191], v[24:27]
	v_mfma_f32_16x16x32_bf16 v[16:19], v[152:155], v[196:199], v[16:19]
	v_mfma_f32_16x16x32_bf16 v[8:11], v[160:163], v[196:199], v[8:11]
	s_barrier
	s_add_u32 s22, s22, 0x20080
	s_addc_u32 s23, s23, 0
	s_add_i32 s24, s24, s27
	v_lshl_add_u64 v[140:141], s[22:23], 0, v[132:133]
	s_mov_b32 m0, s24
	s_nop 0
	global_load_lds_dwordx4 v[140:141], off
	v_lshl_add_u64 v[140:141], s[22:23], 0, v[128:129]
	s_add_i32 m0, s24, 0x2000
	s_nop 0
	global_load_lds_dwordx4 v[140:141], off
	s_waitcnt vmcnt(6)
	s_barrier
	v_mfma_f32_16x16x32_bf16 v[52:55], v[200:203], v[164:167], v[52:55]
	v_mfma_f32_16x16x32_bf16 v[44:47], v[208:211], v[164:167], v[44:47]
	v_mfma_f32_16x16x32_bf16 v[36:39], v[200:203], v[172:175], v[36:39]
	v_mfma_f32_16x16x32_bf16 v[28:31], v[208:211], v[172:175], v[28:31]
	v_mfma_f32_16x16x32_bf16 v[20:23], v[200:203], v[184:187], v[20:23]
	v_mfma_f32_16x16x32_bf16 v[12:15], v[208:211], v[184:187], v[12:15]
	v_mfma_f32_16x16x32_bf16 v[4:7], v[200:203], v[192:195], v[4:7]
	v_mfma_f32_16x16x32_bf16 v[0:3], v[208:211], v[192:195], v[0:3]
	v_mfma_f32_16x16x32_bf16 v[52:55], v[204:207], v[168:171], v[52:55]
	v_mfma_f32_16x16x32_bf16 v[44:47], v[212:215], v[168:171], v[44:47]
	v_mfma_f32_16x16x32_bf16 v[36:39], v[204:207], v[180:183], v[36:39]
	v_mfma_f32_16x16x32_bf16 v[28:31], v[212:215], v[180:183], v[28:31]
	v_mfma_f32_16x16x32_bf16 v[20:23], v[204:207], v[188:191], v[20:23]
	v_mfma_f32_16x16x32_bf16 v[12:15], v[212:215], v[188:191], v[12:15]
	v_mfma_f32_16x16x32_bf16 v[4:7], v[204:207], v[196:199], v[4:7]
	v_mfma_f32_16x16x32_bf16 v[0:3], v[212:215], v[196:199], v[0:3]
	s_add_i32 s44, s44, 2
	s_add_u32 s10, s10, 0x100
	s_addc_u32 s11, s11, 0
	s_add_u32 s42, s42, 0x100
	s_addc_u32 s43, s43, 0
	s_cmp_gt_u32 s44, 5
	s_barrier
	s_cbranch_scc0 .LBB0_1268
	v_lshl_add_u32 v142, s39, 8, v146
	s_nop 0
	v_lshl_or_b32 v140, s38, 8, v148
	v_ashrrev_i32_e32 v143, 31, v142
	s_nop 1
	v_readlane_b32 s46, v252, 13
	v_readlane_b32 s47, v252, 14
	v_ashrrev_i32_e32 v141, 31, v140
	v_lshlrev_b64 v[144:145], 12, v[142:143]
	s_mov_b64 s[42:43], s[46:47]
	v_lshl_add_u64 v[144:145], s[42:43], 0, v[144:145]
	v_lshlrev_b64 v[140:141], 1, v[140:141]
	v_or_b32_e32 v172, 16, v142
	v_lshl_add_u64 v[144:145], v[144:145], 0, v[140:141]
	v_ashrrev_i32_e32 v173, 31, v172
	global_load_dwordx4 v[152:155], v[144:145], off
	global_load_dwordx4 v[156:159], v[144:145], off offset:256
	v_lshlrev_b64 v[144:145], 12, v[172:173]
	v_lshl_add_u64 v[144:145], s[42:43], 0, v[144:145]
	v_lshl_add_u64 v[144:145], v[144:145], 0, v[140:141]
	global_load_dwordx4 v[160:163], v[144:145], off
	global_load_dwordx4 v[164:167], v[144:145], off offset:256
	v_or_b32_e32 v176, 32, v142
	v_ashrrev_i32_e32 v177, 31, v176
	v_lshlrev_b64 v[168:169], 12, v[176:177]
	v_lshl_add_u64 v[168:169], s[42:43], 0, v[168:169]
	v_lshl_add_u64 v[182:183], v[168:169], 0, v[140:141]
	global_load_dwordx4 v[168:171], v[182:183], off
	v_or_b32_e32 v144, 48, v142
	v_ashrrev_i32_e32 v145, 31, v144
	v_lshlrev_b64 v[180:181], 12, v[144:145]
	v_lshlrev_b64 v[174:175], 11, v[142:143]
	v_lshlrev_b64 v[172:173], 11, v[172:173]
	v_lshl_add_u64 v[180:181], s[42:43], 0, v[180:181]
	v_lshl_add_u64 v[174:175], s[82:83], 0, v[174:175]
	v_lshl_add_u64 v[172:173], s[82:83], 0, v[172:173]
	v_lshl_add_u64 v[184:185], v[180:181], 0, v[140:141]
	v_lshl_add_u64 v[188:189], v[174:175], 0, v[140:141]
	v_lshl_add_u64 v[190:191], v[172:173], 0, v[140:141]
	global_load_dwordx4 v[172:175], v[182:183], off offset:256
	s_nop 0
	global_load_dwordx4 v[180:183], v[184:185], off
	s_nop 0
	global_load_dwordx4 v[184:187], v[184:185], off offset:256
	v_add_u32_e32 v234, 0x80, v142
	v_ashrrev_i32_e32 v235, 31, v234
	v_lshlrev_b64 v[236:237], 12, v[234:235]
	v_lshl_add_u64 v[236:237], s[42:43], 0, v[236:237]
	v_lshl_add_u64 v[236:237], v[236:237], 0, v[140:141]
	global_load_dwordx4 v[200:203], v[236:237], off
	global_load_dwordx4 v[204:207], v[236:237], off offset:256
	v_add_u32_e32 v234, 0x90, v142
	v_ashrrev_i32_e32 v235, 31, v234
	v_lshlrev_b64 v[236:237], 12, v[234:235]
	v_lshl_add_u64 v[236:237], s[42:43], 0, v[236:237]
	v_lshl_add_u64 v[236:237], v[236:237], 0, v[140:141]
	global_load_dwordx4 v[208:211], v[236:237], off
	global_load_dwordx4 v[212:215], v[236:237], off offset:256
	v_add_u32_e32 v234, 0xa0, v142
	v_ashrrev_i32_e32 v235, 31, v234
	v_lshlrev_b64 v[236:237], 12, v[234:235]
	v_lshl_add_u64 v[236:237], s[42:43], 0, v[236:237]
	v_lshl_add_u64 v[236:237], v[236:237], 0, v[140:141]
	global_load_dwordx4 v[216:219], v[236:237], off
	global_load_dwordx4 v[222:225], v[236:237], off offset:256
	v_add_u32_e32 v234, 0xb0, v142
	v_ashrrev_i32_e32 v235, 31, v234
	v_lshlrev_b64 v[236:237], 12, v[234:235]
	v_lshl_add_u64 v[236:237], s[42:43], 0, v[236:237]
	v_lshl_add_u64 v[236:237], v[236:237], 0, v[140:141]
	global_load_dwordx4 v[226:229], v[236:237], off
	global_load_dwordx4 v[230:233], v[236:237], off offset:256
	s_and_b64 vcc, exec, s[18:19]
	s_mov_b32 s38, s14
	s_mov_b32 s39, s12
	s_mov_b32 s15, s14
	s_mov_b32 s18, s12
	s_mov_b64 s[22:23], s[20:21]
	s_mov_b64 s[10:11], s[16:17]
	s_mov_b32 s13, s37
	s_nop 7
	s_nop 2
	s_waitcnt vmcnt(8)
	v_lshlrev_b32_e32 v194, 16, v154
	v_and_b32_e32 v195, 0xffff0000, v154
	v_lshlrev_b32_e32 v154, 16, v155
	v_and_b32_e32 v155, 0xffff0000, v155
	v_lshlrev_b32_e32 v196, 16, v156
	v_and_b32_e32 v197, 0xffff0000, v156
	v_lshlrev_b32_e32 v156, 16, v157
	v_and_b32_e32 v157, 0xffff0000, v157
	v_lshlrev_b32_e32 v198, 16, v158
	v_and_b32_e32 v199, 0xffff0000, v158
	v_lshlrev_b32_e32 v158, 16, v159
	v_and_b32_e32 v159, 0xffff0000, v159
	v_lshlrev_b32_e32 v192, 16, v152
	v_and_b32_e32 v193, 0xffff0000, v152
	v_lshlrev_b32_e32 v152, 16, v153
	v_and_b32_e32 v153, 0xffff0000, v153
	v_pk_mul_f32 v[120:121], v[120:121], v[194:195]
	v_pk_mul_f32 v[122:123], v[122:123], v[154:155]
	v_pk_mul_f32 v[118:119], v[118:119], v[156:157]
	v_pk_mul_f32 v[154:155], v[110:111], v[158:159]
	v_lshlrev_b32_e32 v156, 16, v160
	v_and_b32_e32 v157, 0xffff0000, v160
	v_lshlrev_b32_e32 v158, 16, v161
	v_and_b32_e32 v159, 0xffff0000, v161
	v_lshlrev_b32_e32 v160, 16, v162
	v_and_b32_e32 v161, 0xffff0000, v162
	v_lshlrev_b32_e32 v162, 16, v163
	v_and_b32_e32 v163, 0xffff0000, v163
	v_pk_mul_f32 v[124:125], v[124:125], v[192:193]
	v_pk_mul_f32 v[126:127], v[126:127], v[152:153]
	v_cvt_pk_bf16_f32 v110, v120, v121
	v_cvt_pk_bf16_f32 v111, v122, v123
	v_pk_mul_f32 v[112:113], v[112:113], v[156:157]
	v_pk_mul_f32 v[114:115], v[114:115], v[158:159]
	v_pk_mul_f32 v[120:121], v[104:105], v[160:161]
	v_pk_mul_f32 v[122:123], v[106:107], v[162:163]
	v_pk_mul_f32 v[116:117], v[116:117], v[196:197]
	v_pk_mul_f32 v[152:153], v[108:109], v[198:199]
	v_cvt_pk_bf16_f32 v108, v124, v125
	v_cvt_pk_bf16_f32 v109, v126, v127
	v_cvt_pk_bf16_f32 v104, v112, v113
	v_cvt_pk_bf16_f32 v105, v114, v115
	v_cvt_pk_bf16_f32 v106, v120, v121
	v_cvt_pk_bf16_f32 v107, v122, v123
	v_cvt_pk_bf16_f32 v116, v116, v117
	v_cvt_pk_bf16_f32 v117, v118, v119
	v_cvt_pk_bf16_f32 v118, v152, v153
	v_cvt_pk_bf16_f32 v119, v154, v155
	global_store_dwordx4 v[188:189], v[108:111], off
	global_store_dwordx4 v[188:189], v[116:119], off offset:256
	global_store_dwordx4 v[190:191], v[104:107], off
	v_lshlrev_b32_e32 v192, 16, v164
	v_and_b32_e32 v193, 0xffff0000, v164
	v_lshlrev_b32_e32 v104, 16, v165
	v_and_b32_e32 v105, 0xffff0000, v165
	v_pk_mul_f32 v[102:103], v[102:103], v[104:105]
	v_lshlrev_b32_e32 v104, 16, v166
	v_and_b32_e32 v105, 0xffff0000, v166
	v_pk_mul_f32 v[104:105], v[92:93], v[104:105]
	v_lshlrev_b32_e32 v92, 16, v167
	v_and_b32_e32 v93, 0xffff0000, v167
	v_pk_mul_f32 v[100:101], v[100:101], v[192:193]
	v_pk_mul_f32 v[106:107], v[94:95], v[92:93]
	v_cvt_pk_bf16_f32 v92, v100, v101
	v_cvt_pk_bf16_f32 v93, v102, v103
	v_cvt_pk_bf16_f32 v94, v104, v105
	v_cvt_pk_bf16_f32 v95, v106, v107
	global_store_dwordx4 v[190:191], v[92:95], off offset:256
	v_add_u32_e32 v102, 0xb0, v142
	v_ashrrev_i32_e32 v103, 31, v102
	v_lshlrev_b32_e32 v94, 16, v168
	v_and_b32_e32 v95, 0xffff0000, v168
	v_pk_mul_f32 v[94:95], v[96:97], v[94:95]
	v_lshlrev_b32_e32 v96, 16, v169
	v_and_b32_e32 v97, 0xffff0000, v169
	v_pk_mul_f32 v[96:97], v[98:99], v[96:97]
	v_lshlrev_b32_e32 v98, 16, v170
	v_and_b32_e32 v99, 0xffff0000, v170
	v_lshlrev_b64 v[92:93], 11, v[176:177]
	v_pk_mul_f32 v[98:99], v[88:89], v[98:99]
	v_lshlrev_b32_e32 v88, 16, v171
	v_and_b32_e32 v89, 0xffff0000, v171
	v_pk_mul_f32 v[100:101], v[90:91], v[88:89]
	v_lshl_add_u64 v[92:93], s[82:83], 0, v[92:93]
	v_cvt_pk_bf16_f32 v88, v94, v95
	v_cvt_pk_bf16_f32 v89, v96, v97
	v_cvt_pk_bf16_f32 v90, v98, v99
	v_cvt_pk_bf16_f32 v91, v100, v101
	v_lshl_add_u64 v[92:93], v[92:93], 0, v[140:141]
	global_store_dwordx4 v[92:93], v[88:91], off
	v_add_u32_e32 v96, 0x80, v142
	v_ashrrev_i32_e32 v97, 31, v96
	v_lshlrev_b32_e32 v88, 16, v172
	v_and_b32_e32 v89, 0xffff0000, v172
	v_pk_mul_f32 v[84:85], v[84:85], v[88:89]
	v_lshlrev_b32_e32 v88, 16, v173
	v_and_b32_e32 v89, 0xffff0000, v173
	v_pk_mul_f32 v[86:87], v[86:87], v[88:89]
	v_lshlrev_b32_e32 v88, 16, v174
	v_and_b32_e32 v89, 0xffff0000, v174
	v_pk_mul_f32 v[88:89], v[76:77], v[88:89]
	v_lshlrev_b32_e32 v76, 16, v175
	v_and_b32_e32 v77, 0xffff0000, v175
	v_pk_mul_f32 v[90:91], v[78:79], v[76:77]
	v_cvt_pk_bf16_f32 v76, v84, v85
	v_cvt_pk_bf16_f32 v77, v86, v87
	v_cvt_pk_bf16_f32 v78, v88, v89
	v_cvt_pk_bf16_f32 v79, v90, v91
	global_store_dwordx4 v[92:93], v[76:79], off offset:256
	v_add_u32_e32 v98, 0x90, v142
	v_ashrrev_i32_e32 v99, 31, v98
	v_lshlrev_b32_e32 v78, 16, v180
	v_and_b32_e32 v79, 0xffff0000, v180
	v_pk_mul_f32 v[78:79], v[80:81], v[78:79]
	v_lshlrev_b32_e32 v80, 16, v181
	v_and_b32_e32 v81, 0xffff0000, v181
	v_pk_mul_f32 v[80:81], v[82:83], v[80:81]
	v_lshlrev_b32_e32 v82, 16, v182
	v_and_b32_e32 v83, 0xffff0000, v182
	v_lshlrev_b64 v[76:77], 11, v[144:145]
	v_pk_mul_f32 v[82:83], v[72:73], v[82:83]
	v_lshlrev_b32_e32 v72, 16, v183
	v_and_b32_e32 v73, 0xffff0000, v183
	v_pk_mul_f32 v[84:85], v[74:75], v[72:73]
	v_lshl_add_u64 v[76:77], s[82:83], 0, v[76:77]
	v_cvt_pk_bf16_f32 v72, v78, v79
	v_cvt_pk_bf16_f32 v73, v80, v81
	v_cvt_pk_bf16_f32 v74, v82, v83
	v_cvt_pk_bf16_f32 v75, v84, v85
	v_lshl_add_u64 v[76:77], v[76:77], 0, v[140:141]
	global_store_dwordx4 v[76:77], v[72:75], off
	v_add_u32_e32 v100, 0xa0, v142
	v_ashrrev_i32_e32 v101, 31, v100
	v_lshlrev_b32_e32 v72, 16, v184
	v_and_b32_e32 v73, 0xffff0000, v184
	v_pk_mul_f32 v[68:69], v[68:69], v[72:73]
	v_lshlrev_b32_e32 v72, 16, v185
	v_and_b32_e32 v73, 0xffff0000, v185
	v_pk_mul_f32 v[70:71], v[70:71], v[72:73]
	v_lshlrev_b32_e32 v72, 16, v186
	v_and_b32_e32 v73, 0xffff0000, v186
	v_pk_mul_f32 v[72:73], v[64:65], v[72:73]
	v_lshlrev_b32_e32 v64, 16, v187
	v_and_b32_e32 v65, 0xffff0000, v187
	v_pk_mul_f32 v[74:75], v[66:67], v[64:65]
	v_cvt_pk_bf16_f32 v64, v68, v69
	v_cvt_pk_bf16_f32 v65, v70, v71
	v_cvt_pk_bf16_f32 v66, v72, v73
	v_cvt_pk_bf16_f32 v67, v74, v75
	global_store_dwordx4 v[76:77], v[64:67], off offset:256
	s_nop 1
	v_lshlrev_b64 v[64:65], 12, v[96:97]
	v_lshl_add_u64 v[64:65], s[42:43], 0, v[64:65]
	v_lshl_add_u64 v[64:65], v[64:65], 0, v[140:141]
	v_lshlrev_b64 v[64:65], 12, v[98:99]
	v_lshl_add_u64 v[64:65], s[42:43], 0, v[64:65]
	v_lshl_add_u64 v[64:65], v[64:65], 0, v[140:141]
	v_lshlrev_b64 v[64:65], 12, v[100:101]
	v_lshl_add_u64 v[64:65], s[42:43], 0, v[64:65]
	v_lshl_add_u64 v[64:65], v[64:65], 0, v[140:141]
	v_lshlrev_b64 v[64:65], 12, v[102:103]
	v_lshl_add_u64 v[64:65], s[42:43], 0, v[64:65]
	v_lshl_add_u64 v[64:65], v[64:65], 0, v[140:141]
	s_nop 0
	v_lshlrev_b64 v[96:97], 11, v[96:97]
	s_waitcnt vmcnt(8)
	v_lshlrev_b32_e32 v104, 16, v200
	v_and_b32_e32 v105, 0xffff0000, v200
	v_lshlrev_b32_e32 v68, 16, v201
	v_and_b32_e32 v69, 0xffff0000, v201
	v_pk_mul_f32 v[62:63], v[62:63], v[68:69]
	v_lshlrev_b32_e32 v68, 16, v202
	v_and_b32_e32 v69, 0xffff0000, v202
	v_pk_mul_f32 v[60:61], v[60:61], v[104:105]
	v_pk_mul_f32 v[68:69], v[56:57], v[68:69]
	v_lshlrev_b32_e32 v56, 16, v203
	v_and_b32_e32 v57, 0xffff0000, v203
	v_pk_mul_f32 v[70:71], v[58:59], v[56:57]
	v_cvt_pk_bf16_f32 v56, v60, v61
	v_lshl_add_u64 v[60:61], s[82:83], 0, v[96:97]
	v_cvt_pk_bf16_f32 v57, v62, v63
	v_cvt_pk_bf16_f32 v58, v68, v69
	v_cvt_pk_bf16_f32 v59, v70, v71
	v_lshl_add_u64 v[60:61], v[60:61], 0, v[140:141]
	global_store_dwordx4 v[60:61], v[56:59], off
	s_nop 1
	v_lshlrev_b32_e32 v56, 16, v204
	v_and_b32_e32 v57, 0xffff0000, v204
	v_pk_mul_f32 v[52:53], v[52:53], v[56:57]
	v_lshlrev_b32_e32 v56, 16, v205
	v_and_b32_e32 v57, 0xffff0000, v205
	v_pk_mul_f32 v[54:55], v[54:55], v[56:57]
	v_lshlrev_b32_e32 v56, 16, v206
	v_and_b32_e32 v57, 0xffff0000, v206
	v_pk_mul_f32 v[56:57], v[44:45], v[56:57]
	v_lshlrev_b32_e32 v44, 16, v207
	v_and_b32_e32 v45, 0xffff0000, v207
	v_pk_mul_f32 v[58:59], v[46:47], v[44:45]
	v_cvt_pk_bf16_f32 v44, v52, v53
	v_cvt_pk_bf16_f32 v45, v54, v55
	v_cvt_pk_bf16_f32 v46, v56, v57
	v_cvt_pk_bf16_f32 v47, v58, v59
	global_store_dwordx4 v[60:61], v[44:47], off offset:256
	s_nop 1
	v_lshlrev_b32_e32 v46, 16, v208
	v_and_b32_e32 v47, 0xffff0000, v208
	v_pk_mul_f32 v[46:47], v[48:49], v[46:47]
	v_lshlrev_b32_e32 v48, 16, v209
	v_and_b32_e32 v49, 0xffff0000, v209
	v_pk_mul_f32 v[48:49], v[50:51], v[48:49]
	v_lshlrev_b32_e32 v50, 16, v210
	v_and_b32_e32 v51, 0xffff0000, v210
	v_lshlrev_b64 v[44:45], 11, v[98:99]
	v_pk_mul_f32 v[50:51], v[40:41], v[50:51]
	v_lshlrev_b32_e32 v40, 16, v211
	v_and_b32_e32 v41, 0xffff0000, v211
	v_pk_mul_f32 v[52:53], v[42:43], v[40:41]
	v_lshl_add_u64 v[44:45], s[82:83], 0, v[44:45]
	v_cvt_pk_bf16_f32 v40, v46, v47
	v_cvt_pk_bf16_f32 v41, v48, v49
	v_cvt_pk_bf16_f32 v42, v50, v51
	v_cvt_pk_bf16_f32 v43, v52, v53
	v_lshl_add_u64 v[44:45], v[44:45], 0, v[140:141]
	global_store_dwordx4 v[44:45], v[40:43], off
	s_nop 1
	v_lshlrev_b32_e32 v40, 16, v212
	v_and_b32_e32 v41, 0xffff0000, v212
	v_pk_mul_f32 v[36:37], v[36:37], v[40:41]
	v_lshlrev_b32_e32 v40, 16, v213
	v_and_b32_e32 v41, 0xffff0000, v213
	v_pk_mul_f32 v[38:39], v[38:39], v[40:41]
	v_lshlrev_b32_e32 v40, 16, v214
	v_and_b32_e32 v41, 0xffff0000, v214
	v_pk_mul_f32 v[40:41], v[28:29], v[40:41]
	v_lshlrev_b32_e32 v28, 16, v215
	v_and_b32_e32 v29, 0xffff0000, v215
	v_pk_mul_f32 v[42:43], v[30:31], v[28:29]
	v_cvt_pk_bf16_f32 v28, v36, v37
	v_cvt_pk_bf16_f32 v29, v38, v39
	v_cvt_pk_bf16_f32 v30, v40, v41
	v_cvt_pk_bf16_f32 v31, v42, v43
	global_store_dwordx4 v[44:45], v[28:31], off offset:256
	s_nop 1
	v_lshlrev_b32_e32 v30, 16, v216
	v_and_b32_e32 v31, 0xffff0000, v216
	v_pk_mul_f32 v[30:31], v[32:33], v[30:31]
	v_lshlrev_b32_e32 v32, 16, v217
	v_and_b32_e32 v33, 0xffff0000, v217
	v_pk_mul_f32 v[32:33], v[34:35], v[32:33]
	v_lshlrev_b32_e32 v34, 16, v218
	v_and_b32_e32 v35, 0xffff0000, v218
	v_lshlrev_b64 v[28:29], 11, v[100:101]
	v_pk_mul_f32 v[34:35], v[24:25], v[34:35]
	v_lshlrev_b32_e32 v24, 16, v219
	v_and_b32_e32 v25, 0xffff0000, v219
	v_pk_mul_f32 v[36:37], v[26:27], v[24:25]
	v_lshl_add_u64 v[28:29], s[82:83], 0, v[28:29]
	v_cvt_pk_bf16_f32 v24, v30, v31
	v_cvt_pk_bf16_f32 v25, v32, v33
	v_cvt_pk_bf16_f32 v26, v34, v35
	v_cvt_pk_bf16_f32 v27, v36, v37
	v_lshl_add_u64 v[28:29], v[28:29], 0, v[140:141]
	global_store_dwordx4 v[28:29], v[24:27], off
	s_nop 1
	v_lshlrev_b32_e32 v24, 16, v222
	v_and_b32_e32 v25, 0xffff0000, v222
	v_pk_mul_f32 v[20:21], v[20:21], v[24:25]
	v_lshlrev_b32_e32 v24, 16, v223
	v_and_b32_e32 v25, 0xffff0000, v223
	v_pk_mul_f32 v[22:23], v[22:23], v[24:25]
	v_lshlrev_b32_e32 v24, 16, v224
	v_and_b32_e32 v25, 0xffff0000, v224
	v_pk_mul_f32 v[24:25], v[12:13], v[24:25]
	v_lshlrev_b32_e32 v12, 16, v225
	v_and_b32_e32 v13, 0xffff0000, v225
	v_pk_mul_f32 v[26:27], v[14:15], v[12:13]
	v_cvt_pk_bf16_f32 v12, v20, v21
	v_cvt_pk_bf16_f32 v13, v22, v23
	v_cvt_pk_bf16_f32 v14, v24, v25
	v_cvt_pk_bf16_f32 v15, v26, v27
	global_store_dwordx4 v[28:29], v[12:15], off offset:256
	s_nop 1
	v_lshlrev_b32_e32 v14, 16, v226
	v_and_b32_e32 v15, 0xffff0000, v226
	v_pk_mul_f32 v[14:15], v[16:17], v[14:15]
	v_lshlrev_b32_e32 v16, 16, v227
	v_and_b32_e32 v17, 0xffff0000, v227
	v_pk_mul_f32 v[16:17], v[18:19], v[16:17]
	v_lshlrev_b32_e32 v18, 16, v228
	v_and_b32_e32 v19, 0xffff0000, v228
	v_lshlrev_b64 v[12:13], 11, v[102:103]
	v_pk_mul_f32 v[18:19], v[8:9], v[18:19]
	v_lshlrev_b32_e32 v8, 16, v229
	v_and_b32_e32 v9, 0xffff0000, v229
	v_pk_mul_f32 v[20:21], v[10:11], v[8:9]
	v_lshl_add_u64 v[12:13], s[82:83], 0, v[12:13]
	v_cvt_pk_bf16_f32 v8, v14, v15
	v_cvt_pk_bf16_f32 v9, v16, v17
	v_cvt_pk_bf16_f32 v10, v18, v19
	v_cvt_pk_bf16_f32 v11, v20, v21
	v_lshl_add_u64 v[12:13], v[12:13], 0, v[140:141]
	global_store_dwordx4 v[12:13], v[8:11], off
	s_nop 1
	v_lshlrev_b32_e32 v8, 16, v230
	v_and_b32_e32 v9, 0xffff0000, v230
	v_pk_mul_f32 v[4:5], v[4:5], v[8:9]
	v_lshlrev_b32_e32 v8, 16, v231
	v_and_b32_e32 v9, 0xffff0000, v231
	v_pk_mul_f32 v[6:7], v[6:7], v[8:9]
	v_lshlrev_b32_e32 v8, 16, v232
	v_and_b32_e32 v9, 0xffff0000, v232
	v_pk_mul_f32 v[8:9], v[0:1], v[8:9]
	v_lshlrev_b32_e32 v0, 16, v233
	v_and_b32_e32 v1, 0xffff0000, v233
	v_pk_mul_f32 v[10:11], v[2:3], v[0:1]
	v_cvt_pk_bf16_f32 v0, v4, v5
	v_cvt_pk_bf16_f32 v1, v6, v7
	v_cvt_pk_bf16_f32 v2, v8, v9
	v_cvt_pk_bf16_f32 v3, v10, v11
	global_store_dwordx4 v[12:13], v[0:3], off offset:256
	s_cbranch_vccz .LBB0_1260
	s_waitcnt vmcnt(0)
	s_cmpk_gt_u32 s26, 0xff
	s_cbranch_scc1 .LBB0_1272
	s_barrier

.LBB0_1285:
	ds_read_b128 v[144:147], v176
	ds_read_b128 v[148:151], v176 offset:1024
	ds_read_b128 v[164:167], v176 offset:2048
	ds_read_b128 v[168:171], v176 offset:3072
	ds_read_b128 v[180:183], v176 offset:4096
	ds_read_b128 v[184:187], v176 offset:5120
	ds_read_b128 v[188:191], v176 offset:6144
	ds_read_b128 v[192:195], v176 offset:7168
	ds_read_b128 v[128:131], v175
	ds_read_b128 v[132:135], v175 offset:1024
	ds_read_b128 v[136:139], v175 offset:2048
	ds_read_b128 v[140:143], v175 offset:3072
	s_add_u32 s22, s10, 0xfffe0080
	s_addc_u32 s23, s11, -1
	s_cmp_eq_u32 s43, 4
	s_cselect_b32 s25, s13, s23
	s_cselect_b32 s24, s39, s22
	s_cselect_b32 s23, s15, s42
	s_cselect_b32 s22, s40, s41
	v_lshl_add_u64 v[196:197], s[10:11], 0, v[160:161]
	s_add_i32 m0, s1, 0xc000
	global_load_lds_dwordx4 v[196:197], off
	v_lshl_add_u64 v[196:197], s[10:11], 0, v[162:163]
	s_add_i32 m0, s1, 0xe000
	s_nop 0
	global_load_lds_dwordx4 v[196:197], off
	s_waitcnt lgkmcnt(0)
	s_barrier
	s_waitcnt lgkmcnt(0)
	v_mfma_f32_16x16x32_bf16 v[124:127], v[128:131], v[144:147], v[124:127]
	v_mfma_f32_16x16x32_bf16 v[120:123], v[136:139], v[144:147], v[120:123]
	v_mfma_f32_16x16x32_bf16 v[108:111], v[128:131], v[164:167], v[108:111]
	v_mfma_f32_16x16x32_bf16 v[104:107], v[136:139], v[164:167], v[104:107]
	v_mfma_f32_16x16x32_bf16 v[92:95], v[128:131], v[180:183], v[92:95]
	v_mfma_f32_16x16x32_bf16 v[88:91], v[136:139], v[180:183], v[88:91]
	v_mfma_f32_16x16x32_bf16 v[76:79], v[128:131], v[188:191], v[76:79]
	v_mfma_f32_16x16x32_bf16 v[72:75], v[136:139], v[188:191], v[72:75]
	v_mfma_f32_16x16x32_bf16 v[124:127], v[132:135], v[148:151], v[124:127]
	v_mfma_f32_16x16x32_bf16 v[120:123], v[140:143], v[148:151], v[120:123]
	v_mfma_f32_16x16x32_bf16 v[108:111], v[132:135], v[168:171], v[108:111]
	v_mfma_f32_16x16x32_bf16 v[104:107], v[140:143], v[168:171], v[104:107]
	v_mfma_f32_16x16x32_bf16 v[92:95], v[132:135], v[184:187], v[92:95]
	v_mfma_f32_16x16x32_bf16 v[88:91], v[140:143], v[184:187], v[88:91]
	v_mfma_f32_16x16x32_bf16 v[76:79], v[132:135], v[192:195], v[76:79]
	v_mfma_f32_16x16x32_bf16 v[72:75], v[140:143], v[192:195], v[72:75]
	s_barrier
	s_add_i32 s44, s35, s27
	v_lshl_add_u64 v[212:213], s[22:23], 0, v[156:157]
	s_mov_b32 m0, s44
	ds_read_b128 v[196:199], v177
	ds_read_b128 v[200:203], v177 offset:1024
	ds_read_b128 v[204:207], v177 offset:2048
	ds_read_b128 v[208:211], v177 offset:3072
	global_load_lds_dwordx4 v[212:213], off
	v_lshl_add_u64 v[214:215], s[22:23], 0, v[152:153]
	s_add_i32 m0, s44, 0x2000
	s_nop 0
	global_load_lds_dwordx4 v[214:215], off
	s_barrier
	s_waitcnt lgkmcnt(0)
	v_mfma_f32_16x16x32_bf16 v[116:119], v[196:199], v[144:147], v[116:119]
	v_mfma_f32_16x16x32_bf16 v[112:115], v[204:207], v[144:147], v[112:115]
	v_mfma_f32_16x16x32_bf16 v[100:103], v[196:199], v[164:167], v[100:103]
	v_mfma_f32_16x16x32_bf16 v[96:99], v[204:207], v[164:167], v[96:99]
	v_mfma_f32_16x16x32_bf16 v[84:87], v[196:199], v[180:183], v[84:87]
	v_mfma_f32_16x16x32_bf16 v[80:83], v[204:207], v[180:183], v[80:83]
	v_mfma_f32_16x16x32_bf16 v[68:71], v[196:199], v[188:191], v[68:71]
	v_mfma_f32_16x16x32_bf16 v[64:67], v[204:207], v[188:191], v[64:67]
	v_mfma_f32_16x16x32_bf16 v[116:119], v[200:203], v[148:151], v[116:119]
	v_mfma_f32_16x16x32_bf16 v[112:115], v[208:211], v[148:151], v[112:115]
	v_mfma_f32_16x16x32_bf16 v[100:103], v[200:203], v[168:171], v[100:103]
	v_mfma_f32_16x16x32_bf16 v[96:99], v[208:211], v[168:171], v[96:99]
	v_mfma_f32_16x16x32_bf16 v[84:87], v[200:203], v[184:187], v[84:87]
	v_mfma_f32_16x16x32_bf16 v[80:83], v[208:211], v[184:187], v[80:83]
	v_mfma_f32_16x16x32_bf16 v[68:71], v[200:203], v[192:195], v[68:71]
	v_mfma_f32_16x16x32_bf16 v[64:67], v[208:211], v[192:195], v[64:67]
	s_mov_b32 m0, s1
	v_lshl_add_u64 v[216:217], s[24:25], 0, v[158:159]
	s_barrier
	ds_read_b128 v[144:147], v176 offset:16384
	ds_read_b128 v[148:151], v176 offset:17408
	ds_read_b128 v[164:167], v176 offset:18432
	ds_read_b128 v[168:171], v176 offset:19456
	ds_read_b128 v[180:183], v176 offset:20480
	ds_read_b128 v[184:187], v176 offset:21504
	ds_read_b128 v[188:191], v176 offset:22528
	ds_read_b128 v[192:195], v176 offset:23552
	global_load_lds_dwordx4 v[216:217], off
	v_lshl_add_u64 v[218:219], s[24:25], 0, v[154:155]
	s_mov_b32 m0, s7
	s_nop 0
	global_load_lds_dwordx4 v[218:219], off
	s_barrier
	s_waitcnt lgkmcnt(0)
	v_mfma_f32_16x16x32_bf16 v[60:63], v[128:131], v[144:147], v[60:63]
	v_mfma_f32_16x16x32_bf16 v[56:59], v[136:139], v[144:147], v[56:59]
	v_mfma_f32_16x16x32_bf16 v[44:47], v[128:131], v[164:167], v[44:47]
	v_mfma_f32_16x16x32_bf16 v[40:43], v[136:139], v[164:167], v[40:43]
	v_mfma_f32_16x16x32_bf16 v[28:31], v[128:131], v[180:183], v[28:31]
	v_mfma_f32_16x16x32_bf16 v[24:27], v[136:139], v[180:183], v[24:27]
	v_mfma_f32_16x16x32_bf16 v[12:15], v[128:131], v[188:191], v[12:15]
	v_mfma_f32_16x16x32_bf16 v[8:11], v[136:139], v[188:191], v[8:11]
	v_mfma_f32_16x16x32_bf16 v[60:63], v[132:135], v[148:151], v[60:63]
	v_mfma_f32_16x16x32_bf16 v[56:59], v[140:143], v[148:151], v[56:59]
	v_mfma_f32_16x16x32_bf16 v[44:47], v[132:135], v[168:171], v[44:47]
	v_mfma_f32_16x16x32_bf16 v[40:43], v[140:143], v[168:171], v[40:43]
	v_mfma_f32_16x16x32_bf16 v[28:31], v[132:135], v[184:187], v[28:31]
	v_mfma_f32_16x16x32_bf16 v[24:27], v[140:143], v[184:187], v[24:27]
	v_mfma_f32_16x16x32_bf16 v[12:15], v[132:135], v[192:195], v[12:15]
	v_mfma_f32_16x16x32_bf16 v[8:11], v[140:143], v[192:195], v[8:11]
	s_barrier
	s_add_u32 s44, s22, 0x20000
	s_addc_u32 s45, s23, 0
	s_add_i32 s46, s36, s27
	v_lshl_add_u64 v[128:129], s[44:45], 0, v[156:157]
	s_mov_b32 m0, s46
	s_nop 0
	global_load_lds_dwordx4 v[128:129], off
	v_lshl_add_u64 v[128:129], s[44:45], 0, v[152:153]
	s_add_i32 m0, s46, 0x2000
	s_nop 0
	global_load_lds_dwordx4 v[128:129], off
	s_waitcnt vmcnt(6)
	s_barrier
	v_mfma_f32_16x16x32_bf16 v[52:55], v[196:199], v[144:147], v[52:55]
	v_mfma_f32_16x16x32_bf16 v[48:51], v[204:207], v[144:147], v[48:51]
	v_mfma_f32_16x16x32_bf16 v[36:39], v[196:199], v[164:167], v[36:39]
	v_mfma_f32_16x16x32_bf16 v[32:35], v[204:207], v[164:167], v[32:35]
	v_mfma_f32_16x16x32_bf16 v[20:23], v[196:199], v[180:183], v[20:23]
	v_mfma_f32_16x16x32_bf16 v[16:19], v[204:207], v[180:183], v[16:19]
	v_mfma_f32_16x16x32_bf16 v[4:7], v[196:199], v[188:191], v[4:7]
	v_mfma_f32_16x16x32_bf16 v[0:3], v[204:207], v[188:191], v[0:3]
	v_mfma_f32_16x16x32_bf16 v[52:55], v[200:203], v[148:151], v[52:55]
	v_mfma_f32_16x16x32_bf16 v[48:51], v[208:211], v[148:151], v[48:51]
	v_mfma_f32_16x16x32_bf16 v[36:39], v[200:203], v[168:171], v[36:39]
	v_mfma_f32_16x16x32_bf16 v[32:35], v[208:211], v[168:171], v[32:35]
	v_mfma_f32_16x16x32_bf16 v[20:23], v[200:203], v[184:187], v[20:23]
	v_mfma_f32_16x16x32_bf16 v[16:19], v[208:211], v[184:187], v[16:19]
	v_mfma_f32_16x16x32_bf16 v[4:7], v[200:203], v[192:195], v[4:7]
	v_mfma_f32_16x16x32_bf16 v[0:3], v[208:211], v[192:195], v[0:3]
	s_add_i32 s44, 0, 0x18000
	v_add_u32_e32 v140, s44, v173
	s_barrier
	ds_read_b128 v[144:147], v176 offset:32768
	ds_read_b128 v[148:151], v176 offset:33792
	ds_read_b128 v[164:167], v176 offset:34816
	ds_read_b128 v[168:171], v176 offset:35840
	ds_read_b128 v[180:183], v176 offset:36864
	ds_read_b128 v[184:187], v176 offset:37888
	ds_read_b128 v[188:191], v176 offset:38912
	ds_read_b128 v[192:195], v176 offset:39936
	ds_read_b128 v[128:131], v140
	ds_read_b128 v[132:135], v140 offset:1024
	ds_read_b128 v[136:139], v140 offset:2048
	ds_read_b128 v[140:143], v140 offset:3072
	s_add_u32 s24, s24, 0x20000
	s_addc_u32 s25, s25, 0
	s_mov_b32 m0, s28
	v_lshl_add_u64 v[196:197], s[24:25], 0, v[158:159]
	global_load_lds_dwordx4 v[196:197], off
	v_lshl_add_u64 v[196:197], s[24:25], 0, v[154:155]
	s_mov_b32 m0, s29
	s_nop 0
	global_load_lds_dwordx4 v[196:197], off
	s_waitcnt lgkmcnt(0)
	s_barrier
	s_waitcnt lgkmcnt(0)
	v_mfma_f32_16x16x32_bf16 v[124:127], v[128:131], v[144:147], v[124:127]
	v_mfma_f32_16x16x32_bf16 v[120:123], v[136:139], v[144:147], v[120:123]
	v_mfma_f32_16x16x32_bf16 v[108:111], v[128:131], v[164:167], v[108:111]
	v_mfma_f32_16x16x32_bf16 v[104:107], v[136:139], v[164:167], v[104:107]
	v_mfma_f32_16x16x32_bf16 v[92:95], v[128:131], v[180:183], v[92:95]
	v_mfma_f32_16x16x32_bf16 v[88:91], v[136:139], v[180:183], v[88:91]
	v_mfma_f32_16x16x32_bf16 v[76:79], v[128:131], v[188:191], v[76:79]
	v_mfma_f32_16x16x32_bf16 v[72:75], v[136:139], v[188:191], v[72:75]
	v_mfma_f32_16x16x32_bf16 v[124:127], v[132:135], v[148:151], v[124:127]
	v_mfma_f32_16x16x32_bf16 v[120:123], v[140:143], v[148:151], v[120:123]
	v_mfma_f32_16x16x32_bf16 v[108:111], v[132:135], v[168:171], v[108:111]
	v_mfma_f32_16x16x32_bf16 v[104:107], v[140:143], v[168:171], v[104:107]
	v_mfma_f32_16x16x32_bf16 v[92:95], v[132:135], v[184:187], v[92:95]
	v_mfma_f32_16x16x32_bf16 v[88:91], v[140:143], v[184:187], v[88:91]
	v_mfma_f32_16x16x32_bf16 v[76:79], v[132:135], v[192:195], v[76:79]
	v_mfma_f32_16x16x32_bf16 v[72:75], v[140:143], v[192:195], v[72:75]
	s_barrier
	s_add_i32 s24, 0, 0x1c000
	s_add_i32 s25, s44, s27
	v_add_u32_e32 v179, s24, v173
	v_lshl_add_u64 v[212:213], v[212:213], 0, s[4:5]
	s_mov_b32 m0, s25
	ds_read_b128 v[196:199], v179
	ds_read_b128 v[200:203], v179 offset:1024
	ds_read_b128 v[204:207], v179 offset:2048
	ds_read_b128 v[208:211], v179 offset:3072
	global_load_lds_dwordx4 v[212:213], off
	v_lshl_add_u64 v[212:213], v[214:215], 0, s[4:5]
	s_add_i32 m0, s25, 0x2000
	s_nop 0
	global_load_lds_dwordx4 v[212:213], off
	s_barrier
	s_waitcnt lgkmcnt(0)
	v_mfma_f32_16x16x32_bf16 v[116:119], v[196:199], v[144:147], v[116:119]
	v_mfma_f32_16x16x32_bf16 v[112:115], v[204:207], v[144:147], v[112:115]
	v_mfma_f32_16x16x32_bf16 v[100:103], v[196:199], v[164:167], v[100:103]
	v_mfma_f32_16x16x32_bf16 v[96:99], v[204:207], v[164:167], v[96:99]
	v_mfma_f32_16x16x32_bf16 v[84:87], v[196:199], v[180:183], v[84:87]
	v_mfma_f32_16x16x32_bf16 v[80:83], v[204:207], v[180:183], v[80:83]
	v_mfma_f32_16x16x32_bf16 v[68:71], v[196:199], v[188:191], v[68:71]
	v_mfma_f32_16x16x32_bf16 v[64:67], v[204:207], v[188:191], v[64:67]
	v_mfma_f32_16x16x32_bf16 v[116:119], v[200:203], v[148:151], v[116:119]
	v_mfma_f32_16x16x32_bf16 v[112:115], v[208:211], v[148:151], v[112:115]
	v_mfma_f32_16x16x32_bf16 v[100:103], v[200:203], v[168:171], v[100:103]
	v_mfma_f32_16x16x32_bf16 v[96:99], v[208:211], v[168:171], v[96:99]
	v_mfma_f32_16x16x32_bf16 v[84:87], v[200:203], v[184:187], v[84:87]
	v_mfma_f32_16x16x32_bf16 v[80:83], v[208:211], v[184:187], v[80:83]
	v_mfma_f32_16x16x32_bf16 v[68:71], v[200:203], v[192:195], v[68:71]
	v_mfma_f32_16x16x32_bf16 v[64:67], v[208:211], v[192:195], v[64:67]
	s_mov_b32 m0, s31
	v_lshl_add_u64 v[212:213], v[216:217], 0, s[4:5]
	s_barrier
	ds_read_b128 v[144:147], v176 offset:49152
	ds_read_b128 v[148:151], v176 offset:50176
	ds_read_b128 v[164:167], v176 offset:51200
	ds_read_b128 v[168:171], v176 offset:52224
	ds_read_b128 v[180:183], v176 offset:53248
	ds_read_b128 v[184:187], v176 offset:54272
	ds_read_b128 v[188:191], v176 offset:55296
	ds_read_b128 v[192:195], v176 offset:56320
	global_load_lds_dwordx4 v[212:213], off
	v_lshl_add_u64 v[212:213], v[218:219], 0, s[4:5]
	s_mov_b32 m0, s33
	s_nop 0
	global_load_lds_dwordx4 v[212:213], off
	s_barrier
	s_waitcnt lgkmcnt(0)
	v_mfma_f32_16x16x32_bf16 v[60:63], v[128:131], v[144:147], v[60:63]
	v_mfma_f32_16x16x32_bf16 v[56:59], v[136:139], v[144:147], v[56:59]
	v_mfma_f32_16x16x32_bf16 v[44:47], v[128:131], v[164:167], v[44:47]
	v_mfma_f32_16x16x32_bf16 v[40:43], v[136:139], v[164:167], v[40:43]
	v_mfma_f32_16x16x32_bf16 v[28:31], v[128:131], v[180:183], v[28:31]
	v_mfma_f32_16x16x32_bf16 v[24:27], v[136:139], v[180:183], v[24:27]
	v_mfma_f32_16x16x32_bf16 v[12:15], v[128:131], v[188:191], v[12:15]
	v_mfma_f32_16x16x32_bf16 v[8:11], v[136:139], v[188:191], v[8:11]
	v_mfma_f32_16x16x32_bf16 v[60:63], v[132:135], v[148:151], v[60:63]
	v_mfma_f32_16x16x32_bf16 v[56:59], v[140:143], v[148:151], v[56:59]
	v_mfma_f32_16x16x32_bf16 v[44:47], v[132:135], v[168:171], v[44:47]
	v_mfma_f32_16x16x32_bf16 v[40:43], v[140:143], v[168:171], v[40:43]
	v_mfma_f32_16x16x32_bf16 v[28:31], v[132:135], v[184:187], v[28:31]
	v_mfma_f32_16x16x32_bf16 v[24:27], v[140:143], v[184:187], v[24:27]
	v_mfma_f32_16x16x32_bf16 v[12:15], v[132:135], v[192:195], v[12:15]
	v_mfma_f32_16x16x32_bf16 v[8:11], v[140:143], v[192:195], v[8:11]
	s_barrier
	s_add_u32 s22, s22, 0x20080
	s_addc_u32 s23, s23, 0
	s_add_i32 s24, s24, s27
	v_lshl_add_u64 v[128:129], s[22:23], 0, v[156:157]
	s_mov_b32 m0, s24
	s_nop 0
	global_load_lds_dwordx4 v[128:129], off
	v_lshl_add_u64 v[128:129], s[22:23], 0, v[152:153]
	s_add_i32 m0, s24, 0x2000
	s_nop 0
	global_load_lds_dwordx4 v[128:129], off
	s_waitcnt vmcnt(6)
	s_barrier
	v_mfma_f32_16x16x32_bf16 v[52:55], v[196:199], v[144:147], v[52:55]
	v_mfma_f32_16x16x32_bf16 v[48:51], v[204:207], v[144:147], v[48:51]
	v_mfma_f32_16x16x32_bf16 v[36:39], v[196:199], v[164:167], v[36:39]
	v_mfma_f32_16x16x32_bf16 v[32:35], v[204:207], v[164:167], v[32:35]
	v_mfma_f32_16x16x32_bf16 v[20:23], v[196:199], v[180:183], v[20:23]
	v_mfma_f32_16x16x32_bf16 v[16:19], v[204:207], v[180:183], v[16:19]
	v_mfma_f32_16x16x32_bf16 v[4:7], v[196:199], v[188:191], v[4:7]
	v_mfma_f32_16x16x32_bf16 v[0:3], v[204:207], v[188:191], v[0:3]
	v_mfma_f32_16x16x32_bf16 v[52:55], v[200:203], v[148:151], v[52:55]
	v_mfma_f32_16x16x32_bf16 v[48:51], v[208:211], v[148:151], v[48:51]
	v_mfma_f32_16x16x32_bf16 v[36:39], v[200:203], v[168:171], v[36:39]
	v_mfma_f32_16x16x32_bf16 v[32:35], v[208:211], v[168:171], v[32:35]
	v_mfma_f32_16x16x32_bf16 v[20:23], v[200:203], v[184:187], v[20:23]
	v_mfma_f32_16x16x32_bf16 v[16:19], v[208:211], v[184:187], v[16:19]
	v_mfma_f32_16x16x32_bf16 v[4:7], v[200:203], v[192:195], v[4:7]
	v_mfma_f32_16x16x32_bf16 v[0:3], v[208:211], v[192:195], v[0:3]
	s_add_i32 s43, s43, 2
	s_add_u32 s10, s10, 0x100
	s_addc_u32 s11, s11, 0
	s_add_u32 s41, s41, 0x100
	s_addc_u32 s42, s42, 0
	s_cmp_gt_u32 s43, 5
	s_barrier
	s_cbranch_scc0 .LBB0_1285
	v_lshl_add_u32 v164, s38, 8, v172
	s_nop 0
	v_lshl_or_b32 v128, s0, 8, v174
	v_ashrrev_i32_e32 v165, 31, v164
	s_nop 1
	v_readlane_b32 s46, v252, 13
	v_readlane_b32 s47, v252, 14
	v_ashrrev_i32_e32 v129, 31, v128
	v_lshlrev_b64 v[130:131], 12, v[164:165]
	s_mov_b64 s[42:43], s[46:47]
	v_lshl_add_u64 v[130:131], s[42:43], 0, v[130:131]
	v_lshlrev_b64 v[132:133], 11, v[164:165]
	v_lshlrev_b64 v[166:167], 1, v[128:129]
	v_lshl_add_u64 v[132:133], s[82:83], 0, v[132:133]
	v_lshl_add_u64 v[128:129], v[130:131], 0, v[166:167]
	global_load_dwordx4 v[180:183], v[128:129], off offset:2048
	v_lshl_add_u64 v[222:223], v[132:133], 0, v[166:167]
	global_load_dwordx4 v[184:187], v[222:223], off
	global_load_dwordx4 v[188:191], v[128:129], off offset:2304
	global_load_dwordx4 v[192:195], v[222:223], off offset:256
	v_or_b32_e32 v128, 16, v164
	v_ashrrev_i32_e32 v129, 31, v128
	v_lshlrev_b64 v[130:131], 12, v[128:129]
	v_lshlrev_b64 v[128:129], 11, v[128:129]
	v_lshl_add_u64 v[130:131], s[42:43], 0, v[130:131]
	v_lshl_add_u64 v[128:129], s[82:83], 0, v[128:129]
	v_lshl_add_u64 v[130:131], v[130:131], 0, v[166:167]
	v_lshl_add_u64 v[224:225], v[128:129], 0, v[166:167]
	global_load_dwordx4 v[196:199], v[130:131], off offset:2048
	global_load_dwordx4 v[200:203], v[224:225], off
	v_or_b32_e32 v128, 32, v164
	v_or_b32_e32 v132, 48, v164
	v_ashrrev_i32_e32 v129, 31, v128
	v_ashrrev_i32_e32 v133, 31, v132
	v_lshlrev_b64 v[134:135], 12, v[128:129]
	v_lshlrev_b64 v[128:129], 11, v[128:129]
	v_lshlrev_b64 v[136:137], 12, v[132:133]
	v_lshlrev_b64 v[132:133], 11, v[132:133]
	v_lshl_add_u64 v[134:135], s[42:43], 0, v[134:135]
	v_lshl_add_u64 v[128:129], s[82:83], 0, v[128:129]
	v_lshl_add_u64 v[136:137], s[42:43], 0, v[136:137]
	v_lshl_add_u64 v[132:133], s[82:83], 0, v[132:133]
	v_lshl_add_u64 v[134:135], v[134:135], 0, v[166:167]
	v_lshl_add_u64 v[170:171], v[128:129], 0, v[166:167]
	v_lshl_add_u64 v[128:129], v[136:137], 0, v[166:167]
	v_lshl_add_u64 v[168:169], v[132:133], 0, v[166:167]
	global_load_dwordx4 v[204:207], v[130:131], off offset:2304
	global_load_dwordx4 v[208:211], v[224:225], off offset:256
	global_load_dwordx4 v[212:215], v[134:135], off offset:2048
	global_load_dwordx4 v[148:151], v[134:135], off offset:2304
	global_load_dwordx4 v[216:219], v[170:171], off
	global_load_dwordx4 v[144:147], v[170:171], off offset:256
	global_load_dwordx4 v[140:143], v[128:129], off offset:2048
	s_nop 0
	global_load_dwordx4 v[132:135], v[128:129], off offset:2304
	global_load_dwordx4 v[136:139], v[168:169], off
	s_nop 0
	global_load_dwordx4 v[128:131], v[168:169], off offset:256
	s_and_b64 vcc, exec, s[18:19]
	s_mov_b32 s0, s14
	s_mov_b32 s38, s12
	s_mov_b32 s15, s14
	s_mov_b32 s18, s12
	s_mov_b64 s[22:23], s[20:21]
	s_mov_b64 s[10:11], s[16:17]
	s_mov_b32 s13, s37
	s_nop 7
	s_nop 2
	s_waitcnt vmcnt(0)
	v_lshlrev_b32_e32 v228, 16, v184
	v_lshlrev_b32_e32 v226, 16, v180
	v_and_b32_e32 v227, 0xffff0000, v180
	v_and_b32_e32 v229, 0xffff0000, v184
	v_lshlrev_b32_e32 v180, 16, v181
	v_and_b32_e32 v181, 0xffff0000, v181
	v_lshlrev_b32_e32 v184, 16, v185
	v_and_b32_e32 v185, 0xffff0000, v185
	v_lshlrev_b32_e32 v230, 16, v182
	v_and_b32_e32 v231, 0xffff0000, v182
	v_lshlrev_b32_e32 v232, 16, v186
	v_and_b32_e32 v233, 0xffff0000, v186
	v_lshlrev_b32_e32 v182, 16, v183
	v_and_b32_e32 v183, 0xffff0000, v183
	v_lshlrev_b32_e32 v186, 16, v187
	v_and_b32_e32 v187, 0xffff0000, v187
	v_lshlrev_b32_e32 v234, 16, v188
	v_and_b32_e32 v235, 0xffff0000, v188
	v_lshlrev_b32_e32 v236, 16, v192
	v_and_b32_e32 v237, 0xffff0000, v192
	v_lshlrev_b32_e32 v188, 16, v189
	v_and_b32_e32 v189, 0xffff0000, v189
	v_lshlrev_b32_e32 v192, 16, v193
	v_and_b32_e32 v193, 0xffff0000, v193
	v_pk_fma_f32 v[124:125], v[124:125], v[226:227], v[228:229]
	v_pk_fma_f32 v[126:127], v[126:127], v[180:181], v[184:185]
	v_pk_fma_f32 v[120:121], v[120:121], v[230:231], v[232:233]
	v_pk_fma_f32 v[122:123], v[122:123], v[182:183], v[186:187]
	v_lshlrev_b32_e32 v238, 16, v190
	v_and_b32_e32 v239, 0xffff0000, v190
	v_lshlrev_b32_e32 v240, 16, v194
	v_pk_fma_f32 v[180:181], v[116:117], v[234:235], v[236:237]
	v_pk_fma_f32 v[182:183], v[118:119], v[188:189], v[192:193]
	v_cvt_pk_bf16_f32 v116, v124, v125
	v_cvt_pk_bf16_f32 v117, v126, v127
	v_cvt_pk_bf16_f32 v118, v120, v121
	v_cvt_pk_bf16_f32 v119, v122, v123
	v_and_b32_e32 v241, 0xffff0000, v194
	global_store_dwordx4 v[222:223], v[116:119], off
	s_nop 1
	v_pk_fma_f32 v[116:117], v[112:113], v[238:239], v[240:241]
	v_lshlrev_b32_e32 v112, 16, v191
	v_and_b32_e32 v113, 0xffff0000, v191
	v_lshlrev_b32_e32 v118, 16, v195
	v_and_b32_e32 v119, 0xffff0000, v195
	v_pk_fma_f32 v[118:119], v[114:115], v[112:113], v[118:119]
	v_cvt_pk_bf16_f32 v112, v180, v181
	v_cvt_pk_bf16_f32 v113, v182, v183
	v_cvt_pk_bf16_f32 v114, v116, v117
	v_cvt_pk_bf16_f32 v115, v118, v119
	global_store_dwordx4 v[222:223], v[112:115], off offset:256
	s_nop 1
	v_lshlrev_b32_e32 v112, 16, v196
	v_and_b32_e32 v113, 0xffff0000, v196
	v_lshlrev_b32_e32 v114, 16, v200
	v_and_b32_e32 v115, 0xffff0000, v200
	v_pk_fma_f32 v[108:109], v[108:109], v[112:113], v[114:115]
	v_lshlrev_b32_e32 v112, 16, v197
	v_and_b32_e32 v113, 0xffff0000, v197
	v_lshlrev_b32_e32 v114, 16, v201
	v_and_b32_e32 v115, 0xffff0000, v201
	v_pk_fma_f32 v[110:111], v[110:111], v[112:113], v[114:115]
	v_lshlrev_b32_e32 v112, 16, v198
	v_and_b32_e32 v113, 0xffff0000, v198
	v_lshlrev_b32_e32 v114, 16, v202
	v_and_b32_e32 v115, 0xffff0000, v202
	v_pk_fma_f32 v[112:113], v[104:105], v[112:113], v[114:115]
	v_lshlrev_b32_e32 v104, 16, v199
	v_and_b32_e32 v105, 0xffff0000, v199
	v_lshlrev_b32_e32 v114, 16, v203
	v_and_b32_e32 v115, 0xffff0000, v203
	v_pk_fma_f32 v[114:115], v[106:107], v[104:105], v[114:115]
	v_cvt_pk_bf16_f32 v104, v108, v109
	v_cvt_pk_bf16_f32 v105, v110, v111
	v_cvt_pk_bf16_f32 v106, v112, v113
	v_cvt_pk_bf16_f32 v107, v114, v115
	global_store_dwordx4 v[224:225], v[104:107], off
	s_nop 1
	v_lshlrev_b32_e32 v104, 16, v204
	v_and_b32_e32 v105, 0xffff0000, v204
	v_lshlrev_b32_e32 v106, 16, v208
	v_and_b32_e32 v107, 0xffff0000, v208
	v_pk_fma_f32 v[100:101], v[100:101], v[104:105], v[106:107]
	v_lshlrev_b32_e32 v104, 16, v205
	v_and_b32_e32 v105, 0xffff0000, v205
	v_lshlrev_b32_e32 v106, 16, v209
	v_and_b32_e32 v107, 0xffff0000, v209
	v_pk_fma_f32 v[102:103], v[102:103], v[104:105], v[106:107]
	v_lshlrev_b32_e32 v104, 16, v206
	v_and_b32_e32 v105, 0xffff0000, v206
	v_lshlrev_b32_e32 v106, 16, v210
	v_and_b32_e32 v107, 0xffff0000, v210
	v_pk_fma_f32 v[104:105], v[96:97], v[104:105], v[106:107]
	v_lshlrev_b32_e32 v96, 16, v207
	v_and_b32_e32 v97, 0xffff0000, v207
	v_lshlrev_b32_e32 v106, 16, v211
	v_and_b32_e32 v107, 0xffff0000, v211
	v_pk_fma_f32 v[106:107], v[98:99], v[96:97], v[106:107]
	v_cvt_pk_bf16_f32 v96, v100, v101
	v_cvt_pk_bf16_f32 v97, v102, v103
	v_cvt_pk_bf16_f32 v98, v104, v105
	v_cvt_pk_bf16_f32 v99, v106, v107
	global_store_dwordx4 v[224:225], v[96:99], off offset:256
	s_nop 1
	v_lshlrev_b32_e32 v96, 16, v212
	v_and_b32_e32 v97, 0xffff0000, v212
	v_lshlrev_b32_e32 v98, 16, v216
	v_and_b32_e32 v99, 0xffff0000, v216
	v_pk_fma_f32 v[92:93], v[92:93], v[96:97], v[98:99]
	v_lshlrev_b32_e32 v96, 16, v213
	v_and_b32_e32 v97, 0xffff0000, v213
	v_lshlrev_b32_e32 v98, 16, v217
	v_and_b32_e32 v99, 0xffff0000, v217
	v_pk_fma_f32 v[94:95], v[94:95], v[96:97], v[98:99]
	v_lshlrev_b32_e32 v96, 16, v214
	v_and_b32_e32 v97, 0xffff0000, v214
	v_lshlrev_b32_e32 v98, 16, v218
	v_and_b32_e32 v99, 0xffff0000, v218
	v_pk_fma_f32 v[96:97], v[88:89], v[96:97], v[98:99]
	v_lshlrev_b32_e32 v88, 16, v215
	v_and_b32_e32 v89, 0xffff0000, v215
	v_lshlrev_b32_e32 v98, 16, v219
	v_and_b32_e32 v99, 0xffff0000, v219
	v_pk_fma_f32 v[98:99], v[90:91], v[88:89], v[98:99]
	v_cvt_pk_bf16_f32 v88, v92, v93
	v_cvt_pk_bf16_f32 v89, v94, v95
	v_cvt_pk_bf16_f32 v90, v96, v97
	v_cvt_pk_bf16_f32 v91, v98, v99
	global_store_dwordx4 v[170:171], v[88:91], off
	s_nop 1
	v_lshlrev_b32_e32 v88, 16, v148
	v_and_b32_e32 v89, 0xffff0000, v148
	v_lshlrev_b32_e32 v90, 16, v144
	v_and_b32_e32 v91, 0xffff0000, v144
	v_pk_fma_f32 v[84:85], v[84:85], v[88:89], v[90:91]
	v_lshlrev_b32_e32 v88, 16, v149
	v_and_b32_e32 v89, 0xffff0000, v149
	v_lshlrev_b32_e32 v90, 16, v145
	v_and_b32_e32 v91, 0xffff0000, v145
	v_pk_fma_f32 v[86:87], v[86:87], v[88:89], v[90:91]
	v_lshlrev_b32_e32 v88, 16, v150
	v_and_b32_e32 v89, 0xffff0000, v150
	v_lshlrev_b32_e32 v90, 16, v146
	v_and_b32_e32 v91, 0xffff0000, v146
	v_pk_fma_f32 v[88:89], v[80:81], v[88:89], v[90:91]
	v_lshlrev_b32_e32 v80, 16, v151
	v_and_b32_e32 v81, 0xffff0000, v151
	v_lshlrev_b32_e32 v90, 16, v147
	v_and_b32_e32 v91, 0xffff0000, v147
	v_pk_fma_f32 v[90:91], v[82:83], v[80:81], v[90:91]
	v_cvt_pk_bf16_f32 v80, v84, v85
	v_cvt_pk_bf16_f32 v81, v86, v87
	v_cvt_pk_bf16_f32 v82, v88, v89
	v_cvt_pk_bf16_f32 v83, v90, v91
	global_store_dwordx4 v[170:171], v[80:83], off offset:256
	s_nop 1
	v_lshlrev_b32_e32 v80, 16, v140
	v_and_b32_e32 v81, 0xffff0000, v140
	v_lshlrev_b32_e32 v82, 16, v136
	v_and_b32_e32 v83, 0xffff0000, v136
	v_pk_fma_f32 v[76:77], v[76:77], v[80:81], v[82:83]
	v_lshlrev_b32_e32 v80, 16, v141
	v_and_b32_e32 v81, 0xffff0000, v141
	v_lshlrev_b32_e32 v82, 16, v137
	v_and_b32_e32 v83, 0xffff0000, v137
	v_pk_fma_f32 v[78:79], v[78:79], v[80:81], v[82:83]
	v_lshlrev_b32_e32 v80, 16, v142
	v_and_b32_e32 v81, 0xffff0000, v142
	v_lshlrev_b32_e32 v82, 16, v138
	v_and_b32_e32 v83, 0xffff0000, v138
	v_pk_fma_f32 v[80:81], v[72:73], v[80:81], v[82:83]
	v_lshlrev_b32_e32 v72, 16, v143
	v_and_b32_e32 v73, 0xffff0000, v143
	v_lshlrev_b32_e32 v82, 16, v139
	v_and_b32_e32 v83, 0xffff0000, v139
	v_pk_fma_f32 v[82:83], v[74:75], v[72:73], v[82:83]
	v_cvt_pk_bf16_f32 v72, v76, v77
	v_cvt_pk_bf16_f32 v73, v78, v79
	v_cvt_pk_bf16_f32 v74, v80, v81
	v_cvt_pk_bf16_f32 v75, v82, v83
	global_store_dwordx4 v[168:169], v[72:75], off
	s_nop 1
	v_lshlrev_b32_e32 v72, 16, v132
	v_and_b32_e32 v73, 0xffff0000, v132
	v_lshlrev_b32_e32 v74, 16, v128
	v_and_b32_e32 v75, 0xffff0000, v128
	v_pk_fma_f32 v[68:69], v[68:69], v[72:73], v[74:75]
	v_lshlrev_b32_e32 v72, 16, v133
	v_and_b32_e32 v73, 0xffff0000, v133
	v_lshlrev_b32_e32 v74, 16, v129
	v_and_b32_e32 v75, 0xffff0000, v129
	v_pk_fma_f32 v[70:71], v[70:71], v[72:73], v[74:75]
	v_lshlrev_b32_e32 v72, 16, v134
	v_and_b32_e32 v73, 0xffff0000, v134
	v_lshlrev_b32_e32 v74, 16, v130
	v_and_b32_e32 v75, 0xffff0000, v130
	v_pk_fma_f32 v[72:73], v[64:65], v[72:73], v[74:75]
	v_lshlrev_b32_e32 v64, 16, v135
	v_and_b32_e32 v65, 0xffff0000, v135
	v_lshlrev_b32_e32 v74, 16, v131
	v_and_b32_e32 v75, 0xffff0000, v131
	v_pk_fma_f32 v[74:75], v[66:67], v[64:65], v[74:75]
	v_cvt_pk_bf16_f32 v64, v68, v69
	v_cvt_pk_bf16_f32 v65, v70, v71
	v_cvt_pk_bf16_f32 v66, v72, v73
	v_cvt_pk_bf16_f32 v67, v74, v75
	global_store_dwordx4 v[168:169], v[64:67], off offset:256
	s_nop 1
	v_add_u32_e32 v64, 0x80, v164
	v_ashrrev_i32_e32 v65, 31, v64
	v_lshlrev_b64 v[66:67], 12, v[64:65]
	v_lshl_add_u64 v[66:67], s[42:43], 0, v[66:67]
	v_lshlrev_b64 v[64:65], 11, v[64:65]
	v_lshl_add_u64 v[66:67], v[66:67], 0, v[166:167]
	v_lshl_add_u64 v[64:65], s[82:83], 0, v[64:65]
	global_load_dwordx4 v[92:95], v[66:67], off offset:2048
	v_lshl_add_u64 v[132:133], v[64:65], 0, v[166:167]
	global_load_dwordx4 v[96:99], v[132:133], off
	global_load_dwordx4 v[100:103], v[66:67], off offset:2304
	global_load_dwordx4 v[104:107], v[132:133], off offset:256
	v_add_u32_e32 v64, 0x90, v164
	v_ashrrev_i32_e32 v65, 31, v64
	v_lshlrev_b64 v[66:67], 12, v[64:65]
	v_lshl_add_u64 v[66:67], s[42:43], 0, v[66:67]
	v_lshlrev_b64 v[64:65], 11, v[64:65]
	v_lshl_add_u64 v[66:67], v[66:67], 0, v[166:167]
	v_lshl_add_u64 v[64:65], s[82:83], 0, v[64:65]
	global_load_dwordx4 v[108:111], v[66:67], off offset:2048
	v_lshl_add_u64 v[134:135], v[64:65], 0, v[166:167]
	global_load_dwordx4 v[112:115], v[134:135], off
	global_load_dwordx4 v[116:119], v[66:67], off offset:2304
	global_load_dwordx4 v[120:123], v[134:135], off offset:256
	v_add_u32_e32 v64, 0xa0, v164
	v_ashrrev_i32_e32 v65, 31, v64
	v_lshlrev_b64 v[66:67], 12, v[64:65]
	v_lshl_add_u64 v[66:67], s[42:43], 0, v[66:67]
	v_lshlrev_b64 v[64:65], 11, v[64:65]
	v_lshl_add_u64 v[64:65], s[82:83], 0, v[64:65]
	v_lshl_add_u64 v[66:67], v[66:67], 0, v[166:167]
	v_lshl_add_u64 v[90:91], v[64:65], 0, v[166:167]
	global_load_dwordx4 v[124:127], v[66:67], off offset:2048
	global_load_dwordx4 v[84:87], v[66:67], off offset:2304
	global_load_dwordx4 v[128:131], v[90:91], off
	global_load_dwordx4 v[80:83], v[90:91], off offset:256
	v_add_u32_e32 v64, 0xb0, v164
	v_ashrrev_i32_e32 v65, 31, v64
	v_lshlrev_b64 v[66:67], 12, v[64:65]
	v_lshl_add_u64 v[66:67], s[42:43], 0, v[66:67]
	v_lshlrev_b64 v[64:65], 11, v[64:65]
	v_lshl_add_u64 v[64:65], s[82:83], 0, v[64:65]
	v_lshl_add_u64 v[66:67], v[66:67], 0, v[166:167]
	v_lshl_add_u64 v[88:89], v[64:65], 0, v[166:167]
	global_load_dwordx4 v[76:79], v[66:67], off offset:2048
	global_load_dwordx4 v[68:71], v[66:67], off offset:2304
	global_load_dwordx4 v[72:75], v[88:89], off
	s_nop 0
	global_load_dwordx4 v[64:67], v[88:89], off offset:256
	s_waitcnt vmcnt(0)
	v_lshlrev_b32_e32 v136, 16, v92
	v_and_b32_e32 v137, 0xffff0000, v92
	v_lshlrev_b32_e32 v138, 16, v96
	v_and_b32_e32 v139, 0xffff0000, v96
	v_lshlrev_b32_e32 v92, 16, v93
	v_and_b32_e32 v93, 0xffff0000, v93
	v_lshlrev_b32_e32 v96, 16, v97
	v_and_b32_e32 v97, 0xffff0000, v97
	v_pk_fma_f32 v[62:63], v[62:63], v[92:93], v[96:97]
	v_lshlrev_b32_e32 v92, 16, v94
	v_and_b32_e32 v93, 0xffff0000, v94
	v_lshlrev_b32_e32 v96, 16, v98
	v_and_b32_e32 v97, 0xffff0000, v98
	v_pk_fma_f32 v[92:93], v[56:57], v[92:93], v[96:97]
	v_lshlrev_b32_e32 v56, 16, v95
	v_and_b32_e32 v57, 0xffff0000, v95
	v_lshlrev_b32_e32 v94, 16, v99
	v_and_b32_e32 v95, 0xffff0000, v99
	v_pk_fma_f32 v[60:61], v[60:61], v[136:137], v[138:139]
	v_pk_fma_f32 v[94:95], v[58:59], v[56:57], v[94:95]
	v_cvt_pk_bf16_f32 v56, v60, v61
	v_cvt_pk_bf16_f32 v57, v62, v63
	v_cvt_pk_bf16_f32 v58, v92, v93
	v_cvt_pk_bf16_f32 v59, v94, v95
	global_store_dwordx4 v[132:133], v[56:59], off
	s_nop 1
	v_lshlrev_b32_e32 v56, 16, v100
	v_and_b32_e32 v57, 0xffff0000, v100
	v_lshlrev_b32_e32 v58, 16, v104
	v_and_b32_e32 v59, 0xffff0000, v104
	v_pk_fma_f32 v[52:53], v[52:53], v[56:57], v[58:59]
	v_lshlrev_b32_e32 v56, 16, v101
	v_and_b32_e32 v57, 0xffff0000, v101
	v_lshlrev_b32_e32 v58, 16, v105
	v_and_b32_e32 v59, 0xffff0000, v105
	v_pk_fma_f32 v[54:55], v[54:55], v[56:57], v[58:59]
	v_lshlrev_b32_e32 v56, 16, v102
	v_and_b32_e32 v57, 0xffff0000, v102
	v_lshlrev_b32_e32 v58, 16, v106
	v_and_b32_e32 v59, 0xffff0000, v106
	v_pk_fma_f32 v[56:57], v[48:49], v[56:57], v[58:59]
	v_lshlrev_b32_e32 v48, 16, v103
	v_and_b32_e32 v49, 0xffff0000, v103
	v_lshlrev_b32_e32 v58, 16, v107
	v_and_b32_e32 v59, 0xffff0000, v107
	v_pk_fma_f32 v[58:59], v[50:51], v[48:49], v[58:59]
	v_cvt_pk_bf16_f32 v48, v52, v53
	v_cvt_pk_bf16_f32 v49, v54, v55
	v_cvt_pk_bf16_f32 v50, v56, v57
	v_cvt_pk_bf16_f32 v51, v58, v59
	global_store_dwordx4 v[132:133], v[48:51], off offset:256
	s_nop 1
	v_lshlrev_b32_e32 v48, 16, v108
	v_and_b32_e32 v49, 0xffff0000, v108
	v_lshlrev_b32_e32 v50, 16, v112
	v_and_b32_e32 v51, 0xffff0000, v112
	v_pk_fma_f32 v[44:45], v[44:45], v[48:49], v[50:51]
	v_lshlrev_b32_e32 v48, 16, v109
	v_and_b32_e32 v49, 0xffff0000, v109
	v_lshlrev_b32_e32 v50, 16, v113
	v_and_b32_e32 v51, 0xffff0000, v113
	v_pk_fma_f32 v[46:47], v[46:47], v[48:49], v[50:51]
	v_lshlrev_b32_e32 v48, 16, v110
	v_and_b32_e32 v49, 0xffff0000, v110
	v_lshlrev_b32_e32 v50, 16, v114
	v_and_b32_e32 v51, 0xffff0000, v114
	v_pk_fma_f32 v[48:49], v[40:41], v[48:49], v[50:51]
	v_lshlrev_b32_e32 v40, 16, v111
	v_and_b32_e32 v41, 0xffff0000, v111
	v_lshlrev_b32_e32 v50, 16, v115
	v_and_b32_e32 v51, 0xffff0000, v115
	v_pk_fma_f32 v[50:51], v[42:43], v[40:41], v[50:51]
	v_cvt_pk_bf16_f32 v40, v44, v45
	v_cvt_pk_bf16_f32 v41, v46, v47
	v_cvt_pk_bf16_f32 v42, v48, v49
	v_cvt_pk_bf16_f32 v43, v50, v51
	global_store_dwordx4 v[134:135], v[40:43], off
	s_nop 1
	v_lshlrev_b32_e32 v40, 16, v116
	v_and_b32_e32 v41, 0xffff0000, v116
	v_lshlrev_b32_e32 v42, 16, v120
	v_and_b32_e32 v43, 0xffff0000, v120
	v_pk_fma_f32 v[36:37], v[36:37], v[40:41], v[42:43]
	v_lshlrev_b32_e32 v40, 16, v117
	v_and_b32_e32 v41, 0xffff0000, v117
	v_lshlrev_b32_e32 v42, 16, v121
	v_and_b32_e32 v43, 0xffff0000, v121
	v_pk_fma_f32 v[38:39], v[38:39], v[40:41], v[42:43]
	v_lshlrev_b32_e32 v40, 16, v118
	v_and_b32_e32 v41, 0xffff0000, v118
	v_lshlrev_b32_e32 v42, 16, v122
	v_and_b32_e32 v43, 0xffff0000, v122
	v_pk_fma_f32 v[40:41], v[32:33], v[40:41], v[42:43]
	v_lshlrev_b32_e32 v32, 16, v119
	v_and_b32_e32 v33, 0xffff0000, v119
	v_lshlrev_b32_e32 v42, 16, v123
	v_and_b32_e32 v43, 0xffff0000, v123
	v_pk_fma_f32 v[42:43], v[34:35], v[32:33], v[42:43]
	v_cvt_pk_bf16_f32 v32, v36, v37
	v_cvt_pk_bf16_f32 v33, v38, v39
	v_cvt_pk_bf16_f32 v34, v40, v41
	v_cvt_pk_bf16_f32 v35, v42, v43
	global_store_dwordx4 v[134:135], v[32:35], off offset:256
	s_nop 1
	v_lshlrev_b32_e32 v32, 16, v124
	v_and_b32_e32 v33, 0xffff0000, v124
	v_lshlrev_b32_e32 v34, 16, v128
	v_and_b32_e32 v35, 0xffff0000, v128
	v_pk_fma_f32 v[28:29], v[28:29], v[32:33], v[34:35]
	v_lshlrev_b32_e32 v32, 16, v125
	v_and_b32_e32 v33, 0xffff0000, v125
	v_lshlrev_b32_e32 v34, 16, v129
	v_and_b32_e32 v35, 0xffff0000, v129
	v_pk_fma_f32 v[30:31], v[30:31], v[32:33], v[34:35]
	v_lshlrev_b32_e32 v32, 16, v126
	v_and_b32_e32 v33, 0xffff0000, v126
	v_lshlrev_b32_e32 v34, 16, v130
	v_and_b32_e32 v35, 0xffff0000, v130
	v_pk_fma_f32 v[32:33], v[24:25], v[32:33], v[34:35]
	v_lshlrev_b32_e32 v24, 16, v127
	v_and_b32_e32 v25, 0xffff0000, v127
	v_lshlrev_b32_e32 v34, 16, v131
	v_and_b32_e32 v35, 0xffff0000, v131
	v_pk_fma_f32 v[34:35], v[26:27], v[24:25], v[34:35]
	v_cvt_pk_bf16_f32 v24, v28, v29
	v_cvt_pk_bf16_f32 v25, v30, v31
	v_cvt_pk_bf16_f32 v26, v32, v33
	v_cvt_pk_bf16_f32 v27, v34, v35
	global_store_dwordx4 v[90:91], v[24:27], off
	s_nop 1
	v_lshlrev_b32_e32 v24, 16, v84
	v_and_b32_e32 v25, 0xffff0000, v84
	v_lshlrev_b32_e32 v26, 16, v80
	v_and_b32_e32 v27, 0xffff0000, v80
	v_pk_fma_f32 v[20:21], v[20:21], v[24:25], v[26:27]
	v_lshlrev_b32_e32 v24, 16, v85
	v_and_b32_e32 v25, 0xffff0000, v85
	v_lshlrev_b32_e32 v26, 16, v81
	v_and_b32_e32 v27, 0xffff0000, v81
	v_pk_fma_f32 v[22:23], v[22:23], v[24:25], v[26:27]
	v_lshlrev_b32_e32 v24, 16, v86
	v_and_b32_e32 v25, 0xffff0000, v86
	v_lshlrev_b32_e32 v26, 16, v82
	v_and_b32_e32 v27, 0xffff0000, v82
	v_pk_fma_f32 v[24:25], v[16:17], v[24:25], v[26:27]
	v_lshlrev_b32_e32 v16, 16, v87
	v_and_b32_e32 v17, 0xffff0000, v87
	v_lshlrev_b32_e32 v26, 16, v83
	v_and_b32_e32 v27, 0xffff0000, v83
	v_pk_fma_f32 v[26:27], v[18:19], v[16:17], v[26:27]
	v_cvt_pk_bf16_f32 v16, v20, v21
	v_cvt_pk_bf16_f32 v17, v22, v23
	v_cvt_pk_bf16_f32 v18, v24, v25
	v_cvt_pk_bf16_f32 v19, v26, v27
	global_store_dwordx4 v[90:91], v[16:19], off offset:256
	s_nop 1
	v_lshlrev_b32_e32 v16, 16, v76
	v_and_b32_e32 v17, 0xffff0000, v76
	v_lshlrev_b32_e32 v18, 16, v72
	v_and_b32_e32 v19, 0xffff0000, v72
	v_pk_fma_f32 v[12:13], v[12:13], v[16:17], v[18:19]
	v_lshlrev_b32_e32 v16, 16, v77
	v_and_b32_e32 v17, 0xffff0000, v77
	v_lshlrev_b32_e32 v18, 16, v73
	v_and_b32_e32 v19, 0xffff0000, v73
	v_pk_fma_f32 v[14:15], v[14:15], v[16:17], v[18:19]
	v_lshlrev_b32_e32 v16, 16, v78
	v_and_b32_e32 v17, 0xffff0000, v78
	v_lshlrev_b32_e32 v18, 16, v74
	v_and_b32_e32 v19, 0xffff0000, v74
	v_pk_fma_f32 v[16:17], v[8:9], v[16:17], v[18:19]
	v_lshlrev_b32_e32 v8, 16, v79
	v_and_b32_e32 v9, 0xffff0000, v79
	v_lshlrev_b32_e32 v18, 16, v75
	v_and_b32_e32 v19, 0xffff0000, v75
	v_pk_fma_f32 v[18:19], v[10:11], v[8:9], v[18:19]
	v_cvt_pk_bf16_f32 v8, v12, v13
	v_cvt_pk_bf16_f32 v9, v14, v15
	v_cvt_pk_bf16_f32 v10, v16, v17
	v_cvt_pk_bf16_f32 v11, v18, v19
	global_store_dwordx4 v[88:89], v[8:11], off
	s_nop 1
	v_lshlrev_b32_e32 v8, 16, v68
	v_and_b32_e32 v9, 0xffff0000, v68
	v_lshlrev_b32_e32 v10, 16, v64
	v_and_b32_e32 v11, 0xffff0000, v64
	v_pk_fma_f32 v[4:5], v[4:5], v[8:9], v[10:11]
	v_lshlrev_b32_e32 v8, 16, v69
	v_and_b32_e32 v9, 0xffff0000, v69
	v_lshlrev_b32_e32 v10, 16, v65
	v_and_b32_e32 v11, 0xffff0000, v65
	v_pk_fma_f32 v[6:7], v[6:7], v[8:9], v[10:11]
	v_lshlrev_b32_e32 v8, 16, v70
	v_and_b32_e32 v9, 0xffff0000, v70
	v_lshlrev_b32_e32 v10, 16, v66
	v_and_b32_e32 v11, 0xffff0000, v66
	v_pk_fma_f32 v[8:9], v[0:1], v[8:9], v[10:11]
	v_lshlrev_b32_e32 v0, 16, v71
	v_and_b32_e32 v1, 0xffff0000, v71
	v_lshlrev_b32_e32 v10, 16, v67
	v_and_b32_e32 v11, 0xffff0000, v67
	v_pk_fma_f32 v[10:11], v[2:3], v[0:1], v[10:11]
	v_cvt_pk_bf16_f32 v0, v4, v5
	v_cvt_pk_bf16_f32 v1, v6, v7
	v_cvt_pk_bf16_f32 v2, v8, v9
	v_cvt_pk_bf16_f32 v3, v10, v11
	global_store_dwordx4 v[88:89], v[0:3], off offset:256
	s_cbranch_vccz .LBB0_1277
	s_waitcnt vmcnt(0)
	s_cmpk_gt_u32 s26, 0xff
	s_cbranch_scc1 .LBB0_1289
	s_barrier

.LBB0_1356:
	ds_read_b128 v[144:147], v190
	ds_read_b128 v[148:151], v190 offset:1024
	ds_read_b128 v[166:169], v190 offset:2048
	ds_read_b128 v[170:173], v190 offset:3072
	ds_read_b128 v[174:177], v190 offset:4096
	ds_read_b128 v[180:183], v190 offset:5120
	ds_read_b128 v[184:187], v190 offset:6144
	ds_read_b128 v[194:197], v190 offset:7168
	ds_read_b128 v[128:131], v189
	ds_read_b128 v[132:135], v189 offset:1024
	ds_read_b128 v[136:139], v189 offset:2048
	ds_read_b128 v[140:143], v189 offset:3072
	s_add_u32 s24, s10, 0xfffc0080
	s_addc_u32 s25, s11, -1
	s_cmp_eq_u32 s47, 12
	s_cselect_b32 s27, s15, s25
	s_cselect_b32 s26, s29, s24
	s_cselect_b32 s25, s17, s46
	s_cselect_b32 s24, s44, s45
	v_lshl_add_u64 v[198:199], s[10:11], 0, v[162:163]
	s_add_i32 m0, s7, 0xc000
	global_load_lds_dwordx4 v[198:199], off
	v_lshl_add_u64 v[198:199], s[10:11], 0, v[164:165]
	s_add_i32 m0, s7, 0xe000
	s_nop 0
	global_load_lds_dwordx4 v[198:199], off
	s_waitcnt lgkmcnt(0)
	s_barrier
	s_waitcnt lgkmcnt(0)
	v_mfma_f32_16x16x32_bf16 v[124:127], v[128:131], v[144:147], v[124:127]
	v_mfma_f32_16x16x32_bf16 v[120:123], v[136:139], v[144:147], v[120:123]
	v_mfma_f32_16x16x32_bf16 v[108:111], v[128:131], v[166:169], v[108:111]
	v_mfma_f32_16x16x32_bf16 v[104:107], v[136:139], v[166:169], v[104:107]
	v_mfma_f32_16x16x32_bf16 v[92:95], v[128:131], v[174:177], v[92:95]
	v_mfma_f32_16x16x32_bf16 v[88:91], v[136:139], v[174:177], v[88:91]
	v_mfma_f32_16x16x32_bf16 v[76:79], v[128:131], v[184:187], v[76:79]
	v_mfma_f32_16x16x32_bf16 v[72:75], v[136:139], v[184:187], v[72:75]
	v_mfma_f32_16x16x32_bf16 v[124:127], v[132:135], v[148:151], v[124:127]
	v_mfma_f32_16x16x32_bf16 v[120:123], v[140:143], v[148:151], v[120:123]
	v_mfma_f32_16x16x32_bf16 v[108:111], v[132:135], v[170:173], v[108:111]
	v_mfma_f32_16x16x32_bf16 v[104:107], v[140:143], v[170:173], v[104:107]
	v_mfma_f32_16x16x32_bf16 v[92:95], v[132:135], v[180:183], v[92:95]
	v_mfma_f32_16x16x32_bf16 v[88:91], v[140:143], v[180:183], v[88:91]
	v_mfma_f32_16x16x32_bf16 v[76:79], v[132:135], v[194:197], v[76:79]
	v_mfma_f32_16x16x32_bf16 v[72:75], v[140:143], v[194:197], v[72:75]
	s_barrier
	s_add_i32 s48, s41, s33
	v_lshl_add_u64 v[214:215], s[24:25], 0, v[156:157]
	s_mov_b32 m0, s48
	ds_read_b128 v[198:201], v191
	ds_read_b128 v[202:205], v191 offset:1024
	ds_read_b128 v[206:209], v191 offset:2048
	ds_read_b128 v[210:213], v191 offset:3072
	global_load_lds_dwordx4 v[214:215], off
	v_lshl_add_u64 v[216:217], s[24:25], 0, v[152:153]
	s_add_i32 m0, s48, 0x2000
	s_nop 0
	global_load_lds_dwordx4 v[216:217], off
	s_barrier
	s_waitcnt lgkmcnt(0)
	v_mfma_f32_16x16x32_bf16 v[116:119], v[198:201], v[144:147], v[116:119]
	v_mfma_f32_16x16x32_bf16 v[112:115], v[206:209], v[144:147], v[112:115]
	v_mfma_f32_16x16x32_bf16 v[100:103], v[198:201], v[166:169], v[100:103]
	v_mfma_f32_16x16x32_bf16 v[96:99], v[206:209], v[166:169], v[96:99]
	v_mfma_f32_16x16x32_bf16 v[84:87], v[198:201], v[174:177], v[84:87]
	v_mfma_f32_16x16x32_bf16 v[80:83], v[206:209], v[174:177], v[80:83]
	v_mfma_f32_16x16x32_bf16 v[68:71], v[198:201], v[184:187], v[68:71]
	v_mfma_f32_16x16x32_bf16 v[64:67], v[206:209], v[184:187], v[64:67]
	v_mfma_f32_16x16x32_bf16 v[116:119], v[202:205], v[148:151], v[116:119]
	v_mfma_f32_16x16x32_bf16 v[112:115], v[210:213], v[148:151], v[112:115]
	v_mfma_f32_16x16x32_bf16 v[100:103], v[202:205], v[170:173], v[100:103]
	v_mfma_f32_16x16x32_bf16 v[96:99], v[210:213], v[170:173], v[96:99]
	v_mfma_f32_16x16x32_bf16 v[84:87], v[202:205], v[180:183], v[84:87]
	v_mfma_f32_16x16x32_bf16 v[80:83], v[210:213], v[180:183], v[80:83]
	v_mfma_f32_16x16x32_bf16 v[68:71], v[202:205], v[194:197], v[68:71]
	v_mfma_f32_16x16x32_bf16 v[64:67], v[210:213], v[194:197], v[64:67]
	s_mov_b32 m0, s7
	v_lshl_add_u64 v[218:219], s[26:27], 0, v[158:159]
	s_barrier
	ds_read_b128 v[144:147], v190 offset:16384
	ds_read_b128 v[148:151], v190 offset:17408
	ds_read_b128 v[166:169], v190 offset:18432
	ds_read_b128 v[170:173], v190 offset:19456
	ds_read_b128 v[174:177], v190 offset:20480
	ds_read_b128 v[180:183], v190 offset:21504
	ds_read_b128 v[184:187], v190 offset:22528
	ds_read_b128 v[194:197], v190 offset:23552
	global_load_lds_dwordx4 v[218:219], off
	v_lshl_add_u64 v[222:223], s[26:27], 0, v[154:155]
	s_mov_b32 m0, s35
	s_nop 0
	global_load_lds_dwordx4 v[222:223], off
	s_barrier
	s_waitcnt lgkmcnt(0)
	v_mfma_f32_16x16x32_bf16 v[60:63], v[128:131], v[144:147], v[60:63]
	v_mfma_f32_16x16x32_bf16 v[56:59], v[136:139], v[144:147], v[56:59]
	v_mfma_f32_16x16x32_bf16 v[44:47], v[128:131], v[166:169], v[44:47]
	v_mfma_f32_16x16x32_bf16 v[40:43], v[136:139], v[166:169], v[40:43]
	v_mfma_f32_16x16x32_bf16 v[28:31], v[128:131], v[174:177], v[28:31]
	v_mfma_f32_16x16x32_bf16 v[24:27], v[136:139], v[174:177], v[24:27]
	v_mfma_f32_16x16x32_bf16 v[12:15], v[128:131], v[184:187], v[12:15]
	v_mfma_f32_16x16x32_bf16 v[8:11], v[136:139], v[184:187], v[8:11]
	v_mfma_f32_16x16x32_bf16 v[60:63], v[132:135], v[148:151], v[60:63]
	v_mfma_f32_16x16x32_bf16 v[56:59], v[140:143], v[148:151], v[56:59]
	v_mfma_f32_16x16x32_bf16 v[44:47], v[132:135], v[170:173], v[44:47]
	v_mfma_f32_16x16x32_bf16 v[40:43], v[140:143], v[170:173], v[40:43]
	v_mfma_f32_16x16x32_bf16 v[28:31], v[132:135], v[180:183], v[28:31]
	v_mfma_f32_16x16x32_bf16 v[24:27], v[140:143], v[180:183], v[24:27]
	v_mfma_f32_16x16x32_bf16 v[12:15], v[132:135], v[194:197], v[12:15]
	v_mfma_f32_16x16x32_bf16 v[8:11], v[140:143], v[194:197], v[8:11]
	s_barrier
	s_add_u32 s48, s24, 0x40000
	s_addc_u32 s49, s25, 0
	s_add_i32 s50, s42, s33
	v_lshl_add_u64 v[128:129], s[48:49], 0, v[156:157]
	s_mov_b32 m0, s50
	s_nop 0
	global_load_lds_dwordx4 v[128:129], off
	v_lshl_add_u64 v[128:129], s[48:49], 0, v[152:153]
	s_add_i32 m0, s50, 0x2000
	s_nop 0
	global_load_lds_dwordx4 v[128:129], off
	s_waitcnt vmcnt(6)
	s_barrier
	v_mfma_f32_16x16x32_bf16 v[52:55], v[198:201], v[144:147], v[52:55]
	v_mfma_f32_16x16x32_bf16 v[48:51], v[206:209], v[144:147], v[48:51]
	v_mfma_f32_16x16x32_bf16 v[36:39], v[198:201], v[166:169], v[36:39]
	v_mfma_f32_16x16x32_bf16 v[32:35], v[206:209], v[166:169], v[32:35]
	v_mfma_f32_16x16x32_bf16 v[20:23], v[198:201], v[174:177], v[20:23]
	v_mfma_f32_16x16x32_bf16 v[16:19], v[206:209], v[174:177], v[16:19]
	v_mfma_f32_16x16x32_bf16 v[4:7], v[198:201], v[184:187], v[4:7]
	v_mfma_f32_16x16x32_bf16 v[0:3], v[206:209], v[184:187], v[0:3]
	v_mfma_f32_16x16x32_bf16 v[52:55], v[202:205], v[148:151], v[52:55]
	v_mfma_f32_16x16x32_bf16 v[48:51], v[210:213], v[148:151], v[48:51]
	v_mfma_f32_16x16x32_bf16 v[36:39], v[202:205], v[170:173], v[36:39]
	v_mfma_f32_16x16x32_bf16 v[32:35], v[210:213], v[170:173], v[32:35]
	v_mfma_f32_16x16x32_bf16 v[20:23], v[202:205], v[180:183], v[20:23]
	v_mfma_f32_16x16x32_bf16 v[16:19], v[210:213], v[180:183], v[16:19]
	v_mfma_f32_16x16x32_bf16 v[4:7], v[202:205], v[194:197], v[4:7]
	v_mfma_f32_16x16x32_bf16 v[0:3], v[210:213], v[194:197], v[0:3]
	s_add_i32 s48, 0, 0x18000
	v_add_u32_e32 v140, s48, v188
	s_barrier
	ds_read_b128 v[144:147], v190 offset:32768
	ds_read_b128 v[148:151], v190 offset:33792
	ds_read_b128 v[166:169], v190 offset:34816
	ds_read_b128 v[170:173], v190 offset:35840
	ds_read_b128 v[174:177], v190 offset:36864
	ds_read_b128 v[180:183], v190 offset:37888
	ds_read_b128 v[184:187], v190 offset:38912
	ds_read_b128 v[194:197], v190 offset:39936
	ds_read_b128 v[128:131], v140
	ds_read_b128 v[132:135], v140 offset:1024
	ds_read_b128 v[136:139], v140 offset:2048
	ds_read_b128 v[140:143], v140 offset:3072
	s_add_u32 s26, s26, 0x40000
	s_addc_u32 s27, s27, 0
	s_mov_b32 m0, s36
	v_lshl_add_u64 v[198:199], s[26:27], 0, v[158:159]
	global_load_lds_dwordx4 v[198:199], off
	v_lshl_add_u64 v[198:199], s[26:27], 0, v[154:155]
	s_mov_b32 m0, s37
	s_nop 0
	global_load_lds_dwordx4 v[198:199], off
	s_waitcnt lgkmcnt(0)
	s_barrier
	s_waitcnt lgkmcnt(0)
	v_mfma_f32_16x16x32_bf16 v[124:127], v[128:131], v[144:147], v[124:127]
	v_mfma_f32_16x16x32_bf16 v[120:123], v[136:139], v[144:147], v[120:123]
	v_mfma_f32_16x16x32_bf16 v[108:111], v[128:131], v[166:169], v[108:111]
	v_mfma_f32_16x16x32_bf16 v[104:107], v[136:139], v[166:169], v[104:107]
	v_mfma_f32_16x16x32_bf16 v[92:95], v[128:131], v[174:177], v[92:95]
	v_mfma_f32_16x16x32_bf16 v[88:91], v[136:139], v[174:177], v[88:91]
	v_mfma_f32_16x16x32_bf16 v[76:79], v[128:131], v[184:187], v[76:79]
	v_mfma_f32_16x16x32_bf16 v[72:75], v[136:139], v[184:187], v[72:75]
	v_mfma_f32_16x16x32_bf16 v[124:127], v[132:135], v[148:151], v[124:127]
	v_mfma_f32_16x16x32_bf16 v[120:123], v[140:143], v[148:151], v[120:123]
	v_mfma_f32_16x16x32_bf16 v[108:111], v[132:135], v[170:173], v[108:111]
	v_mfma_f32_16x16x32_bf16 v[104:107], v[140:143], v[170:173], v[104:107]
	v_mfma_f32_16x16x32_bf16 v[92:95], v[132:135], v[180:183], v[92:95]
	v_mfma_f32_16x16x32_bf16 v[88:91], v[140:143], v[180:183], v[88:91]
	v_mfma_f32_16x16x32_bf16 v[76:79], v[132:135], v[194:197], v[76:79]
	v_mfma_f32_16x16x32_bf16 v[72:75], v[140:143], v[194:197], v[72:75]
	s_barrier
	s_add_i32 s26, 0, 0x1c000
	s_add_i32 s27, s48, s33
	v_add_u32_e32 v193, s26, v188
	v_lshl_add_u64 v[214:215], v[214:215], 0, s[12:13]
	s_mov_b32 m0, s27
	ds_read_b128 v[198:201], v193
	ds_read_b128 v[202:205], v193 offset:1024
	ds_read_b128 v[206:209], v193 offset:2048
	ds_read_b128 v[210:213], v193 offset:3072
	global_load_lds_dwordx4 v[214:215], off
	v_lshl_add_u64 v[214:215], v[216:217], 0, s[12:13]
	s_add_i32 m0, s27, 0x2000
	s_nop 0
	global_load_lds_dwordx4 v[214:215], off
	s_barrier
	s_waitcnt lgkmcnt(0)
	v_mfma_f32_16x16x32_bf16 v[116:119], v[198:201], v[144:147], v[116:119]
	v_mfma_f32_16x16x32_bf16 v[112:115], v[206:209], v[144:147], v[112:115]
	v_mfma_f32_16x16x32_bf16 v[100:103], v[198:201], v[166:169], v[100:103]
	v_mfma_f32_16x16x32_bf16 v[96:99], v[206:209], v[166:169], v[96:99]
	v_mfma_f32_16x16x32_bf16 v[84:87], v[198:201], v[174:177], v[84:87]
	v_mfma_f32_16x16x32_bf16 v[80:83], v[206:209], v[174:177], v[80:83]
	v_mfma_f32_16x16x32_bf16 v[68:71], v[198:201], v[184:187], v[68:71]
	v_mfma_f32_16x16x32_bf16 v[64:67], v[206:209], v[184:187], v[64:67]
	v_mfma_f32_16x16x32_bf16 v[116:119], v[202:205], v[148:151], v[116:119]
	v_mfma_f32_16x16x32_bf16 v[112:115], v[210:213], v[148:151], v[112:115]
	v_mfma_f32_16x16x32_bf16 v[100:103], v[202:205], v[170:173], v[100:103]
	v_mfma_f32_16x16x32_bf16 v[96:99], v[210:213], v[170:173], v[96:99]
	v_mfma_f32_16x16x32_bf16 v[84:87], v[202:205], v[180:183], v[84:87]
	v_mfma_f32_16x16x32_bf16 v[80:83], v[210:213], v[180:183], v[80:83]
	v_mfma_f32_16x16x32_bf16 v[68:71], v[202:205], v[194:197], v[68:71]
	v_mfma_f32_16x16x32_bf16 v[64:67], v[210:213], v[194:197], v[64:67]
	s_mov_b32 m0, s39
	v_lshl_add_u64 v[214:215], v[218:219], 0, s[12:13]
	s_barrier
	ds_read_b128 v[144:147], v190 offset:49152
	ds_read_b128 v[148:151], v190 offset:50176
	ds_read_b128 v[166:169], v190 offset:51200
	ds_read_b128 v[170:173], v190 offset:52224
	ds_read_b128 v[174:177], v190 offset:53248
	ds_read_b128 v[180:183], v190 offset:54272
	ds_read_b128 v[184:187], v190 offset:55296
	ds_read_b128 v[194:197], v190 offset:56320
	global_load_lds_dwordx4 v[214:215], off
	v_lshl_add_u64 v[214:215], v[222:223], 0, s[12:13]
	s_mov_b32 m0, s40
	s_nop 0
	global_load_lds_dwordx4 v[214:215], off
	s_barrier
	s_waitcnt lgkmcnt(0)
	v_mfma_f32_16x16x32_bf16 v[60:63], v[128:131], v[144:147], v[60:63]
	v_mfma_f32_16x16x32_bf16 v[56:59], v[136:139], v[144:147], v[56:59]
	v_mfma_f32_16x16x32_bf16 v[44:47], v[128:131], v[166:169], v[44:47]
	v_mfma_f32_16x16x32_bf16 v[40:43], v[136:139], v[166:169], v[40:43]
	v_mfma_f32_16x16x32_bf16 v[28:31], v[128:131], v[174:177], v[28:31]
	v_mfma_f32_16x16x32_bf16 v[24:27], v[136:139], v[174:177], v[24:27]
	v_mfma_f32_16x16x32_bf16 v[12:15], v[128:131], v[184:187], v[12:15]
	v_mfma_f32_16x16x32_bf16 v[8:11], v[136:139], v[184:187], v[8:11]
	v_mfma_f32_16x16x32_bf16 v[60:63], v[132:135], v[148:151], v[60:63]
	v_mfma_f32_16x16x32_bf16 v[56:59], v[140:143], v[148:151], v[56:59]
	v_mfma_f32_16x16x32_bf16 v[44:47], v[132:135], v[170:173], v[44:47]
	v_mfma_f32_16x16x32_bf16 v[40:43], v[140:143], v[170:173], v[40:43]
	v_mfma_f32_16x16x32_bf16 v[28:31], v[132:135], v[180:183], v[28:31]
	v_mfma_f32_16x16x32_bf16 v[24:27], v[140:143], v[180:183], v[24:27]
	v_mfma_f32_16x16x32_bf16 v[12:15], v[132:135], v[194:197], v[12:15]
	v_mfma_f32_16x16x32_bf16 v[8:11], v[140:143], v[194:197], v[8:11]
	s_barrier
	s_add_u32 s24, s24, 0x40080
	s_addc_u32 s25, s25, 0
	s_add_i32 s26, s26, s33
	v_lshl_add_u64 v[128:129], s[24:25], 0, v[156:157]
	s_mov_b32 m0, s26
	s_nop 0
	global_load_lds_dwordx4 v[128:129], off
	v_lshl_add_u64 v[128:129], s[24:25], 0, v[152:153]
	s_add_i32 m0, s26, 0x2000
	s_nop 0
	global_load_lds_dwordx4 v[128:129], off
	s_waitcnt vmcnt(6)
	s_barrier
	v_mfma_f32_16x16x32_bf16 v[52:55], v[198:201], v[144:147], v[52:55]
	v_mfma_f32_16x16x32_bf16 v[48:51], v[206:209], v[144:147], v[48:51]
	v_mfma_f32_16x16x32_bf16 v[36:39], v[198:201], v[166:169], v[36:39]
	v_mfma_f32_16x16x32_bf16 v[32:35], v[206:209], v[166:169], v[32:35]
	v_mfma_f32_16x16x32_bf16 v[20:23], v[198:201], v[174:177], v[20:23]
	v_mfma_f32_16x16x32_bf16 v[16:19], v[206:209], v[174:177], v[16:19]
	v_mfma_f32_16x16x32_bf16 v[4:7], v[198:201], v[184:187], v[4:7]
	v_mfma_f32_16x16x32_bf16 v[0:3], v[206:209], v[184:187], v[0:3]
	v_mfma_f32_16x16x32_bf16 v[52:55], v[202:205], v[148:151], v[52:55]
	v_mfma_f32_16x16x32_bf16 v[48:51], v[210:213], v[148:151], v[48:51]
	v_mfma_f32_16x16x32_bf16 v[36:39], v[202:205], v[170:173], v[36:39]
	v_mfma_f32_16x16x32_bf16 v[32:35], v[210:213], v[170:173], v[32:35]
	v_mfma_f32_16x16x32_bf16 v[20:23], v[202:205], v[180:183], v[20:23]
	v_mfma_f32_16x16x32_bf16 v[16:19], v[210:213], v[180:183], v[16:19]
	v_mfma_f32_16x16x32_bf16 v[4:7], v[202:205], v[194:197], v[4:7]
	v_mfma_f32_16x16x32_bf16 v[0:3], v[210:213], v[194:197], v[0:3]
	s_add_i32 s47, s47, 2
	s_add_u32 s10, s10, 0x100
	s_addc_u32 s11, s11, 0
	s_add_u32 s45, s45, 0x100
	s_addc_u32 s46, s46, 0
	s_cmp_gt_u32 s47, 13
	s_barrier
	s_cbranch_scc0 .LBB0_1356
	s_lshl_b32 s24, s4, 8
	s_ashr_i32 s25, s24, 31
	s_lshl_b32 s10, s4, 2
	s_nop 0
	v_lshl_add_u32 v166, s28, 8, v179
	s_ashr_i32 s11, s10, 31
	s_lshl_b64 s[28:29], s[24:25], 1
	v_readlane_b32 s50, v253, 40
	v_readlane_b32 s51, v253, 41
	s_add_u32 s26, s50, s28
	v_ashrrev_i32_e32 v167, 31, v166
	s_addc_u32 s27, s51, s29
	v_lshlrev_b64 v[204:205], 11, v[166:167]
	v_lshl_add_u64 v[128:129], s[26:27], 0, v[204:205]
	v_lshl_add_u64 v[206:207], v[128:129], 0, v[160:161]
	global_load_dwordx4 v[196:199], v[206:207], off
	global_load_dwordx4 v[200:203], v[206:207], off offset:256
	v_or_b32_e32 v182, 16, v166
	v_or_b32_e32 v174, 32, v166
	v_or_b32_e32 v168, 48, v166
	v_ashrrev_i32_e32 v183, 31, v182
	v_ashrrev_i32_e32 v175, 31, v174
	v_ashrrev_i32_e32 v169, 31, v168
	v_lshlrev_b64 v[186:187], 11, v[182:183]
	v_lshlrev_b64 v[180:181], 11, v[174:175]
	v_lshlrev_b64 v[172:173], 11, v[168:169]
	v_lshl_add_u64 v[128:129], s[26:27], 0, v[186:187]
	v_lshl_add_u64 v[130:131], s[26:27], 0, v[180:181]
	v_lshl_add_u64 v[132:133], s[26:27], 0, v[172:173]
	v_lshl_add_u64 v[184:185], v[128:129], 0, v[160:161]
	v_lshl_add_u64 v[176:177], v[130:131], 0, v[160:161]
	v_lshl_add_u64 v[170:171], v[132:133], 0, v[160:161]
	global_load_dwordx4 v[148:151], v[184:185], off
	global_load_dwordx4 v[144:147], v[184:185], off offset:256
	global_load_dwordx4 v[140:143], v[176:177], off
	global_load_dwordx4 v[136:139], v[176:177], off offset:256
	global_load_dwordx4 v[132:135], v[170:171], off
	global_load_dwordx4 v[128:131], v[170:171], off offset:256
	v_and_b32_e32 v194, 64, v192
	v_xor_b32_e32 v193, 16, v192
	v_add_u32_e32 v194, 64, v194
	v_cmp_lt_i32_e32 vcc, v193, v194
	v_xor_b32_e32 v195, 32, v192
	v_lshl_add_u64 v[204:205], s[50:51], 0, v[204:205]
	v_cndmask_b32_e32 v193, v192, v193, vcc
	v_cmp_lt_i32_e32 vcc, v195, v194
	v_lshlrev_b32_e32 v194, 2, v193
	s_nop 0
	v_cndmask_b32_e32 v195, v192, v195, vcc
	v_lshlrev_b32_e32 v193, 2, v195
	s_nop 7
	s_nop 3
	s_waitcnt vmcnt(0)
	v_lshlrev_b32_e32 v210, 16, v198
	v_and_b32_e32 v211, 0xffff0000, v198
	v_lshlrev_b32_e32 v208, 16, v196
	v_and_b32_e32 v209, 0xffff0000, v196
	v_lshlrev_b32_e32 v198, 16, v199
	v_and_b32_e32 v199, 0xffff0000, v199
	v_lshlrev_b32_e32 v214, 16, v202
	v_and_b32_e32 v215, 0xffff0000, v202
	v_lshlrev_b32_e32 v202, 16, v203
	v_and_b32_e32 v203, 0xffff0000, v203
	v_pk_add_f32 v[120:121], v[120:121], v[210:211]
	v_lshlrev_b32_e32 v196, 16, v197
	v_and_b32_e32 v197, 0xffff0000, v197
	v_pk_add_f32 v[124:125], v[124:125], v[208:209]
	v_pk_add_f32 v[122:123], v[122:123], v[198:199]
	v_pk_add_f32 v[198:199], v[114:115], v[202:203]
	v_cvt_pk_bf16_f32 v114, v120, v121
	v_pk_mul_f32 v[120:121], v[120:121], v[120:121]
	v_pk_add_f32 v[126:127], v[126:127], v[196:197]
	v_cvt_pk_bf16_f32 v115, v122, v123
	v_pk_mul_f32 v[122:123], v[122:123], v[122:123]
	v_pk_fma_f32 v[120:121], v[124:125], v[124:125], v[120:121]
	v_lshlrev_b32_e32 v212, 16, v200
	v_and_b32_e32 v213, 0xffff0000, v200
	v_lshlrev_b32_e32 v200, 16, v201
	v_and_b32_e32 v201, 0xffff0000, v201
	v_pk_add_f32 v[196:197], v[112:113], v[214:215]
	v_pk_fma_f32 v[122:123], v[126:127], v[126:127], v[122:123]
	v_add_f32_e32 v120, v120, v121
	v_pk_add_f32 v[116:117], v[116:117], v[212:213]
	v_pk_add_f32 v[118:119], v[118:119], v[200:201]
	v_pk_mul_f32 v[200:201], v[196:197], v[196:197]
	v_add_f32_e32 v120, v122, v120
	v_cvt_pk_bf16_f32 v112, v124, v125
	v_pk_fma_f32 v[124:125], v[116:117], v[116:117], v[200:201]
	v_add_f32_e32 v120, v123, v120
	v_pk_mul_f32 v[202:203], v[198:199], v[198:199]
	v_add_f32_e32 v120, v124, v120
	v_cvt_pk_bf16_f32 v113, v126, v127
	v_pk_fma_f32 v[126:127], v[118:119], v[118:119], v[202:203]
	v_add_f32_e32 v120, v125, v120
	v_add_f32_e32 v120, v126, v120
	v_add_f32_e32 v122, v127, v120
	ds_bpermute_b32 v123, v194, v122
	global_store_dwordx4 v[206:207], v[112:115], off
	v_lshl_add_u64 v[120:121], v[204:205], 0, s[28:29]
	s_nop 0
	v_cvt_pk_bf16_f32 v114, v116, v117
	s_waitcnt lgkmcnt(0)
	v_add_f32_e32 v112, v122, v123
	ds_bpermute_b32 v113, v193, v112
	v_cvt_pk_bf16_f32 v115, v118, v119
	v_cvt_pk_bf16_f32 v116, v196, v197
	v_cvt_pk_bf16_f32 v117, v198, v199
	v_lshl_add_u64 v[118:119], v[120:121], 0, v[160:161]
	global_store_dwordx4 v[118:119], v[114:117], off offset:256
	s_and_saveexec_b64 s[28:29], s[0:1]
	s_cbranch_execz .LBB0_1359
	s_waitcnt lgkmcnt(0)
	v_add_f32_e32 v114, v112, v113
	v_lshlrev_b64 v[112:113], 6, v[166:167]
	v_lshl_add_u64 v[112:113], s[86:87], 0, v[112:113]
	v_lshl_add_u64 v[112:113], s[10:11], 2, v[112:113]
	s_lshl_b32 s4, s38, 2
	v_lshl_add_u64 v[112:113], v[112:113], 0, s[4:5]
	global_store_dword v[112:113], v114, off

.LBB0_1441:
	ds_read_b128 v[184:187], v165
	ds_read_b128 v[188:191], v165 offset:1024
	ds_read_b128 v[192:195], v165 offset:2048
	ds_read_b128 v[196:199], v165 offset:3072
	ds_read_b128 v[200:203], v165 offset:4096
	ds_read_b128 v[204:207], v165 offset:5120
	ds_read_b128 v[208:211], v165 offset:6144
	ds_read_b128 v[212:215], v165 offset:7168
	ds_read_b128 v[144:147], v161
	ds_read_b128 v[148:151], v161 offset:1024
	ds_read_b128 v[172:175], v161 offset:2048
	ds_read_b128 v[180:183], v161 offset:3072
	s_add_u32 s4, s0, 0xfffc0080
	s_addc_u32 s5, s1, -1
	s_cmp_eq_u32 s45, 12
	s_cselect_b32 s11, s19, s5
	s_cselect_b32 s10, s41, s4
	s_cselect_b32 s5, s21, s44
	s_cselect_b32 s4, s42, s43
	v_lshl_add_u64 v[154:155], s[0:1], 0, v[140:141]
	s_add_i32 m0, s17, 0xc000
	global_load_lds_dwordx4 v[154:155], off
	v_lshl_add_u64 v[154:155], s[0:1], 0, v[142:143]
	s_add_i32 m0, s17, 0xe000
	s_nop 0
	global_load_lds_dwordx4 v[154:155], off
	s_waitcnt lgkmcnt(0)
	s_barrier
	s_waitcnt lgkmcnt(0)
	v_mfma_f32_16x16x32_bf16 v[124:127], v[144:147], v[184:187], v[124:127]
	v_mfma_f32_16x16x32_bf16 v[120:123], v[172:175], v[184:187], v[120:123]
	v_mfma_f32_16x16x32_bf16 v[108:111], v[144:147], v[192:195], v[108:111]
	v_mfma_f32_16x16x32_bf16 v[104:107], v[172:175], v[192:195], v[104:107]
	v_mfma_f32_16x16x32_bf16 v[92:95], v[144:147], v[200:203], v[92:95]
	v_mfma_f32_16x16x32_bf16 v[88:91], v[172:175], v[200:203], v[88:91]
	v_mfma_f32_16x16x32_bf16 v[76:79], v[144:147], v[208:211], v[76:79]
	v_mfma_f32_16x16x32_bf16 v[72:75], v[172:175], v[208:211], v[72:75]
	v_mfma_f32_16x16x32_bf16 v[124:127], v[148:151], v[188:191], v[124:127]
	v_mfma_f32_16x16x32_bf16 v[120:123], v[180:183], v[188:191], v[120:123]
	v_mfma_f32_16x16x32_bf16 v[108:111], v[148:151], v[196:199], v[108:111]
	v_mfma_f32_16x16x32_bf16 v[104:107], v[180:183], v[196:199], v[104:107]
	v_mfma_f32_16x16x32_bf16 v[92:95], v[148:151], v[204:207], v[92:95]
	v_mfma_f32_16x16x32_bf16 v[88:91], v[180:183], v[204:207], v[88:91]
	v_mfma_f32_16x16x32_bf16 v[76:79], v[148:151], v[212:215], v[76:79]
	v_mfma_f32_16x16x32_bf16 v[72:75], v[180:183], v[212:215], v[72:75]
	s_barrier
	s_add_i32 s46, s37, s15
	v_lshl_add_u64 v[154:155], s[4:5], 0, v[132:133]
	s_mov_b32 m0, s46
	ds_read_b128 v[216:219], v167
	ds_read_b128 v[222:225], v167 offset:1024
	ds_read_b128 v[226:229], v167 offset:2048
	ds_read_b128 v[230:233], v167 offset:3072
	global_load_lds_dwordx4 v[154:155], off
	v_lshl_add_u64 v[158:159], s[4:5], 0, v[128:129]
	s_add_i32 m0, s46, 0x2000
	s_nop 0
	global_load_lds_dwordx4 v[158:159], off
	s_barrier
	s_waitcnt lgkmcnt(0)
	v_mfma_f32_16x16x32_bf16 v[116:119], v[216:219], v[184:187], v[116:119]
	v_mfma_f32_16x16x32_bf16 v[112:115], v[226:229], v[184:187], v[112:115]
	v_mfma_f32_16x16x32_bf16 v[100:103], v[216:219], v[192:195], v[100:103]
	v_mfma_f32_16x16x32_bf16 v[96:99], v[226:229], v[192:195], v[96:99]
	v_mfma_f32_16x16x32_bf16 v[84:87], v[216:219], v[200:203], v[84:87]
	v_mfma_f32_16x16x32_bf16 v[80:83], v[226:229], v[200:203], v[80:83]
	v_mfma_f32_16x16x32_bf16 v[68:71], v[216:219], v[208:211], v[68:71]
	v_mfma_f32_16x16x32_bf16 v[64:67], v[226:229], v[208:211], v[64:67]
	v_mfma_f32_16x16x32_bf16 v[116:119], v[222:225], v[188:191], v[116:119]
	v_mfma_f32_16x16x32_bf16 v[112:115], v[230:233], v[188:191], v[112:115]
	v_mfma_f32_16x16x32_bf16 v[100:103], v[222:225], v[196:199], v[100:103]
	v_mfma_f32_16x16x32_bf16 v[96:99], v[230:233], v[196:199], v[96:99]
	v_mfma_f32_16x16x32_bf16 v[84:87], v[222:225], v[204:207], v[84:87]
	v_mfma_f32_16x16x32_bf16 v[80:83], v[230:233], v[204:207], v[80:83]
	v_mfma_f32_16x16x32_bf16 v[68:71], v[222:225], v[212:215], v[68:71]
	v_mfma_f32_16x16x32_bf16 v[64:67], v[230:233], v[212:215], v[64:67]
	s_mov_b32 m0, s17
	v_lshl_add_u64 v[162:163], s[10:11], 0, v[134:135]
	s_barrier
	ds_read_b128 v[184:187], v165 offset:16384
	ds_read_b128 v[188:191], v165 offset:17408
	ds_read_b128 v[192:195], v165 offset:18432
	ds_read_b128 v[196:199], v165 offset:19456
	ds_read_b128 v[200:203], v165 offset:20480
	ds_read_b128 v[204:207], v165 offset:21504
	ds_read_b128 v[208:211], v165 offset:22528
	ds_read_b128 v[212:215], v165 offset:23552
	global_load_lds_dwordx4 v[162:163], off
	v_lshl_add_u64 v[168:169], s[10:11], 0, v[130:131]
	s_mov_b32 m0, s28
	s_nop 0
	global_load_lds_dwordx4 v[168:169], off
	s_barrier
	s_waitcnt lgkmcnt(0)
	v_mfma_f32_16x16x32_bf16 v[60:63], v[144:147], v[184:187], v[60:63]
	v_mfma_f32_16x16x32_bf16 v[56:59], v[172:175], v[184:187], v[56:59]
	v_mfma_f32_16x16x32_bf16 v[44:47], v[144:147], v[192:195], v[44:47]
	v_mfma_f32_16x16x32_bf16 v[40:43], v[172:175], v[192:195], v[40:43]
	v_mfma_f32_16x16x32_bf16 v[28:31], v[144:147], v[200:203], v[28:31]
	v_mfma_f32_16x16x32_bf16 v[24:27], v[172:175], v[200:203], v[24:27]
	v_mfma_f32_16x16x32_bf16 v[12:15], v[144:147], v[208:211], v[12:15]
	v_mfma_f32_16x16x32_bf16 v[8:11], v[172:175], v[208:211], v[8:11]
	v_mfma_f32_16x16x32_bf16 v[60:63], v[148:151], v[188:191], v[60:63]
	v_mfma_f32_16x16x32_bf16 v[56:59], v[180:183], v[188:191], v[56:59]
	v_mfma_f32_16x16x32_bf16 v[44:47], v[148:151], v[196:199], v[44:47]
	v_mfma_f32_16x16x32_bf16 v[40:43], v[180:183], v[196:199], v[40:43]
	v_mfma_f32_16x16x32_bf16 v[28:31], v[148:151], v[204:207], v[28:31]
	v_mfma_f32_16x16x32_bf16 v[24:27], v[180:183], v[204:207], v[24:27]
	v_mfma_f32_16x16x32_bf16 v[12:15], v[148:151], v[212:215], v[12:15]
	v_mfma_f32_16x16x32_bf16 v[8:11], v[180:183], v[212:215], v[8:11]
	s_barrier
	s_add_u32 s46, s4, 0x40000
	s_addc_u32 s47, s5, 0
	s_add_i32 s48, s38, s15
	v_lshl_add_u64 v[144:145], s[46:47], 0, v[132:133]
	s_mov_b32 m0, s48
	s_nop 0
	global_load_lds_dwordx4 v[144:145], off
	v_lshl_add_u64 v[144:145], s[46:47], 0, v[128:129]
	s_add_i32 m0, s48, 0x2000
	s_nop 0
	global_load_lds_dwordx4 v[144:145], off
	s_waitcnt vmcnt(6)
	s_barrier
	v_mfma_f32_16x16x32_bf16 v[52:55], v[216:219], v[184:187], v[52:55]
	v_mfma_f32_16x16x32_bf16 v[48:51], v[226:229], v[184:187], v[48:51]
	v_mfma_f32_16x16x32_bf16 v[36:39], v[216:219], v[192:195], v[36:39]
	v_mfma_f32_16x16x32_bf16 v[32:35], v[226:229], v[192:195], v[32:35]
	v_mfma_f32_16x16x32_bf16 v[20:23], v[216:219], v[200:203], v[20:23]
	v_mfma_f32_16x16x32_bf16 v[16:19], v[226:229], v[200:203], v[16:19]
	v_mfma_f32_16x16x32_bf16 v[4:7], v[216:219], v[208:211], v[4:7]
	v_mfma_f32_16x16x32_bf16 v[0:3], v[226:229], v[208:211], v[0:3]
	v_mfma_f32_16x16x32_bf16 v[52:55], v[222:225], v[188:191], v[52:55]
	v_mfma_f32_16x16x32_bf16 v[48:51], v[230:233], v[188:191], v[48:51]
	v_mfma_f32_16x16x32_bf16 v[36:39], v[222:225], v[196:199], v[36:39]
	v_mfma_f32_16x16x32_bf16 v[32:35], v[230:233], v[196:199], v[32:35]
	v_mfma_f32_16x16x32_bf16 v[20:23], v[222:225], v[204:207], v[20:23]
	v_mfma_f32_16x16x32_bf16 v[16:19], v[230:233], v[204:207], v[16:19]
	v_mfma_f32_16x16x32_bf16 v[4:7], v[222:225], v[212:215], v[4:7]
	v_mfma_f32_16x16x32_bf16 v[0:3], v[230:233], v[212:215], v[0:3]
	s_add_i32 s46, 0, 0x18000
	v_add_u32_e32 v152, s46, v157
	s_barrier
	ds_read_b128 v[184:187], v165 offset:32768
	ds_read_b128 v[188:191], v165 offset:33792
	ds_read_b128 v[192:195], v165 offset:34816
	ds_read_b128 v[196:199], v165 offset:35840
	ds_read_b128 v[200:203], v165 offset:36864
	ds_read_b128 v[204:207], v165 offset:37888
	ds_read_b128 v[208:211], v165 offset:38912
	ds_read_b128 v[212:215], v165 offset:39936
	ds_read_b128 v[144:147], v152
	ds_read_b128 v[148:151], v152 offset:1024
	ds_read_b128 v[172:175], v152 offset:2048
	ds_read_b128 v[180:183], v152 offset:3072
	s_add_u32 s10, s10, 0x40000
	s_addc_u32 s11, s11, 0
	s_mov_b32 m0, s29
	v_lshl_add_u64 v[176:177], s[10:11], 0, v[134:135]
	global_load_lds_dwordx4 v[176:177], off
	v_lshl_add_u64 v[176:177], s[10:11], 0, v[130:131]
	s_mov_b32 m0, s31
	s_nop 0
	global_load_lds_dwordx4 v[176:177], off
	s_waitcnt lgkmcnt(0)
	s_barrier
	s_waitcnt lgkmcnt(0)
	v_mfma_f32_16x16x32_bf16 v[124:127], v[144:147], v[184:187], v[124:127]
	v_mfma_f32_16x16x32_bf16 v[120:123], v[172:175], v[184:187], v[120:123]
	v_mfma_f32_16x16x32_bf16 v[108:111], v[144:147], v[192:195], v[108:111]
	v_mfma_f32_16x16x32_bf16 v[104:107], v[172:175], v[192:195], v[104:107]
	v_mfma_f32_16x16x32_bf16 v[92:95], v[144:147], v[200:203], v[92:95]
	v_mfma_f32_16x16x32_bf16 v[88:91], v[172:175], v[200:203], v[88:91]
	v_mfma_f32_16x16x32_bf16 v[76:79], v[144:147], v[208:211], v[76:79]
	v_mfma_f32_16x16x32_bf16 v[72:75], v[172:175], v[208:211], v[72:75]
	v_mfma_f32_16x16x32_bf16 v[124:127], v[148:151], v[188:191], v[124:127]
	v_mfma_f32_16x16x32_bf16 v[120:123], v[180:183], v[188:191], v[120:123]
	v_mfma_f32_16x16x32_bf16 v[108:111], v[148:151], v[196:199], v[108:111]
	v_mfma_f32_16x16x32_bf16 v[104:107], v[180:183], v[196:199], v[104:107]
	v_mfma_f32_16x16x32_bf16 v[92:95], v[148:151], v[204:207], v[92:95]
	v_mfma_f32_16x16x32_bf16 v[88:91], v[180:183], v[204:207], v[88:91]
	v_mfma_f32_16x16x32_bf16 v[76:79], v[148:151], v[212:215], v[76:79]
	v_mfma_f32_16x16x32_bf16 v[72:75], v[180:183], v[212:215], v[72:75]
	s_barrier
	s_add_i32 s10, 0, 0x1c000
	s_add_i32 s11, s46, s15
	v_add_u32_e32 v152, s10, v157
	v_lshl_add_u64 v[154:155], v[154:155], 0, s[12:13]
	s_mov_b32 m0, s11
	ds_read_b128 v[216:219], v152
	ds_read_b128 v[222:225], v152 offset:1024
	ds_read_b128 v[226:229], v152 offset:2048
	ds_read_b128 v[230:233], v152 offset:3072
	global_load_lds_dwordx4 v[154:155], off
	v_lshl_add_u64 v[154:155], v[158:159], 0, s[12:13]
	s_add_i32 m0, s11, 0x2000
	s_nop 0
	global_load_lds_dwordx4 v[154:155], off
	s_barrier
	s_waitcnt lgkmcnt(0)
	v_mfma_f32_16x16x32_bf16 v[116:119], v[216:219], v[184:187], v[116:119]
	v_mfma_f32_16x16x32_bf16 v[112:115], v[226:229], v[184:187], v[112:115]
	v_mfma_f32_16x16x32_bf16 v[100:103], v[216:219], v[192:195], v[100:103]
	v_mfma_f32_16x16x32_bf16 v[96:99], v[226:229], v[192:195], v[96:99]
	v_mfma_f32_16x16x32_bf16 v[84:87], v[216:219], v[200:203], v[84:87]
	v_mfma_f32_16x16x32_bf16 v[80:83], v[226:229], v[200:203], v[80:83]
	v_mfma_f32_16x16x32_bf16 v[68:71], v[216:219], v[208:211], v[68:71]
	v_mfma_f32_16x16x32_bf16 v[64:67], v[226:229], v[208:211], v[64:67]
	v_mfma_f32_16x16x32_bf16 v[116:119], v[222:225], v[188:191], v[116:119]
	v_mfma_f32_16x16x32_bf16 v[112:115], v[230:233], v[188:191], v[112:115]
	v_mfma_f32_16x16x32_bf16 v[100:103], v[222:225], v[196:199], v[100:103]
	v_mfma_f32_16x16x32_bf16 v[96:99], v[230:233], v[196:199], v[96:99]
	v_mfma_f32_16x16x32_bf16 v[84:87], v[222:225], v[204:207], v[84:87]
	v_mfma_f32_16x16x32_bf16 v[80:83], v[230:233], v[204:207], v[80:83]
	v_mfma_f32_16x16x32_bf16 v[68:71], v[222:225], v[212:215], v[68:71]
	v_mfma_f32_16x16x32_bf16 v[64:67], v[230:233], v[212:215], v[64:67]
	s_mov_b32 m0, s35
	v_lshl_add_u64 v[154:155], v[162:163], 0, s[12:13]
	s_barrier
	ds_read_b128 v[184:187], v165 offset:49152
	ds_read_b128 v[188:191], v165 offset:50176
	ds_read_b128 v[192:195], v165 offset:51200
	ds_read_b128 v[196:199], v165 offset:52224
	ds_read_b128 v[200:203], v165 offset:53248
	ds_read_b128 v[204:207], v165 offset:54272
	ds_read_b128 v[208:211], v165 offset:55296
	ds_read_b128 v[212:215], v165 offset:56320
	global_load_lds_dwordx4 v[154:155], off
	v_lshl_add_u64 v[154:155], v[168:169], 0, s[12:13]
	s_mov_b32 m0, s36
	s_nop 0
	global_load_lds_dwordx4 v[154:155], off
	s_barrier
	s_waitcnt lgkmcnt(0)
	v_mfma_f32_16x16x32_bf16 v[60:63], v[144:147], v[184:187], v[60:63]
	v_mfma_f32_16x16x32_bf16 v[56:59], v[172:175], v[184:187], v[56:59]
	v_mfma_f32_16x16x32_bf16 v[44:47], v[144:147], v[192:195], v[44:47]
	v_mfma_f32_16x16x32_bf16 v[40:43], v[172:175], v[192:195], v[40:43]
	v_mfma_f32_16x16x32_bf16 v[28:31], v[144:147], v[200:203], v[28:31]
	v_mfma_f32_16x16x32_bf16 v[24:27], v[172:175], v[200:203], v[24:27]
	v_mfma_f32_16x16x32_bf16 v[12:15], v[144:147], v[208:211], v[12:15]
	v_mfma_f32_16x16x32_bf16 v[8:11], v[172:175], v[208:211], v[8:11]
	v_mfma_f32_16x16x32_bf16 v[60:63], v[148:151], v[188:191], v[60:63]
	v_mfma_f32_16x16x32_bf16 v[56:59], v[180:183], v[188:191], v[56:59]
	v_mfma_f32_16x16x32_bf16 v[44:47], v[148:151], v[196:199], v[44:47]
	v_mfma_f32_16x16x32_bf16 v[40:43], v[180:183], v[196:199], v[40:43]
	v_mfma_f32_16x16x32_bf16 v[28:31], v[148:151], v[204:207], v[28:31]
	v_mfma_f32_16x16x32_bf16 v[24:27], v[180:183], v[204:207], v[24:27]
	v_mfma_f32_16x16x32_bf16 v[12:15], v[148:151], v[212:215], v[12:15]
	v_mfma_f32_16x16x32_bf16 v[8:11], v[180:183], v[212:215], v[8:11]
	s_barrier
	s_add_u32 s4, s4, 0x40080
	s_addc_u32 s5, s5, 0
	s_add_i32 s10, s10, s15
	v_lshl_add_u64 v[144:145], s[4:5], 0, v[132:133]
	s_mov_b32 m0, s10
	s_nop 0
	global_load_lds_dwordx4 v[144:145], off
	v_lshl_add_u64 v[144:145], s[4:5], 0, v[128:129]
	s_add_i32 m0, s10, 0x2000
	s_nop 0
	global_load_lds_dwordx4 v[144:145], off
	s_waitcnt vmcnt(6)
	s_barrier
	v_mfma_f32_16x16x32_bf16 v[52:55], v[216:219], v[184:187], v[52:55]
	v_mfma_f32_16x16x32_bf16 v[48:51], v[226:229], v[184:187], v[48:51]
	v_mfma_f32_16x16x32_bf16 v[36:39], v[216:219], v[192:195], v[36:39]
	v_mfma_f32_16x16x32_bf16 v[32:35], v[226:229], v[192:195], v[32:35]
	v_mfma_f32_16x16x32_bf16 v[20:23], v[216:219], v[200:203], v[20:23]
	v_mfma_f32_16x16x32_bf16 v[16:19], v[226:229], v[200:203], v[16:19]
	v_mfma_f32_16x16x32_bf16 v[4:7], v[216:219], v[208:211], v[4:7]
	v_mfma_f32_16x16x32_bf16 v[0:3], v[226:229], v[208:211], v[0:3]
	v_mfma_f32_16x16x32_bf16 v[52:55], v[222:225], v[188:191], v[52:55]
	v_mfma_f32_16x16x32_bf16 v[48:51], v[230:233], v[188:191], v[48:51]
	v_mfma_f32_16x16x32_bf16 v[36:39], v[222:225], v[196:199], v[36:39]
	v_mfma_f32_16x16x32_bf16 v[32:35], v[230:233], v[196:199], v[32:35]
	v_mfma_f32_16x16x32_bf16 v[20:23], v[222:225], v[204:207], v[20:23]
	v_mfma_f32_16x16x32_bf16 v[16:19], v[230:233], v[204:207], v[16:19]
	v_mfma_f32_16x16x32_bf16 v[4:7], v[222:225], v[212:215], v[4:7]
	v_mfma_f32_16x16x32_bf16 v[0:3], v[230:233], v[212:215], v[0:3]
	s_add_i32 s45, s45, 2
	s_add_u32 s0, s0, 0x100
	s_addc_u32 s1, s1, 0
	s_add_u32 s43, s43, 0x100
	s_addc_u32 s44, s44, 0
	s_cmp_gt_u32 s45, 13
	s_barrier
	s_cbranch_scc0 .LBB0_1441
	v_lshl_add_u32 v168, s72, 8, v153
	v_ashrrev_i32_e32 v169, 31, v168
	v_or_b32_e32 v162, 16, v168
	v_lshlrev_b64 v[144:145], 6, v[168:169]
	v_ashrrev_i32_e32 v163, 31, v162
	v_or_b32_e32 v158, 32, v168
	v_lshl_add_u64 v[144:145], v[138:139], 0, v[144:145]
	v_lshlrev_b64 v[146:147], 6, v[162:163]
	v_ashrrev_i32_e32 v159, 31, v158
	v_lshl_add_u64 v[146:147], v[138:139], 0, v[146:147]
	global_load_dwordx4 v[172:175], v[144:145], off
	global_load_dwordx4 v[180:183], v[146:147], off
	v_lshlrev_b64 v[144:145], 6, v[158:159]
	v_or_b32_e32 v154, 48, v168
	v_lshl_add_u64 v[144:145], v[138:139], 0, v[144:145]
	v_ashrrev_i32_e32 v155, 31, v154
	global_load_dwordx4 v[184:187], v[144:145], off
	v_lshlrev_b64 v[144:145], 6, v[154:155]
	v_lshl_add_u64 v[144:145], v[138:139], 0, v[144:145]
	global_load_dwordx4 v[188:191], v[144:145], off
	v_add_u32_e32 v150, 0x80, v168
	v_ashrrev_i32_e32 v151, 31, v150
	v_lshlrev_b64 v[144:145], 6, v[150:151]
	v_add_u32_e32 v148, 0x90, v168
	v_lshl_add_u64 v[144:145], v[138:139], 0, v[144:145]
	v_ashrrev_i32_e32 v149, 31, v148
	global_load_dwordx4 v[192:195], v[144:145], off
	v_lshlrev_b64 v[144:145], 6, v[148:149]
	v_lshl_add_u64 v[144:145], v[138:139], 0, v[144:145]
	global_load_dwordx4 v[196:199], v[144:145], off
	v_and_b32_e32 v145, 64, v171
	v_add_u32_e32 v146, 0xa0, v168
	v_add_u32_e32 v144, 0xb0, v168
	v_add_u32_e32 v160, 64, v145
	v_ashrrev_i32_e32 v147, 31, v146
	v_ashrrev_i32_e32 v145, 31, v144
	v_lshlrev_b64 v[200:201], 6, v[146:147]
	v_lshlrev_b64 v[202:203], 6, v[144:145]
	v_lshl_add_u64 v[200:201], v[138:139], 0, v[200:201]
	v_lshl_add_u64 v[204:205], v[138:139], 0, v[202:203]
	global_load_dwordx4 v[200:203], v[200:201], off
	s_nop 0
	global_load_dwordx4 v[204:207], v[204:205], off
	v_xor_b32_e32 v152, 16, v171
	v_cmp_lt_i32_e32 vcc, v152, v160
	v_xor_b32_e32 v156, 32, v171
	v_mov_b64_e32 v[176:177], s[16:17]
	v_cndmask_b32_e32 v152, v171, v152, vcc
	v_lshlrev_b32_e32 v152, 2, v152
	v_cmp_lt_i32_e32 vcc, v156, v160
	v_lshlrev_b64 v[168:169], 7, v[168:169]
	s_mov_b32 s72, s18
	v_cndmask_b32_e32 v156, v171, v156, vcc
	v_lshlrev_b32_e32 v156, 2, v156
	s_mov_b32 s21, s18
	s_mov_b32 s19, s40
	s_waitcnt vmcnt(0)
	v_mov_b32_e32 v208, v173
	v_mov_b32_e32 v209, v174
	v_mov_b32_e32 v173, v175
	v_mov_b32_e32 v174, v181
	v_mov_b32_e32 v175, v182
	v_mov_b32_e32 v181, v183
	v_pk_add_f32 v[172:173], v[208:209], v[172:173]
	v_pk_add_f32 v[174:175], v[174:175], v[180:181]
	v_mov_b32_e32 v181, v172
	v_mov_b32_e32 v180, v174
	v_mov_b32_e32 v172, v175
	v_mov_b32_e32 v182, v185
	v_mov_b32_e32 v183, v186
	v_mov_b32_e32 v185, v187
	v_mov_b32_e32 v186, v189
	v_mov_b32_e32 v187, v190
	v_mov_b32_e32 v189, v191
	v_pk_add_f32 v[172:173], v[180:181], v[172:173]
	v_pk_add_f32 v[182:183], v[182:183], v[184:185]
	v_pk_add_f32 v[184:185], v[186:187], v[188:189]
	ds_bpermute_b32 v181, v152, v173
	ds_bpermute_b32 v180, v152, v172
	v_mov_b32_e32 v174, v184
	v_mov_b32_e32 v175, v182
	v_mov_b32_e32 v182, v185
	v_pk_add_f32 v[174:175], v[174:175], v[182:183]
	ds_bpermute_b32 v183, v152, v175
	ds_bpermute_b32 v182, v152, v174
	s_waitcnt lgkmcnt(0)
	v_pk_add_f32 v[172:173], v[172:173], v[180:181]
	ds_bpermute_b32 v181, v156, v173
	ds_bpermute_b32 v180, v156, v172
	v_mov_b32_e32 v184, v193
	v_pk_add_f32 v[174:175], v[174:175], v[182:183]
	ds_bpermute_b32 v183, v156, v175
	ds_bpermute_b32 v182, v156, v174
	s_waitcnt lgkmcnt(2)
	v_pk_add_f32 v[172:173], v[172:173], v[180:181]
	v_mov_b32_e32 v185, v194
	v_mov_b32_e32 v193, v195
	v_mov_b32_e32 v186, v197
	v_mov_b32_e32 v187, v198
	v_pk_fma_f32 v[172:173], v[172:173], s[14:15], v[176:177] op_sel_hi:[1,0,0]
	v_mov_b32_e32 v197, v199
	v_pk_add_f32 v[184:185], v[184:185], v[192:193]
	v_mul_f32_e32 v160, 0x4b800000, v173
	v_cmp_gt_f32_e32 vcc, s39, v173
	v_pk_add_f32 v[180:181], v[186:187], v[196:197]
	s_waitcnt lgkmcnt(0)
	v_pk_add_f32 v[174:175], v[174:175], v[182:183]
	v_cndmask_b32_e32 v160, v173, v160, vcc
	v_mov_b32_e32 v182, v180
	v_mov_b32_e32 v183, v184
	v_mov_b32_e32 v184, v181
	v_rsq_f32_e32 v160, v160
	v_pk_add_f32 v[180:181], v[182:183], v[184:185]
	ds_bpermute_b32 v183, v152, v181
	ds_bpermute_b32 v182, v152, v180
	v_pk_fma_f32 v[174:175], v[174:175], s[14:15], v[176:177] op_sel_hi:[1,0,0]
	v_mul_f32_e32 v164, 0x4b800000, v172
	v_cmp_gt_f32_e64 s[0:1], s39, v172
	v_mul_f32_e32 v170, 0x45800000, v160
	v_mul_f32_e32 v166, 0x4b800000, v175
	v_cndmask_b32_e64 v164, v172, v164, s[0:1]
	v_cmp_gt_f32_e64 s[4:5], s39, v175
	v_cndmask_b32_e32 v172, v160, v170, vcc
	v_mul_f32_e32 v160, 0x4b800000, v174
	v_cmp_gt_f32_e32 vcc, s39, v174
	v_cndmask_b32_e64 v166, v175, v166, s[4:5]
	v_mov_b32_e32 v184, v205
	v_cndmask_b32_e32 v160, v174, v160, vcc
	s_waitcnt lgkmcnt(0)
	v_pk_add_f32 v[174:175], v[180:181], v[182:183]
	ds_bpermute_b32 v181, v156, v175
	ds_bpermute_b32 v180, v156, v174
	v_mov_b32_e32 v185, v206
	v_mov_b32_e32 v205, v207
	v_pk_add_f32 v[184:185], v[184:185], v[204:205]
	v_rsq_f32_e32 v164, v164
	s_waitcnt lgkmcnt(0)
	v_pk_add_f32 v[174:175], v[174:175], v[180:181]
	v_mov_b32_e32 v180, v201
	v_mov_b32_e32 v181, v202
	v_mov_b32_e32 v201, v203
	v_pk_add_f32 v[180:181], v[180:181], v[200:201]
	v_mov_b32_e32 v186, v184
	v_mov_b32_e32 v187, v180
	v_mov_b32_e32 v180, v185
	v_rsq_f32_e32 v166, v166
	v_pk_add_f32 v[180:181], v[186:187], v[180:181]
	ds_bpermute_b32 v185, v152, v181
	ds_bpermute_b32 v184, v152, v180
	v_mul_f32_e32 v173, 0x45800000, v164
	v_cndmask_b32_e64 v182, v164, v173, s[0:1]
	v_mul_f32_e32 v164, 0x45800000, v166
	v_pk_fma_f32 v[174:175], v[174:175], s[14:15], v[176:177] op_sel_hi:[1,0,0]
	v_cndmask_b32_e64 v170, v166, v164, s[4:5]
	v_mul_f32_e32 v166, 0x4b800000, v175
	v_cmp_gt_f32_e64 s[0:1], s39, v175
	v_mul_f32_e32 v152, 0x4b800000, v174
	v_cmp_gt_f32_e64 s[4:5], s39, v174
	v_cndmask_b32_e64 v166, v175, v166, s[0:1]
	v_rsq_f32_e32 v160, v160
	v_cndmask_b32_e64 v152, v174, v152, s[4:5]
	s_waitcnt lgkmcnt(0)
	v_pk_add_f32 v[174:175], v[180:181], v[184:185]
	ds_bpermute_b32 v181, v156, v175
	ds_bpermute_b32 v180, v156, v174
	v_rsq_f32_e32 v173, v166
	v_mul_f32_e32 v164, 0x45800000, v160
	v_cndmask_b32_e32 v166, v160, v164, vcc
	v_rsq_f32_e32 v152, v152
	s_waitcnt lgkmcnt(0)
	v_pk_add_f32 v[174:175], v[174:175], v[180:181]
	v_mul_f32_e32 v156, 0x45800000, v173
	v_pk_fma_f32 v[174:175], v[174:175], s[14:15], v[176:177] op_sel_hi:[1,0,0]
	v_cndmask_b32_e64 v164, v173, v156, s[0:1]
	v_mul_f32_e32 v160, 0x4b800000, v175
	v_cmp_gt_f32_e32 vcc, s39, v175
	v_cmp_gt_f32_e64 s[0:1], s39, v174
	v_mul_f32_e32 v156, 0x45800000, v152
	v_cndmask_b32_e32 v160, v175, v160, vcc
	v_rsq_f32_e32 v173, v160
	v_mul_f32_e32 v160, 0x4b800000, v174
	v_cndmask_b32_e64 v160, v174, v160, s[0:1]
	v_rsq_f32_e32 v174, v160
	v_cndmask_b32_e64 v160, v152, v156, s[4:5]
	v_mul_f32_e32 v152, 0x45800000, v173
	v_cndmask_b32_e32 v156, v173, v152, vcc
	v_mul_f32_e32 v152, 0x45800000, v174
	v_cndmask_b32_e64 v152, v174, v152, s[0:1]
	s_lshl_b32 s0, s70, 8
	s_or_b32 s0, s0, s33
	s_ashr_i32 s4, s0, 6
	s_ashr_i32 s5, s4, 31
	s_lshl_b64 s[0:1], s[4:5], 22
	v_pk_mul_f32 v[124:125], v[124:125], v[172:173] op_sel_hi:[1,0]
	v_pk_mul_f32 v[120:121], v[120:121], v[172:173] op_sel_hi:[1,0]
	s_add_u32 s0, s84, s0
	v_pk_mul_f32 v[126:127], v[126:127], v[172:173] op_sel_hi:[1,0]
	v_pk_mul_f32 v[122:123], v[122:123], v[172:173] op_sel_hi:[1,0]
	v_max_f32_e32 v124, 0, v124
	v_max_f32_e32 v120, 0, v120
	v_max_f32_e32 v125, 0, v125
	v_max_f32_e32 v121, 0, v121
	s_addc_u32 s1, s85, s1
	s_or_b32 s4, s4, 2
	v_pk_mul_f32 v[124:125], v[124:125], v[124:125]
	v_pk_mul_f32 v[174:175], v[120:121], v[120:121]
	v_max_f32_e32 v120, 0, v126
	v_max_f32_e32 v122, 0, v122
	v_max_f32_e32 v121, 0, v127
	v_max_f32_e32 v123, 0, v123
	s_ashr_i32 s5, s4, 31
	v_pk_mul_f32 v[126:127], v[120:121], v[120:121]
	v_pk_mul_f32 v[176:177], v[122:123], v[122:123]
	v_cvt_pk_bf16_f32 v120, v124, v125
	v_lshl_add_u64 v[124:125], s[0:1], 0, v[168:169]
	v_pk_mul_f32 v[116:117], v[116:117], v[172:173] op_sel_hi:[1,0]
	v_pk_mul_f32 v[112:113], v[112:113], v[172:173] op_sel_hi:[1,0]
	s_lshl_b64 s[4:5], s[4:5], 22
	v_cvt_pk_bf16_f32 v121, v126, v127
	v_cvt_pk_bf16_f32 v122, v174, v175
	v_cvt_pk_bf16_f32 v123, v176, v177
	v_lshl_add_u64 v[124:125], v[124:125], 0, v[136:137]
	v_pk_mul_f32 v[118:119], v[118:119], v[172:173] op_sel_hi:[1,0]
	v_pk_mul_f32 v[114:115], v[114:115], v[172:173] op_sel_hi:[1,0]
	v_max_f32_e32 v116, 0, v116
	v_max_f32_e32 v112, 0, v112
	v_max_f32_e32 v117, 0, v117
	v_max_f32_e32 v113, 0, v113
	s_add_u32 s4, s84, s4
	global_store_dwordx4 v[124:125], v[120:123], off nt
	v_pk_mul_f32 v[116:117], v[116:117], v[116:117]
	v_max_f32_e32 v114, 0, v114
	v_pk_mul_f32 v[120:121], v[112:113], v[112:113]
	v_max_f32_e32 v112, 0, v118
	v_max_f32_e32 v113, 0, v119
	v_max_f32_e32 v115, 0, v115
	s_addc_u32 s5, s85, s5
	v_pk_mul_f32 v[118:119], v[112:113], v[112:113]
	v_pk_mul_f32 v[122:123], v[114:115], v[114:115]
	v_cvt_pk_bf16_f32 v112, v116, v117
	v_lshl_add_u64 v[116:117], s[4:5], 0, v[168:169]
	v_pk_mul_f32 v[108:109], v[108:109], v[182:183] op_sel_hi:[1,0]
	v_pk_mul_f32 v[104:105], v[104:105], v[182:183] op_sel_hi:[1,0]
	v_cvt_pk_bf16_f32 v113, v118, v119
	v_cvt_pk_bf16_f32 v114, v120, v121
	v_cvt_pk_bf16_f32 v115, v122, v123
	v_lshl_add_u64 v[116:117], v[116:117], 0, v[136:137]
	v_pk_mul_f32 v[110:111], v[110:111], v[182:183] op_sel_hi:[1,0]
	v_pk_mul_f32 v[106:107], v[106:107], v[182:183] op_sel_hi:[1,0]
	v_max_f32_e32 v108, 0, v108
	v_max_f32_e32 v104, 0, v104
	v_max_f32_e32 v109, 0, v109
	v_max_f32_e32 v105, 0, v105
	global_store_dwordx4 v[116:117], v[112:115], off nt
	v_pk_mul_f32 v[108:109], v[108:109], v[108:109]
	v_max_f32_e32 v106, 0, v106
	v_lshlrev_b64 v[112:113], 7, v[162:163]
	v_pk_mul_f32 v[114:115], v[104:105], v[104:105]
	v_max_f32_e32 v104, 0, v110
	v_max_f32_e32 v105, 0, v111
	v_max_f32_e32 v107, 0, v107
	v_pk_mul_f32 v[110:111], v[104:105], v[104:105]
	v_pk_mul_f32 v[116:117], v[106:107], v[106:107]
	v_cvt_pk_bf16_f32 v104, v108, v109
	v_lshl_add_u64 v[108:109], s[0:1], 0, v[112:113]
	v_pk_mul_f32 v[100:101], v[100:101], v[182:183] op_sel_hi:[1,0]
	v_pk_mul_f32 v[96:97], v[96:97], v[182:183] op_sel_hi:[1,0]
	v_cvt_pk_bf16_f32 v105, v110, v111
	v_cvt_pk_bf16_f32 v106, v114, v115
	v_cvt_pk_bf16_f32 v107, v116, v117
	v_lshl_add_u64 v[108:109], v[108:109], 0, v[136:137]
	v_pk_mul_f32 v[102:103], v[102:103], v[182:183] op_sel_hi:[1,0]
	v_pk_mul_f32 v[98:99], v[98:99], v[182:183] op_sel_hi:[1,0]
	v_max_f32_e32 v100, 0, v100
	v_max_f32_e32 v96, 0, v96
	v_max_f32_e32 v101, 0, v101
	v_max_f32_e32 v97, 0, v97
	global_store_dwordx4 v[108:109], v[104:107], off nt
	v_pk_mul_f32 v[100:101], v[100:101], v[100:101]
	v_max_f32_e32 v98, 0, v98
	v_pk_mul_f32 v[104:105], v[96:97], v[96:97]
	v_max_f32_e32 v96, 0, v102
	v_max_f32_e32 v97, 0, v103
	v_max_f32_e32 v99, 0, v99
	v_pk_mul_f32 v[102:103], v[96:97], v[96:97]
	v_pk_mul_f32 v[106:107], v[98:99], v[98:99]
	v_cvt_pk_bf16_f32 v96, v100, v101
	v_lshl_add_u64 v[100:101], s[4:5], 0, v[112:113]
	v_pk_mul_f32 v[92:93], v[92:93], v[170:171] op_sel_hi:[1,0]
	v_pk_mul_f32 v[88:89], v[88:89], v[170:171] op_sel_hi:[1,0]
	v_cvt_pk_bf16_f32 v97, v102, v103
	v_cvt_pk_bf16_f32 v98, v104, v105
	v_cvt_pk_bf16_f32 v99, v106, v107
	v_lshl_add_u64 v[100:101], v[100:101], 0, v[136:137]
	v_pk_mul_f32 v[94:95], v[94:95], v[170:171] op_sel_hi:[1,0]
	v_pk_mul_f32 v[90:91], v[90:91], v[170:171] op_sel_hi:[1,0]
	v_max_f32_e32 v92, 0, v92
	v_max_f32_e32 v88, 0, v88
	v_max_f32_e32 v93, 0, v93
	v_max_f32_e32 v89, 0, v89
	global_store_dwordx4 v[100:101], v[96:99], off nt
	v_pk_mul_f32 v[92:93], v[92:93], v[92:93]
	v_max_f32_e32 v90, 0, v90
	v_lshlrev_b64 v[96:97], 7, v[158:159]
	v_pk_mul_f32 v[98:99], v[88:89], v[88:89]
	v_max_f32_e32 v88, 0, v94
	v_max_f32_e32 v89, 0, v95
	v_max_f32_e32 v91, 0, v91
	v_pk_mul_f32 v[94:95], v[88:89], v[88:89]
	v_pk_mul_f32 v[100:101], v[90:91], v[90:91]
	v_cvt_pk_bf16_f32 v88, v92, v93
	v_lshl_add_u64 v[92:93], s[0:1], 0, v[96:97]
	v_pk_mul_f32 v[84:85], v[84:85], v[170:171] op_sel_hi:[1,0]
	v_pk_mul_f32 v[80:81], v[80:81], v[170:171] op_sel_hi:[1,0]
	v_cvt_pk_bf16_f32 v89, v94, v95
	v_cvt_pk_bf16_f32 v90, v98, v99
	v_cvt_pk_bf16_f32 v91, v100, v101
	v_lshl_add_u64 v[92:93], v[92:93], 0, v[136:137]
	v_pk_mul_f32 v[86:87], v[86:87], v[170:171] op_sel_hi:[1,0]
	v_pk_mul_f32 v[82:83], v[82:83], v[170:171] op_sel_hi:[1,0]
	v_max_f32_e32 v84, 0, v84
	v_max_f32_e32 v80, 0, v80
	v_max_f32_e32 v85, 0, v85
	v_max_f32_e32 v81, 0, v81
	global_store_dwordx4 v[92:93], v[88:91], off nt
	v_pk_mul_f32 v[84:85], v[84:85], v[84:85]
	v_max_f32_e32 v82, 0, v82
	v_pk_mul_f32 v[88:89], v[80:81], v[80:81]
	v_max_f32_e32 v80, 0, v86
	v_max_f32_e32 v81, 0, v87
	v_max_f32_e32 v83, 0, v83
	v_pk_mul_f32 v[86:87], v[80:81], v[80:81]
	v_pk_mul_f32 v[90:91], v[82:83], v[82:83]
	v_cvt_pk_bf16_f32 v80, v84, v85
	v_lshl_add_u64 v[84:85], s[4:5], 0, v[96:97]
	v_pk_mul_f32 v[76:77], v[76:77], v[166:167] op_sel_hi:[1,0]
	v_pk_mul_f32 v[72:73], v[72:73], v[166:167] op_sel_hi:[1,0]
	v_cvt_pk_bf16_f32 v81, v86, v87
	v_cvt_pk_bf16_f32 v82, v88, v89
	v_cvt_pk_bf16_f32 v83, v90, v91
	v_lshl_add_u64 v[84:85], v[84:85], 0, v[136:137]
	v_pk_mul_f32 v[78:79], v[78:79], v[166:167] op_sel_hi:[1,0]
	v_pk_mul_f32 v[74:75], v[74:75], v[166:167] op_sel_hi:[1,0]
	v_max_f32_e32 v76, 0, v76
	v_max_f32_e32 v72, 0, v72
	v_max_f32_e32 v77, 0, v77
	v_max_f32_e32 v73, 0, v73
	global_store_dwordx4 v[84:85], v[80:83], off nt
	v_pk_mul_f32 v[76:77], v[76:77], v[76:77]
	v_max_f32_e32 v74, 0, v74
	v_lshlrev_b64 v[80:81], 7, v[154:155]
	v_pk_mul_f32 v[82:83], v[72:73], v[72:73]
	v_max_f32_e32 v72, 0, v78
	v_max_f32_e32 v73, 0, v79
	v_max_f32_e32 v75, 0, v75
	v_pk_mul_f32 v[78:79], v[72:73], v[72:73]
	v_pk_mul_f32 v[84:85], v[74:75], v[74:75]
	v_cvt_pk_bf16_f32 v72, v76, v77
	v_lshl_add_u64 v[76:77], s[0:1], 0, v[80:81]
	v_pk_mul_f32 v[68:69], v[68:69], v[166:167] op_sel_hi:[1,0]
	v_pk_mul_f32 v[64:65], v[64:65], v[166:167] op_sel_hi:[1,0]
	v_cvt_pk_bf16_f32 v73, v78, v79
	v_cvt_pk_bf16_f32 v74, v82, v83
	v_cvt_pk_bf16_f32 v75, v84, v85
	v_lshl_add_u64 v[76:77], v[76:77], 0, v[136:137]
	v_pk_mul_f32 v[70:71], v[70:71], v[166:167] op_sel_hi:[1,0]
	v_pk_mul_f32 v[66:67], v[66:67], v[166:167] op_sel_hi:[1,0]
	v_max_f32_e32 v68, 0, v68
	v_max_f32_e32 v64, 0, v64
	v_max_f32_e32 v69, 0, v69
	v_max_f32_e32 v65, 0, v65
	global_store_dwordx4 v[76:77], v[72:75], off nt
	v_pk_mul_f32 v[68:69], v[68:69], v[68:69]
	v_max_f32_e32 v66, 0, v66
	v_pk_mul_f32 v[72:73], v[64:65], v[64:65]
	v_max_f32_e32 v64, 0, v70
	v_max_f32_e32 v65, 0, v71
	v_max_f32_e32 v67, 0, v67
	v_pk_mul_f32 v[70:71], v[64:65], v[64:65]
	v_pk_mul_f32 v[74:75], v[66:67], v[66:67]
	v_cvt_pk_bf16_f32 v64, v68, v69
	v_lshl_add_u64 v[68:69], s[4:5], 0, v[80:81]
	v_pk_mul_f32 v[60:61], v[60:61], v[164:165] op_sel_hi:[1,0]
	v_pk_mul_f32 v[56:57], v[56:57], v[164:165] op_sel_hi:[1,0]
	v_cvt_pk_bf16_f32 v65, v70, v71
	v_cvt_pk_bf16_f32 v66, v72, v73
	v_cvt_pk_bf16_f32 v67, v74, v75
	v_lshl_add_u64 v[68:69], v[68:69], 0, v[136:137]
	v_pk_mul_f32 v[62:63], v[62:63], v[164:165] op_sel_hi:[1,0]
	v_pk_mul_f32 v[58:59], v[58:59], v[164:165] op_sel_hi:[1,0]
	v_max_f32_e32 v60, 0, v60
	v_max_f32_e32 v56, 0, v56
	v_max_f32_e32 v61, 0, v61
	v_max_f32_e32 v57, 0, v57
	global_store_dwordx4 v[68:69], v[64:67], off nt
	v_pk_mul_f32 v[60:61], v[60:61], v[60:61]
	v_max_f32_e32 v58, 0, v58
	v_lshlrev_b64 v[64:65], 7, v[150:151]
	v_pk_mul_f32 v[66:67], v[56:57], v[56:57]
	v_max_f32_e32 v56, 0, v62
	v_max_f32_e32 v57, 0, v63
	v_max_f32_e32 v59, 0, v59
	v_pk_mul_f32 v[62:63], v[56:57], v[56:57]
	v_pk_mul_f32 v[68:69], v[58:59], v[58:59]
	v_cvt_pk_bf16_f32 v56, v60, v61
	v_lshl_add_u64 v[60:61], s[0:1], 0, v[64:65]
	v_pk_mul_f32 v[52:53], v[52:53], v[164:165] op_sel_hi:[1,0]
	v_pk_mul_f32 v[48:49], v[48:49], v[164:165] op_sel_hi:[1,0]
	v_cvt_pk_bf16_f32 v57, v62, v63
	v_cvt_pk_bf16_f32 v58, v66, v67
	v_cvt_pk_bf16_f32 v59, v68, v69
	v_lshl_add_u64 v[60:61], v[60:61], 0, v[136:137]
	v_pk_mul_f32 v[54:55], v[54:55], v[164:165] op_sel_hi:[1,0]
	v_pk_mul_f32 v[50:51], v[50:51], v[164:165] op_sel_hi:[1,0]
	v_max_f32_e32 v52, 0, v52
	v_max_f32_e32 v48, 0, v48
	v_max_f32_e32 v53, 0, v53
	v_max_f32_e32 v49, 0, v49
	global_store_dwordx4 v[60:61], v[56:59], off nt
	v_pk_mul_f32 v[52:53], v[52:53], v[52:53]
	v_max_f32_e32 v50, 0, v50
	v_pk_mul_f32 v[56:57], v[48:49], v[48:49]
	v_max_f32_e32 v48, 0, v54
	v_max_f32_e32 v49, 0, v55
	v_max_f32_e32 v51, 0, v51
	v_pk_mul_f32 v[54:55], v[48:49], v[48:49]
	v_pk_mul_f32 v[58:59], v[50:51], v[50:51]
	v_cvt_pk_bf16_f32 v48, v52, v53
	v_lshl_add_u64 v[52:53], s[4:5], 0, v[64:65]
	v_pk_mul_f32 v[44:45], v[44:45], v[160:161] op_sel_hi:[1,0]
	v_pk_mul_f32 v[40:41], v[40:41], v[160:161] op_sel_hi:[1,0]
	v_cvt_pk_bf16_f32 v49, v54, v55
	v_cvt_pk_bf16_f32 v50, v56, v57
	v_cvt_pk_bf16_f32 v51, v58, v59
	v_lshl_add_u64 v[52:53], v[52:53], 0, v[136:137]
	v_pk_mul_f32 v[46:47], v[46:47], v[160:161] op_sel_hi:[1,0]
	v_pk_mul_f32 v[42:43], v[42:43], v[160:161] op_sel_hi:[1,0]
	v_max_f32_e32 v44, 0, v44
	v_max_f32_e32 v40, 0, v40
	v_max_f32_e32 v45, 0, v45
	v_max_f32_e32 v41, 0, v41
	global_store_dwordx4 v[52:53], v[48:51], off nt
	v_pk_mul_f32 v[44:45], v[44:45], v[44:45]
	v_max_f32_e32 v42, 0, v42
	v_lshlrev_b64 v[48:49], 7, v[148:149]
	v_pk_mul_f32 v[50:51], v[40:41], v[40:41]
	v_max_f32_e32 v40, 0, v46
	v_max_f32_e32 v41, 0, v47
	v_max_f32_e32 v43, 0, v43
	v_pk_mul_f32 v[46:47], v[40:41], v[40:41]
	v_pk_mul_f32 v[52:53], v[42:43], v[42:43]
	v_cvt_pk_bf16_f32 v40, v44, v45
	v_lshl_add_u64 v[44:45], s[0:1], 0, v[48:49]
	v_pk_mul_f32 v[36:37], v[36:37], v[160:161] op_sel_hi:[1,0]
	v_pk_mul_f32 v[32:33], v[32:33], v[160:161] op_sel_hi:[1,0]
	v_cvt_pk_bf16_f32 v41, v46, v47
	v_cvt_pk_bf16_f32 v42, v50, v51
	v_cvt_pk_bf16_f32 v43, v52, v53
	v_lshl_add_u64 v[44:45], v[44:45], 0, v[136:137]
	v_pk_mul_f32 v[38:39], v[38:39], v[160:161] op_sel_hi:[1,0]
	v_pk_mul_f32 v[34:35], v[34:35], v[160:161] op_sel_hi:[1,0]
	v_max_f32_e32 v36, 0, v36
	v_max_f32_e32 v32, 0, v32
	v_max_f32_e32 v37, 0, v37
	v_max_f32_e32 v33, 0, v33
	global_store_dwordx4 v[44:45], v[40:43], off nt
	v_pk_mul_f32 v[36:37], v[36:37], v[36:37]
	v_max_f32_e32 v34, 0, v34
	v_pk_mul_f32 v[40:41], v[32:33], v[32:33]
	v_max_f32_e32 v32, 0, v38
	v_max_f32_e32 v33, 0, v39
	v_max_f32_e32 v35, 0, v35
	v_pk_mul_f32 v[38:39], v[32:33], v[32:33]
	v_pk_mul_f32 v[42:43], v[34:35], v[34:35]
	v_cvt_pk_bf16_f32 v32, v36, v37
	v_lshl_add_u64 v[36:37], s[4:5], 0, v[48:49]
	v_pk_mul_f32 v[28:29], v[28:29], v[156:157] op_sel_hi:[1,0]
	v_pk_mul_f32 v[24:25], v[24:25], v[156:157] op_sel_hi:[1,0]
	v_cvt_pk_bf16_f32 v33, v38, v39
	v_cvt_pk_bf16_f32 v34, v40, v41
	v_cvt_pk_bf16_f32 v35, v42, v43
	v_lshl_add_u64 v[36:37], v[36:37], 0, v[136:137]
	v_pk_mul_f32 v[30:31], v[30:31], v[156:157] op_sel_hi:[1,0]
	v_pk_mul_f32 v[26:27], v[26:27], v[156:157] op_sel_hi:[1,0]
	v_max_f32_e32 v28, 0, v28
	v_max_f32_e32 v24, 0, v24
	v_max_f32_e32 v29, 0, v29
	v_max_f32_e32 v25, 0, v25
	global_store_dwordx4 v[36:37], v[32:35], off nt
	v_pk_mul_f32 v[28:29], v[28:29], v[28:29]
	v_max_f32_e32 v26, 0, v26
	v_lshlrev_b64 v[32:33], 7, v[146:147]
	v_pk_mul_f32 v[34:35], v[24:25], v[24:25]
	v_max_f32_e32 v24, 0, v30
	v_max_f32_e32 v25, 0, v31
	v_max_f32_e32 v27, 0, v27
	v_pk_mul_f32 v[30:31], v[24:25], v[24:25]
	v_pk_mul_f32 v[36:37], v[26:27], v[26:27]
	v_cvt_pk_bf16_f32 v24, v28, v29
	v_lshl_add_u64 v[28:29], s[0:1], 0, v[32:33]
	v_pk_mul_f32 v[20:21], v[20:21], v[156:157] op_sel_hi:[1,0]
	v_pk_mul_f32 v[16:17], v[16:17], v[156:157] op_sel_hi:[1,0]
	v_cvt_pk_bf16_f32 v25, v30, v31
	v_cvt_pk_bf16_f32 v26, v34, v35
	v_cvt_pk_bf16_f32 v27, v36, v37
	v_lshl_add_u64 v[28:29], v[28:29], 0, v[136:137]
	v_pk_mul_f32 v[22:23], v[22:23], v[156:157] op_sel_hi:[1,0]
	v_pk_mul_f32 v[18:19], v[18:19], v[156:157] op_sel_hi:[1,0]
	v_max_f32_e32 v20, 0, v20
	v_max_f32_e32 v16, 0, v16
	v_max_f32_e32 v21, 0, v21
	v_max_f32_e32 v17, 0, v17
	global_store_dwordx4 v[28:29], v[24:27], off nt
	v_pk_mul_f32 v[20:21], v[20:21], v[20:21]
	v_max_f32_e32 v18, 0, v18
	v_pk_mul_f32 v[24:25], v[16:17], v[16:17]
	v_max_f32_e32 v16, 0, v22
	v_max_f32_e32 v17, 0, v23
	v_max_f32_e32 v19, 0, v19
	v_pk_mul_f32 v[22:23], v[16:17], v[16:17]
	v_pk_mul_f32 v[26:27], v[18:19], v[18:19]
	v_cvt_pk_bf16_f32 v16, v20, v21
	v_lshl_add_u64 v[20:21], s[4:5], 0, v[32:33]
	v_pk_mul_f32 v[12:13], v[12:13], v[152:153] op_sel_hi:[1,0]
	v_pk_mul_f32 v[8:9], v[8:9], v[152:153] op_sel_hi:[1,0]
	v_cvt_pk_bf16_f32 v17, v22, v23
	v_cvt_pk_bf16_f32 v18, v24, v25
	v_cvt_pk_bf16_f32 v19, v26, v27
	v_lshl_add_u64 v[20:21], v[20:21], 0, v[136:137]
	v_pk_mul_f32 v[14:15], v[14:15], v[152:153] op_sel_hi:[1,0]
	v_pk_mul_f32 v[10:11], v[10:11], v[152:153] op_sel_hi:[1,0]
	v_max_f32_e32 v12, 0, v12
	v_max_f32_e32 v8, 0, v8
	v_max_f32_e32 v13, 0, v13
	v_max_f32_e32 v9, 0, v9
	global_store_dwordx4 v[20:21], v[16:19], off nt
	v_pk_mul_f32 v[12:13], v[12:13], v[12:13]
	v_max_f32_e32 v10, 0, v10
	v_lshlrev_b64 v[16:17], 7, v[144:145]
	v_pk_mul_f32 v[18:19], v[8:9], v[8:9]
	v_max_f32_e32 v8, 0, v14
	v_max_f32_e32 v9, 0, v15
	v_max_f32_e32 v11, 0, v11
	v_pk_mul_f32 v[14:15], v[8:9], v[8:9]
	v_pk_mul_f32 v[20:21], v[10:11], v[10:11]
	v_cvt_pk_bf16_f32 v8, v12, v13
	v_lshl_add_u64 v[12:13], s[0:1], 0, v[16:17]
	v_pk_mul_f32 v[4:5], v[4:5], v[152:153] op_sel_hi:[1,0]
	v_pk_mul_f32 v[0:1], v[0:1], v[152:153] op_sel_hi:[1,0]
	v_cvt_pk_bf16_f32 v9, v14, v15
	v_cvt_pk_bf16_f32 v10, v18, v19
	v_cvt_pk_bf16_f32 v11, v20, v21
	v_lshl_add_u64 v[12:13], v[12:13], 0, v[136:137]
	v_pk_mul_f32 v[6:7], v[6:7], v[152:153] op_sel_hi:[1,0]
	v_pk_mul_f32 v[2:3], v[2:3], v[152:153] op_sel_hi:[1,0]
	v_max_f32_e32 v4, 0, v4
	v_max_f32_e32 v0, 0, v0
	v_max_f32_e32 v5, 0, v5
	v_max_f32_e32 v1, 0, v1
	global_store_dwordx4 v[12:13], v[8:11], off nt
	v_pk_mul_f32 v[4:5], v[4:5], v[4:5]
	v_max_f32_e32 v2, 0, v2
	v_pk_mul_f32 v[8:9], v[0:1], v[0:1]
	v_max_f32_e32 v0, 0, v6
	v_max_f32_e32 v1, 0, v7
	v_max_f32_e32 v3, 0, v3
	v_pk_mul_f32 v[6:7], v[0:1], v[0:1]
	v_pk_mul_f32 v[10:11], v[2:3], v[2:3]
	v_cvt_pk_bf16_f32 v0, v4, v5
	v_lshl_add_u64 v[4:5], s[4:5], 0, v[16:17]
	v_cvt_pk_bf16_f32 v1, v6, v7
	v_cvt_pk_bf16_f32 v2, v8, v9
	v_cvt_pk_bf16_f32 v3, v10, v11
	v_lshl_add_u64 v[4:5], v[4:5], 0, v[136:137]
	s_and_b64 vcc, exec, s[24:25]
	s_mov_b32 s70, s20
	s_mov_b32 s24, s20
	s_mov_b64 s[4:5], s[26:27]
	s_mov_b64 s[0:1], s[22:23]
	global_store_dwordx4 v[4:5], v[0:3], off nt
	s_cbranch_vccz .LBB0_1433
	s_waitcnt vmcnt(0)
	s_cmpk_gt_u32 s7, 0xff
	s_cbranch_scc1 .LBB0_1445
	s_barrier

.LBB0_1512:
	ds_read_b128 v[144:147], v204
	ds_read_b128 v[148:151], v204 offset:1024
	ds_read_b128 v[172:175], v204 offset:2048
	ds_read_b128 v[176:179], v204 offset:3072
	ds_read_b128 v[180:183], v204 offset:4096
	ds_read_b128 v[184:187], v204 offset:5120
	ds_read_b128 v[188:191], v204 offset:6144
	ds_read_b128 v[192:195], v204 offset:7168
	ds_read_b128 v[128:131], v203
	ds_read_b128 v[132:135], v203 offset:1024
	ds_read_b128 v[136:139], v203 offset:2048
	ds_read_b128 v[140:143], v203 offset:3072
	s_add_u32 s26, s24, 0x3fc000
	s_addc_u32 s27, s25, 0
	s_cmp_eq_u32 s49, 60
	s_cselect_b32 s30, s7, s26
	s_cselect_b32 s31, s5, s27
	s_cselect_b32 s26, s15, s17
	s_cselect_b32 s27, s8, s48
	s_add_u32 s28, s30, 0x400000
	s_addc_u32 s29, s31, 0
	v_lshl_add_u64 v[196:197], s[24:25], 0, v[168:169]
	s_add_i32 m0, s33, 0xc000
	global_load_lds_dwordx4 v[196:197], off
	v_lshl_add_u64 v[196:197], s[24:25], 0, v[170:171]
	s_add_i32 m0, s33, 0xe000
	s_nop 0
	global_load_lds_dwordx4 v[196:197], off
	s_waitcnt lgkmcnt(0)
	s_barrier
	s_waitcnt lgkmcnt(0)
	v_mfma_f32_16x16x32_bf16 v[124:127], v[128:131], v[144:147], v[124:127]
	v_mfma_f32_16x16x32_bf16 v[120:123], v[136:139], v[144:147], v[120:123]
	v_mfma_f32_16x16x32_bf16 v[108:111], v[128:131], v[172:175], v[108:111]
	v_mfma_f32_16x16x32_bf16 v[104:107], v[136:139], v[172:175], v[104:107]
	v_mfma_f32_16x16x32_bf16 v[92:95], v[128:131], v[180:183], v[92:95]
	v_mfma_f32_16x16x32_bf16 v[88:91], v[136:139], v[180:183], v[88:91]
	v_mfma_f32_16x16x32_bf16 v[76:79], v[128:131], v[188:191], v[76:79]
	v_mfma_f32_16x16x32_bf16 v[72:75], v[136:139], v[188:191], v[72:75]
	v_mfma_f32_16x16x32_bf16 v[124:127], v[132:135], v[148:151], v[124:127]
	v_mfma_f32_16x16x32_bf16 v[120:123], v[140:143], v[148:151], v[120:123]
	v_mfma_f32_16x16x32_bf16 v[108:111], v[132:135], v[176:179], v[108:111]
	v_mfma_f32_16x16x32_bf16 v[104:107], v[140:143], v[176:179], v[104:107]
	v_mfma_f32_16x16x32_bf16 v[92:95], v[132:135], v[184:187], v[92:95]
	v_mfma_f32_16x16x32_bf16 v[88:91], v[140:143], v[184:187], v[88:91]
	v_mfma_f32_16x16x32_bf16 v[76:79], v[132:135], v[192:195], v[76:79]
	v_mfma_f32_16x16x32_bf16 v[72:75], v[140:143], v[192:195], v[72:75]
	s_barrier
	s_add_i32 s50, s44, s13
	v_lshl_add_u64 v[200:201], s[26:27], 0, v[156:157]
	s_mov_b32 m0, s50
	ds_read_b128 v[196:199], v205
	ds_read_b128 v[208:211], v205 offset:1024
	ds_read_b128 v[212:215], v205 offset:2048
	ds_read_b128 v[216:219], v205 offset:3072
	global_load_lds_dwordx4 v[200:201], off
	v_lshl_add_u64 v[200:201], s[26:27], 0, v[152:153]
	s_add_i32 m0, s50, 0x2000
	s_nop 0
	global_load_lds_dwordx4 v[200:201], off
	s_barrier
	s_waitcnt lgkmcnt(0)
	v_mfma_f32_16x16x32_bf16 v[116:119], v[196:199], v[144:147], v[116:119]
	v_mfma_f32_16x16x32_bf16 v[112:115], v[212:215], v[144:147], v[112:115]
	v_mfma_f32_16x16x32_bf16 v[100:103], v[196:199], v[172:175], v[100:103]
	v_mfma_f32_16x16x32_bf16 v[96:99], v[212:215], v[172:175], v[96:99]
	v_mfma_f32_16x16x32_bf16 v[84:87], v[196:199], v[180:183], v[84:87]
	v_mfma_f32_16x16x32_bf16 v[80:83], v[212:215], v[180:183], v[80:83]
	v_mfma_f32_16x16x32_bf16 v[68:71], v[196:199], v[188:191], v[68:71]
	v_mfma_f32_16x16x32_bf16 v[64:67], v[212:215], v[188:191], v[64:67]
	v_mfma_f32_16x16x32_bf16 v[116:119], v[208:211], v[148:151], v[116:119]
	v_mfma_f32_16x16x32_bf16 v[112:115], v[216:219], v[148:151], v[112:115]
	v_mfma_f32_16x16x32_bf16 v[100:103], v[208:211], v[176:179], v[100:103]
	v_mfma_f32_16x16x32_bf16 v[96:99], v[216:219], v[176:179], v[96:99]
	v_mfma_f32_16x16x32_bf16 v[84:87], v[208:211], v[184:187], v[84:87]
	v_mfma_f32_16x16x32_bf16 v[80:83], v[216:219], v[184:187], v[80:83]
	v_mfma_f32_16x16x32_bf16 v[68:71], v[208:211], v[192:195], v[68:71]
	v_mfma_f32_16x16x32_bf16 v[64:67], v[216:219], v[192:195], v[64:67]
	s_mov_b32 m0, s33
	v_lshl_add_u64 v[200:201], s[30:31], 0, v[158:159]
	s_barrier
	ds_read_b128 v[144:147], v204 offset:16384
	ds_read_b128 v[148:151], v204 offset:17408
	ds_read_b128 v[172:175], v204 offset:18432
	ds_read_b128 v[176:179], v204 offset:19456
	ds_read_b128 v[180:183], v204 offset:20480
	ds_read_b128 v[184:187], v204 offset:21504
	ds_read_b128 v[188:191], v204 offset:22528
	ds_read_b128 v[192:195], v204 offset:23552
	global_load_lds_dwordx4 v[200:201], off
	v_lshl_add_u64 v[200:201], s[30:31], 0, v[154:155]
	s_mov_b32 m0, s35
	s_nop 0
	global_load_lds_dwordx4 v[200:201], off
	s_barrier
	s_waitcnt lgkmcnt(0)
	v_mfma_f32_16x16x32_bf16 v[60:63], v[128:131], v[144:147], v[60:63]
	v_mfma_f32_16x16x32_bf16 v[56:59], v[136:139], v[144:147], v[56:59]
	v_mfma_f32_16x16x32_bf16 v[44:47], v[128:131], v[172:175], v[44:47]
	v_mfma_f32_16x16x32_bf16 v[40:43], v[136:139], v[172:175], v[40:43]
	v_mfma_f32_16x16x32_bf16 v[28:31], v[128:131], v[180:183], v[28:31]
	v_mfma_f32_16x16x32_bf16 v[24:27], v[136:139], v[180:183], v[24:27]
	v_mfma_f32_16x16x32_bf16 v[12:15], v[128:131], v[188:191], v[12:15]
	v_mfma_f32_16x16x32_bf16 v[8:11], v[136:139], v[188:191], v[8:11]
	v_mfma_f32_16x16x32_bf16 v[60:63], v[132:135], v[148:151], v[60:63]
	v_mfma_f32_16x16x32_bf16 v[56:59], v[140:143], v[148:151], v[56:59]
	v_mfma_f32_16x16x32_bf16 v[44:47], v[132:135], v[176:179], v[44:47]
	v_mfma_f32_16x16x32_bf16 v[40:43], v[140:143], v[176:179], v[40:43]
	v_mfma_f32_16x16x32_bf16 v[28:31], v[132:135], v[184:187], v[28:31]
	v_mfma_f32_16x16x32_bf16 v[24:27], v[140:143], v[184:187], v[24:27]
	v_mfma_f32_16x16x32_bf16 v[12:15], v[132:135], v[192:195], v[12:15]
	v_mfma_f32_16x16x32_bf16 v[8:11], v[140:143], v[192:195], v[8:11]
	s_barrier
	s_add_u32 s50, s26, 0x4000
	s_addc_u32 s51, s27, 0
	s_add_i32 s52, s45, s13
	v_lshl_add_u64 v[128:129], s[50:51], 0, v[156:157]
	s_mov_b32 m0, s52
	s_nop 0
	global_load_lds_dwordx4 v[128:129], off
	v_lshl_add_u64 v[128:129], s[50:51], 0, v[152:153]
	s_add_i32 m0, s52, 0x2000
	s_nop 0
	global_load_lds_dwordx4 v[128:129], off
	s_waitcnt vmcnt(6)
	s_barrier
	v_mfma_f32_16x16x32_bf16 v[52:55], v[196:199], v[144:147], v[52:55]
	v_mfma_f32_16x16x32_bf16 v[48:51], v[212:215], v[144:147], v[48:51]
	v_mfma_f32_16x16x32_bf16 v[36:39], v[196:199], v[172:175], v[36:39]
	v_mfma_f32_16x16x32_bf16 v[32:35], v[212:215], v[172:175], v[32:35]
	v_mfma_f32_16x16x32_bf16 v[20:23], v[196:199], v[180:183], v[20:23]
	v_mfma_f32_16x16x32_bf16 v[16:19], v[212:215], v[180:183], v[16:19]
	v_mfma_f32_16x16x32_bf16 v[4:7], v[196:199], v[188:191], v[4:7]
	v_mfma_f32_16x16x32_bf16 v[0:3], v[212:215], v[188:191], v[0:3]
	v_mfma_f32_16x16x32_bf16 v[52:55], v[208:211], v[148:151], v[52:55]
	v_mfma_f32_16x16x32_bf16 v[48:51], v[216:219], v[148:151], v[48:51]
	v_mfma_f32_16x16x32_bf16 v[36:39], v[208:211], v[176:179], v[36:39]
	v_mfma_f32_16x16x32_bf16 v[32:35], v[216:219], v[176:179], v[32:35]
	v_mfma_f32_16x16x32_bf16 v[20:23], v[208:211], v[184:187], v[20:23]
	v_mfma_f32_16x16x32_bf16 v[16:19], v[216:219], v[184:187], v[16:19]
	v_mfma_f32_16x16x32_bf16 v[4:7], v[208:211], v[192:195], v[4:7]
	v_mfma_f32_16x16x32_bf16 v[0:3], v[216:219], v[192:195], v[0:3]
	s_add_i32 s50, 0, 0x18000
	v_add_u32_e32 v140, s50, v202
	s_barrier
	ds_read_b128 v[144:147], v204 offset:32768
	ds_read_b128 v[148:151], v204 offset:33792
	ds_read_b128 v[172:175], v204 offset:34816
	ds_read_b128 v[176:179], v204 offset:35840
	ds_read_b128 v[180:183], v204 offset:36864
	ds_read_b128 v[184:187], v204 offset:37888
	ds_read_b128 v[188:191], v204 offset:38912
	ds_read_b128 v[192:195], v204 offset:39936
	ds_read_b128 v[128:131], v140
	ds_read_b128 v[132:135], v140 offset:1024
	ds_read_b128 v[136:139], v140 offset:2048
	ds_read_b128 v[140:143], v140 offset:3072
	s_add_u32 s30, s30, 0x4000
	s_addc_u32 s31, s31, 0
	s_mov_b32 m0, s36
	v_lshl_add_u64 v[196:197], s[30:31], 0, v[158:159]
	global_load_lds_dwordx4 v[196:197], off
	v_lshl_add_u64 v[196:197], s[30:31], 0, v[154:155]
	s_mov_b32 m0, s37
	s_nop 0
	global_load_lds_dwordx4 v[196:197], off
	s_waitcnt lgkmcnt(0)
	s_barrier
	s_waitcnt lgkmcnt(0)
	v_mfma_f32_16x16x32_bf16 v[124:127], v[128:131], v[144:147], v[124:127]
	v_mfma_f32_16x16x32_bf16 v[120:123], v[136:139], v[144:147], v[120:123]
	v_mfma_f32_16x16x32_bf16 v[108:111], v[128:131], v[172:175], v[108:111]
	v_mfma_f32_16x16x32_bf16 v[104:107], v[136:139], v[172:175], v[104:107]
	v_mfma_f32_16x16x32_bf16 v[92:95], v[128:131], v[180:183], v[92:95]
	v_mfma_f32_16x16x32_bf16 v[88:91], v[136:139], v[180:183], v[88:91]
	v_mfma_f32_16x16x32_bf16 v[76:79], v[128:131], v[188:191], v[76:79]
	v_mfma_f32_16x16x32_bf16 v[72:75], v[136:139], v[188:191], v[72:75]
	v_mfma_f32_16x16x32_bf16 v[124:127], v[132:135], v[148:151], v[124:127]
	v_mfma_f32_16x16x32_bf16 v[120:123], v[140:143], v[148:151], v[120:123]
	v_mfma_f32_16x16x32_bf16 v[108:111], v[132:135], v[176:179], v[108:111]
	v_mfma_f32_16x16x32_bf16 v[104:107], v[140:143], v[176:179], v[104:107]
	v_mfma_f32_16x16x32_bf16 v[92:95], v[132:135], v[184:187], v[92:95]
	v_mfma_f32_16x16x32_bf16 v[88:91], v[140:143], v[184:187], v[88:91]
	v_mfma_f32_16x16x32_bf16 v[76:79], v[132:135], v[192:195], v[76:79]
	v_mfma_f32_16x16x32_bf16 v[72:75], v[140:143], v[192:195], v[72:75]
	s_barrier
	s_add_i32 s51, 0, 0x1c000
	s_add_u32 s30, s26, 0x20000
	v_add_u32_e32 v200, s51, v202
	s_addc_u32 s31, s27, 0
	s_add_i32 s50, s50, s13
	ds_read_b128 v[196:199], v200
	ds_read_b128 v[208:211], v200 offset:1024
	ds_read_b128 v[212:215], v200 offset:2048
	ds_read_b128 v[216:219], v200 offset:3072
	v_lshl_add_u64 v[200:201], s[30:31], 0, v[156:157]
	s_mov_b32 m0, s50
	s_nop 0
	global_load_lds_dwordx4 v[200:201], off
	v_lshl_add_u64 v[200:201], s[30:31], 0, v[152:153]
	s_add_i32 m0, s50, 0x2000
	s_nop 0
	global_load_lds_dwordx4 v[200:201], off
	s_barrier
	s_waitcnt lgkmcnt(0)
	v_mfma_f32_16x16x32_bf16 v[116:119], v[196:199], v[144:147], v[116:119]
	v_mfma_f32_16x16x32_bf16 v[112:115], v[212:215], v[144:147], v[112:115]
	v_mfma_f32_16x16x32_bf16 v[100:103], v[196:199], v[172:175], v[100:103]
	v_mfma_f32_16x16x32_bf16 v[96:99], v[212:215], v[172:175], v[96:99]
	v_mfma_f32_16x16x32_bf16 v[84:87], v[196:199], v[180:183], v[84:87]
	v_mfma_f32_16x16x32_bf16 v[80:83], v[212:215], v[180:183], v[80:83]
	v_mfma_f32_16x16x32_bf16 v[68:71], v[196:199], v[188:191], v[68:71]
	v_mfma_f32_16x16x32_bf16 v[64:67], v[212:215], v[188:191], v[64:67]
	v_mfma_f32_16x16x32_bf16 v[116:119], v[208:211], v[148:151], v[116:119]
	v_mfma_f32_16x16x32_bf16 v[112:115], v[216:219], v[148:151], v[112:115]
	v_mfma_f32_16x16x32_bf16 v[100:103], v[208:211], v[176:179], v[100:103]
	v_mfma_f32_16x16x32_bf16 v[96:99], v[216:219], v[176:179], v[96:99]
	v_mfma_f32_16x16x32_bf16 v[84:87], v[208:211], v[184:187], v[84:87]
	v_mfma_f32_16x16x32_bf16 v[80:83], v[216:219], v[184:187], v[80:83]
	v_mfma_f32_16x16x32_bf16 v[68:71], v[208:211], v[192:195], v[68:71]
	v_mfma_f32_16x16x32_bf16 v[64:67], v[216:219], v[192:195], v[64:67]
	s_mov_b32 m0, s41
	v_lshl_add_u64 v[200:201], s[28:29], 0, v[158:159]
	s_barrier
	ds_read_b128 v[144:147], v204 offset:49152
	ds_read_b128 v[148:151], v204 offset:50176
	ds_read_b128 v[172:175], v204 offset:51200
	ds_read_b128 v[176:179], v204 offset:52224
	ds_read_b128 v[180:183], v204 offset:53248
	ds_read_b128 v[184:187], v204 offset:54272
	ds_read_b128 v[188:191], v204 offset:55296
	ds_read_b128 v[192:195], v204 offset:56320
	global_load_lds_dwordx4 v[200:201], off
	v_lshl_add_u64 v[200:201], s[28:29], 0, v[154:155]
	s_mov_b32 m0, s42
	s_nop 0
	global_load_lds_dwordx4 v[200:201], off
	s_barrier
	s_waitcnt lgkmcnt(0)
	v_mfma_f32_16x16x32_bf16 v[60:63], v[128:131], v[144:147], v[60:63]
	v_mfma_f32_16x16x32_bf16 v[56:59], v[136:139], v[144:147], v[56:59]
	v_mfma_f32_16x16x32_bf16 v[44:47], v[128:131], v[172:175], v[44:47]
	v_mfma_f32_16x16x32_bf16 v[40:43], v[136:139], v[172:175], v[40:43]
	v_mfma_f32_16x16x32_bf16 v[28:31], v[128:131], v[180:183], v[28:31]
	v_mfma_f32_16x16x32_bf16 v[24:27], v[136:139], v[180:183], v[24:27]
	v_mfma_f32_16x16x32_bf16 v[12:15], v[128:131], v[188:191], v[12:15]
	v_mfma_f32_16x16x32_bf16 v[8:11], v[136:139], v[188:191], v[8:11]
	v_mfma_f32_16x16x32_bf16 v[60:63], v[132:135], v[148:151], v[60:63]
	v_mfma_f32_16x16x32_bf16 v[56:59], v[140:143], v[148:151], v[56:59]
	v_mfma_f32_16x16x32_bf16 v[44:47], v[132:135], v[176:179], v[44:47]
	v_mfma_f32_16x16x32_bf16 v[40:43], v[140:143], v[176:179], v[40:43]
	v_mfma_f32_16x16x32_bf16 v[28:31], v[132:135], v[184:187], v[28:31]
	v_mfma_f32_16x16x32_bf16 v[24:27], v[140:143], v[184:187], v[24:27]
	v_mfma_f32_16x16x32_bf16 v[12:15], v[132:135], v[192:195], v[12:15]
	v_mfma_f32_16x16x32_bf16 v[8:11], v[140:143], v[192:195], v[8:11]
	s_barrier
	s_add_u32 s26, s26, 0x24000
	s_addc_u32 s27, s27, 0
	s_add_i32 s28, s51, s13
	v_lshl_add_u64 v[128:129], s[26:27], 0, v[156:157]
	s_mov_b32 m0, s28
	s_nop 0
	global_load_lds_dwordx4 v[128:129], off
	v_lshl_add_u64 v[128:129], s[26:27], 0, v[152:153]
	s_add_i32 m0, s28, 0x2000
	s_nop 0
	global_load_lds_dwordx4 v[128:129], off
	s_waitcnt vmcnt(6)
	s_barrier
	v_mfma_f32_16x16x32_bf16 v[52:55], v[196:199], v[144:147], v[52:55]
	v_mfma_f32_16x16x32_bf16 v[48:51], v[212:215], v[144:147], v[48:51]
	v_mfma_f32_16x16x32_bf16 v[36:39], v[196:199], v[172:175], v[36:39]
	v_mfma_f32_16x16x32_bf16 v[32:35], v[212:215], v[172:175], v[32:35]
	v_mfma_f32_16x16x32_bf16 v[20:23], v[196:199], v[180:183], v[20:23]
	v_mfma_f32_16x16x32_bf16 v[16:19], v[212:215], v[180:183], v[16:19]
	v_mfma_f32_16x16x32_bf16 v[4:7], v[196:199], v[188:191], v[4:7]
	v_mfma_f32_16x16x32_bf16 v[0:3], v[212:215], v[188:191], v[0:3]
	v_mfma_f32_16x16x32_bf16 v[52:55], v[208:211], v[148:151], v[52:55]
	v_mfma_f32_16x16x32_bf16 v[48:51], v[216:219], v[148:151], v[48:51]
	v_mfma_f32_16x16x32_bf16 v[36:39], v[208:211], v[176:179], v[36:39]
	v_mfma_f32_16x16x32_bf16 v[32:35], v[216:219], v[176:179], v[32:35]
	v_mfma_f32_16x16x32_bf16 v[20:23], v[208:211], v[184:187], v[20:23]
	v_mfma_f32_16x16x32_bf16 v[16:19], v[216:219], v[184:187], v[16:19]
	v_mfma_f32_16x16x32_bf16 v[4:7], v[208:211], v[192:195], v[4:7]
	v_mfma_f32_16x16x32_bf16 v[0:3], v[216:219], v[192:195], v[0:3]
	s_add_i32 s49, s49, 2
	s_add_u32 s17, s17, 0x40000
	s_addc_u32 s48, s48, 0
	s_add_u32 s24, s24, 0x800000
	s_addc_u32 s25, s25, 0
	s_cmp_gt_u32 s49, 61
	s_barrier
	s_cbranch_scc0 .LBB0_1512
	s_nop 0
	s_lshl_b32 s24, s4, 8
	v_readlane_b32 s68, v253, 38
	v_readlane_b32 s69, v253, 39
	s_ashr_i32 s25, s24, 31
	s_lshl_b32 s4, s4, 2
	v_readlane_b32 s70, v253, 40
	v_readlane_b32 s71, v253, 41
	s_mov_b64 s[48:49], s[68:69]
	v_lshl_add_u32 v178, s6, 8, v163
	s_ashr_i32 s5, s4, 31
	s_lshl_b64 s[26:27], s[24:25], 1
	s_mov_b64 s[50:51], s[70:71]
	s_add_u32 s26, s50, s26
	v_ashrrev_i32_e32 v179, 31, v178
	s_addc_u32 s27, s51, s27
	v_lshlrev_b64 v[128:129], 11, v[178:179]
	v_lshl_add_u64 v[128:129], s[26:27], 0, v[128:129]
	v_lshl_add_u64 v[128:129], v[128:129], 0, v[160:161]
	global_load_dwordx4 v[180:183], v[128:129], off
	global_load_dwordx4 v[184:187], v[128:129], off offset:256
	v_or_b32_e32 v176, 16, v178
	v_or_b32_e32 v174, 32, v178
	v_or_b32_e32 v172, 48, v178
	v_ashrrev_i32_e32 v177, 31, v176
	v_ashrrev_i32_e32 v175, 31, v174
	v_ashrrev_i32_e32 v173, 31, v172
	v_lshlrev_b64 v[128:129], 11, v[176:177]
	v_lshlrev_b64 v[130:131], 11, v[174:175]
	v_lshlrev_b64 v[132:133], 11, v[172:173]
	v_lshl_add_u64 v[128:129], s[26:27], 0, v[128:129]
	v_lshl_add_u64 v[130:131], s[26:27], 0, v[130:131]
	v_lshl_add_u64 v[132:133], s[26:27], 0, v[132:133]
	v_lshl_add_u64 v[128:129], v[128:129], 0, v[160:161]
	v_lshl_add_u64 v[130:131], v[130:131], 0, v[160:161]
	v_lshl_add_u64 v[188:189], v[132:133], 0, v[160:161]
	global_load_dwordx4 v[148:151], v[128:129], off
	global_load_dwordx4 v[144:147], v[128:129], off offset:256
	global_load_dwordx4 v[140:143], v[130:131], off
	global_load_dwordx4 v[136:139], v[130:131], off offset:256
	global_load_dwordx4 v[132:135], v[188:189], off
	s_nop 0
	global_load_dwordx4 v[128:131], v[188:189], off offset:256
	v_and_b32_e32 v189, 64, v206
	v_xor_b32_e32 v188, 16, v206
	v_add_u32_e32 v196, 64, v189
	v_cmp_lt_i32_e32 vcc, v188, v196
	s_nop 1
	v_cndmask_b32_e32 v188, v206, v188, vcc
	v_lshlrev_b32_e32 v207, 2, v188
	s_nop 7
	s_nop 0
	s_waitcnt vmcnt(0)
	v_lshlrev_b32_e32 v190, 16, v182
	v_and_b32_e32 v191, 0xffff0000, v182
	v_lshlrev_b32_e32 v188, 16, v180
	v_and_b32_e32 v189, 0xffff0000, v180
	v_lshlrev_b32_e32 v180, 16, v181
	v_and_b32_e32 v181, 0xffff0000, v181
	v_lshlrev_b32_e32 v182, 16, v183
	v_and_b32_e32 v183, 0xffff0000, v183
	v_pk_add_f32 v[120:121], v[120:121], v[190:191]
	v_pk_add_f32 v[126:127], v[126:127], v[180:181]
	v_pk_add_f32 v[124:125], v[124:125], v[188:189]
	v_pk_add_f32 v[122:123], v[122:123], v[182:183]
	v_mul_f32_e32 v180, v120, v120
	v_mul_f32_e32 v181, v121, v121
	v_lshlrev_b32_e32 v194, 16, v186
	v_and_b32_e32 v195, 0xffff0000, v186
	v_mul_f32_e32 v182, v122, v122
	v_fmac_f32_e32 v180, v124, v124
	v_fmac_f32_e32 v181, v125, v125
	v_lshlrev_b32_e32 v192, 16, v184
	v_and_b32_e32 v193, 0xffff0000, v184
	v_lshlrev_b32_e32 v184, 16, v185
	v_and_b32_e32 v185, 0xffff0000, v185
	v_pk_add_f32 v[112:113], v[112:113], v[194:195]
	v_mul_f32_e32 v183, v123, v123
	v_fmac_f32_e32 v182, v126, v126
	v_add_f32_e32 v180, v180, v181
	v_lshlrev_b32_e32 v186, 16, v187
	v_and_b32_e32 v187, 0xffff0000, v187
	v_pk_add_f32 v[118:119], v[118:119], v[184:185]
	v_pk_add_f32 v[116:117], v[116:117], v[192:193]
	v_mul_f32_e32 v184, v112, v112
	v_fmac_f32_e32 v183, v127, v127
	v_add_f32_e32 v180, v182, v180
	v_pk_add_f32 v[114:115], v[114:115], v[186:187]
	v_mul_f32_e32 v185, v113, v113
	v_fmac_f32_e32 v184, v116, v116
	v_add_f32_e32 v180, v183, v180
	v_mul_f32_e32 v186, v114, v114
	v_fmac_f32_e32 v185, v117, v117
	v_add_f32_e32 v180, v184, v180
	v_mul_f32_e32 v187, v115, v115
	v_fmac_f32_e32 v186, v118, v118
	v_add_f32_e32 v180, v185, v180
	v_add_f32_e32 v180, v186, v180
	v_fmac_f32_e32 v187, v119, v119
	v_add_f32_e32 v180, v187, v180
	ds_bpermute_b32 v181, v207, v180
	v_xor_b32_e32 v182, 32, v206
	v_cmp_lt_i32_e32 vcc, v182, v196
	v_lshlrev_b64 v[188:189], 6, v[178:179]
	s_waitcnt lgkmcnt(0)
	v_add_f32_e32 v180, v180, v181
	v_cndmask_b32_e32 v182, v206, v182, vcc
	v_lshlrev_b32_e32 v208, 2, v182
	ds_bpermute_b32 v181, v208, v180
	s_and_saveexec_b64 s[28:29], s[0:1]
	s_cbranch_execz .LBB0_1515
	s_waitcnt lgkmcnt(0)
	v_add_f32_e32 v182, v180, v181
	v_lshl_add_u64 v[180:181], s[88:89], 0, v[188:189]
	v_lshl_add_u64 v[180:181], s[4:5], 2, v[180:181]
	s_lshl_b32 s8, s40, 2
	v_lshl_add_u64 v[180:181], v[180:181], 0, s[8:9]
	global_store_dword v[180:181], v182, off sc1
